# adjacent vmcnt/lgkmcnt waits merged into single s_waitcnt (51 sites, 40 in GEMM loops)
# baseline (speedup 1.0000x reference)
; __device__ __forceinline__ unsigned xb_add(unsigned* p, unsigned v) { return __hip_atomic_fetch_add(p, v, __ATOMIC_RELAXED, __HIP_MEMORY_SCOPE_AGENT); }
; __device__ __forceinline__ void xcd_barrier(const XcdBarrier& b, bool leader) {
;     ...
;         if (old + 1u == (gen + 1u) * nloc) {
;             __builtin_amdgcn_fence(__ATOMIC_RELEASE, "agent");
;             asm volatile("s_waitcnt vmcnt(0)" ::: "memory");
;             const unsigned og = xb_add(&bar[XB_TOP], 1u);
.LBB0_150:
	s_andn2_saveexec_b64 s[6:7], s[6:7]
	s_cbranch_execz .LBB0_170
	s_mov_b64 s[6:7], exec
	buffer_wbl2 sc1
	s_waitcnt vmcnt(0) lgkmcnt(0)
	v_mbcnt_lo_u32_b32 v1, s6, 0
	v_mbcnt_hi_u32_b32 v1, s7, v1
	v_cmp_eq_u32_e32 vcc, 0, v1
	s_and_saveexec_b64 s[8:9], vcc
	s_cbranch_execz .LBB0_153
	s_bcnt1_i32_b64 s6, s[6:7]
	v_mov_b32_e32 v2, 0x3000
	v_mov_b32_e32 v3, s6
	global_atomic_add v2, v2, v3, s[30:31] offset:1024 sc0

; #define PG8_STAGE(bufoff, gbase, voff) do { _Pragma("unroll") for (int _i = 0; _i < 2; ++_i) \
;         __builtin_amdgcn_global_load_lds((const unsigned*)((const char*)(gbase) + (voff)[_i]), (PG8_LAS unsigned*)(lds + (bufoff) + ldsw + _i * 8192), 16, 0, 0); } while (0)
; #define PG8_LDA(dst, b, h) do { _Pragma("unroll") for (int m = 0; m < 4; ++m) _Pragma("unroll") for (int k = 0; k < 2; ++k) dst[m][k] = *(const PG8_LAS bf16x8*)(lds + PG8_SA(b, h) + aoff + m * 2048 + k * 1024); } while (0)
; #define PG8_LDB(dst, b, h) do { _Pragma("unroll") for (int n = 0; n < 2; ++n) _Pragma("unroll") for (int k = 0; k < 2; ++k) dst[n][k] = *(const PG8_LAS bf16x8*)(lds + PG8_SB(b, h) + boff + n * 2048 + k * 1024); } while (0)
; #define PG8_MMA(ai, bj, At, Bt) do { __builtin_amdgcn_s_setprio(1); _Pragma("unroll") for (int m = 0; m < 4; ++m) _Pragma("unroll") for (int n = 0; n < 2; ++n) _Pragma("unroll") for (int k = 0; k < 2; ++k) \
;         acc[ai][bj][m][n] = __builtin_amdgcn_mfma_f32_16x16x32_bf16(Bt[n][k], At[m][k], acc[ai][bj][m][n], 0, 0, 0); __builtin_amdgcn_s_setprio(0); } while (0)
; #define PG8_WAIT_V(n) asm volatile("s_waitcnt vmcnt(" #n ")" ::: "memory")
; #define PG8_WAIT_L(n) asm volatile("s_waitcnt lgkmcnt(" #n ")" ::: "memory")
; #define PG8_BAR __builtin_amdgcn_s_barrier()
; #define PG8_SCHED __builtin_amdgcn_sched_barrier(0)
; template <class Epi, class Sched, bool ALIGN_EPI = false, bool SP2 = false>
; __device__ __forceinline__ void gemm_phase(PG8_LAS unsigned char* lds, const Gemm g, const Sched& S, const Epi& E, int wave_s) {
;     ...
;             PG8_LDB(B0, 0, 0); PG8_LDB(B1, 0, 1); PG8_SCHED; PG8_LDA(At, 0, 0); PG8_STAGE(PG8_SA(1, 1), a1 + hstep, voffA);
;             PG8_WAIT_V(8); PG8_WAIT_L(0); PG8_BAR; PG8_MMA(0, 0, At, B0); PG8_MMA(0, 1, At, B1); PG8_BAR; PG8_SCHED;
;             PG8_LDA(At, 0, 1); PG8_STAGE(PG8_SB(0, 0), b2, voffB); PG8_STAGE(PG8_SB(0, 1), b2 + hstep, voffB); PG8_STAGE(PG8_SA(0, 0), a2, voffA);
;             PG8_WAIT_V(8); PG8_WAIT_L(0); PG8_BAR; PG8_MMA(1, 0, At, B0); PG8_MMA(1, 1, At, B1); PG8_BAR; PG8_SCHED;
;             PG8_LDB(B0, 1, 0); PG8_LDB(B1, 1, 1); PG8_SCHED; PG8_LDA(At, 1, 0); PG8_STAGE(PG8_SA(0, 1), a2 + hstep, voffA);
;             PG8_WAIT_V(8); PG8_WAIT_L(0); PG8_BAR; PG8_MMA(0, 0, At, B0); PG8_MMA(0, 1, At, B1); PG8_BAR; PG8_SCHED;
.LBB0_191:
	s_add_u32 s22, s20, 0xfffc0080
	s_addc_u32 s23, s21, -1
	s_add_i32 s72, 0, 0x10000
	s_cmp_eq_u32 s70, 12
	s_cselect_b32 s25, s13, s23
	s_cselect_b32 s24, s57, s22
	s_cselect_b32 s23, s11, s63
	s_cselect_b32 s22, s58, s62
	s_add_i32 s74, 0, 0x14000
	v_add_u32_e32 v156, s72, v145
	v_add_u32_e32 v160, s74, v145
	ds_read_b128 v[140:143], v156
	ds_read_b128 v[148:151], v156 offset:1024
	ds_read_b128 v[152:155], v156 offset:2048
	ds_read_b128 v[156:159], v156 offset:3072
	ds_read_b128 v[178:181], v160
	ds_read_b128 v[182:185], v160 offset:1024
	ds_read_b128 v[186:189], v160 offset:2048
	ds_read_b128 v[190:193], v160 offset:3072
	v_lshl_add_u64 v[160:161], s[20:21], 0, v[136:137]
	s_add_i32 m0, s19, 0xc000
	ds_read_b128 v[194:197], v147
	ds_read_b128 v[198:201], v147 offset:1024
	ds_read_b128 v[202:205], v147 offset:2048
	ds_read_b128 v[214:217], v147 offset:3072
	ds_read_b128 v[218:221], v147 offset:4096
	ds_read_b128 v[222:225], v147 offset:5120
	ds_read_b128 v[226:229], v147 offset:6144
	ds_read_b128 v[230:233], v147 offset:7168
	global_load_lds_dwordx4 v[160:161], off
	v_lshl_add_u64 v[160:161], s[20:21], 0, v[138:139]
	s_add_i32 m0, s19, 0xe000
	s_nop 0
	global_load_lds_dwordx4 v[160:161], off
	s_waitcnt vmcnt(8) lgkmcnt(0)
	s_barrier
	s_setprio 1
	v_mfma_f32_16x16x32_bf16 v[126:129], v[140:143], v[194:197], v[126:129]
	v_mfma_f32_16x16x32_bf16 v[122:125], v[152:155], v[194:197], v[122:125]
	v_mfma_f32_16x16x32_bf16 v[118:121], v[140:143], v[202:205], v[118:121]
	v_mfma_f32_16x16x32_bf16 v[110:113], v[152:155], v[202:205], v[110:113]
	v_mfma_f32_16x16x32_bf16 v[102:105], v[140:143], v[218:221], v[102:105]
	v_mfma_f32_16x16x32_bf16 v[94:97], v[152:155], v[218:221], v[94:97]
	v_mfma_f32_16x16x32_bf16 v[86:89], v[140:143], v[226:229], v[86:89]
	v_mfma_f32_16x16x32_bf16 v[78:81], v[152:155], v[226:229], v[78:81]
	v_mfma_f32_16x16x32_bf16 v[126:129], v[148:151], v[198:201], v[126:129]
	v_mfma_f32_16x16x32_bf16 v[122:125], v[156:159], v[198:201], v[122:125]
	v_mfma_f32_16x16x32_bf16 v[118:121], v[148:151], v[214:217], v[118:121]
	v_mfma_f32_16x16x32_bf16 v[110:113], v[156:159], v[214:217], v[110:113]
	v_mfma_f32_16x16x32_bf16 v[102:105], v[148:151], v[222:225], v[102:105]
	v_mfma_f32_16x16x32_bf16 v[94:97], v[156:159], v[222:225], v[94:97]
	v_mfma_f32_16x16x32_bf16 v[86:89], v[148:151], v[230:233], v[86:89]
	v_mfma_f32_16x16x32_bf16 v[78:81], v[156:159], v[230:233], v[78:81]
	s_setprio 0
	s_setprio 1
	v_mfma_f32_16x16x32_bf16 v[114:117], v[178:181], v[194:197], v[114:117]
	v_mfma_f32_16x16x32_bf16 v[106:109], v[186:189], v[194:197], v[106:109]
	v_mfma_f32_16x16x32_bf16 v[98:101], v[178:181], v[202:205], v[98:101]
	v_mfma_f32_16x16x32_bf16 v[90:93], v[186:189], v[202:205], v[90:93]
	v_mfma_f32_16x16x32_bf16 v[82:85], v[178:181], v[218:221], v[82:85]
	v_mfma_f32_16x16x32_bf16 v[74:77], v[186:189], v[218:221], v[74:77]
	v_mfma_f32_16x16x32_bf16 v[70:73], v[178:181], v[226:229], v[70:73]
	v_mfma_f32_16x16x32_bf16 v[66:69], v[186:189], v[226:229], v[66:69]
	v_mfma_f32_16x16x32_bf16 v[114:117], v[182:185], v[198:201], v[114:117]
	v_mfma_f32_16x16x32_bf16 v[106:109], v[190:193], v[198:201], v[106:109]
	v_mfma_f32_16x16x32_bf16 v[98:101], v[182:185], v[214:217], v[98:101]
	v_mfma_f32_16x16x32_bf16 v[90:93], v[190:193], v[214:217], v[90:93]
	v_mfma_f32_16x16x32_bf16 v[82:85], v[182:185], v[222:225], v[82:85]
	v_mfma_f32_16x16x32_bf16 v[74:77], v[190:193], v[222:225], v[74:77]
	v_mfma_f32_16x16x32_bf16 v[70:73], v[182:185], v[230:233], v[70:73]
	v_mfma_f32_16x16x32_bf16 v[66:69], v[190:193], v[230:233], v[66:69]
	s_setprio 0
	s_barrier
	s_add_i32 s72, s72, s37
	v_lshl_add_u64 v[160:161], s[22:23], 0, v[0:1]
	s_mov_b32 m0, s72
	ds_read_b128 v[194:197], v147 offset:16384
	ds_read_b128 v[198:201], v147 offset:17408
	ds_read_b128 v[202:205], v147 offset:18432
	ds_read_b128 v[214:217], v147 offset:19456
	ds_read_b128 v[218:221], v147 offset:20480
	ds_read_b128 v[222:225], v147 offset:21504
	ds_read_b128 v[226:229], v147 offset:22528
	ds_read_b128 v[230:233], v147 offset:23552
	global_load_lds_dwordx4 v[160:161], off
	s_add_i32 m0, s72, 0x2000
	s_add_u32 s72, s22, 0x40000
	v_lshl_add_u64 v[162:163], s[22:23], 0, v[134:135]
	s_addc_u32 s73, s23, 0
	s_add_i32 s74, s74, s37
	global_load_lds_dwordx4 v[162:163], off
	v_lshl_add_u64 v[164:165], s[72:73], 0, v[0:1]
	s_mov_b32 m0, s74
	v_lshl_add_u64 v[166:167], s[24:25], 0, v[132:133]
	global_load_lds_dwordx4 v[164:165], off
	v_lshl_add_u64 v[164:165], s[72:73], 0, v[134:135]
	s_add_i32 m0, s74, 0x2000
	s_nop 0
	global_load_lds_dwordx4 v[164:165], off
	v_lshl_add_u64 v[164:165], s[24:25], 0, v[130:131]
	s_mov_b32 m0, s19
	s_nop 0
	global_load_lds_dwordx4 v[164:165], off
	s_mov_b32 m0, s46
	s_nop 0
	global_load_lds_dwordx4 v[166:167], off
	s_waitcnt vmcnt(8) lgkmcnt(0)
	s_barrier
; #define PG8_STAGE(bufoff, gbase, voff) do { _Pragma("unroll") for (int _i = 0; _i < 2; ++_i) \
;         __builtin_amdgcn_global_load_lds((const unsigned*)((const char*)(gbase) + (voff)[_i]), (PG8_LAS unsigned*)(lds + (bufoff) + ldsw + _i * 8192), 16, 0, 0); } while (0)
; #define PG8_LDA(dst, b, h) do { _Pragma("unroll") for (int m = 0; m < 4; ++m) _Pragma("unroll") for (int k = 0; k < 2; ++k) dst[m][k] = *(const PG8_LAS bf16x8*)(lds + PG8_SA(b, h) + aoff + m * 2048 + k * 1024); } while (0)
; #define PG8_LDB(dst, b, h) do { _Pragma("unroll") for (int n = 0; n < 2; ++n) _Pragma("unroll") for (int k = 0; k < 2; ++k) dst[n][k] = *(const PG8_LAS bf16x8*)(lds + PG8_SB(b, h) + boff + n * 2048 + k * 1024); } while (0)
; #define PG8_MMA(ai, bj, At, Bt) do { __builtin_amdgcn_s_setprio(1); _Pragma("unroll") for (int m = 0; m < 4; ++m) _Pragma("unroll") for (int n = 0; n < 2; ++n) _Pragma("unroll") for (int k = 0; k < 2; ++k) \
;         acc[ai][bj][m][n] = __builtin_amdgcn_mfma_f32_16x16x32_bf16(Bt[n][k], At[m][k], acc[ai][bj][m][n], 0, 0, 0); __builtin_amdgcn_s_setprio(0); } while (0)
; #define PG8_WAIT_V(n) asm volatile("s_waitcnt vmcnt(" #n ")" ::: "memory")
; #define PG8_WAIT_L(n) asm volatile("s_waitcnt lgkmcnt(" #n ")" ::: "memory")
; #define PG8_BAR __builtin_amdgcn_s_barrier()
; #define PG8_SCHED __builtin_amdgcn_sched_barrier(0)
; template <class Epi, class Sched, bool ALIGN_EPI = false, bool SP2 = false>
; __device__ __forceinline__ void gemm_phase(PG8_LAS unsigned char* lds, const Gemm g, const Sched& S, const Epi& E, int wave_s) {
;     ...
;             PG8_WAIT_V(8); PG8_WAIT_L(0); PG8_BAR; PG8_MMA(1, 0, At, B0); PG8_MMA(1, 1, At, B1); PG8_BAR; PG8_SCHED;
;             PG8_LDB(B0, 1, 0); PG8_LDB(B1, 1, 1); PG8_SCHED; PG8_LDA(At, 1, 0); PG8_STAGE(PG8_SA(0, 1), a2 + hstep, voffA);
;             PG8_WAIT_V(8); PG8_WAIT_L(0); PG8_BAR; PG8_MMA(0, 0, At, B0); PG8_MMA(0, 1, At, B1); PG8_BAR; PG8_SCHED;
	s_setprio 1
	v_mfma_f32_16x16x32_bf16 v[62:65], v[140:143], v[194:197], v[62:65]
	v_mfma_f32_16x16x32_bf16 v[58:61], v[152:155], v[194:197], v[58:61]
	v_mfma_f32_16x16x32_bf16 v[54:57], v[140:143], v[202:205], v[54:57]
	v_mfma_f32_16x16x32_bf16 v[46:49], v[152:155], v[202:205], v[46:49]
	v_mfma_f32_16x16x32_bf16 v[38:41], v[140:143], v[218:221], v[38:41]
	v_mfma_f32_16x16x32_bf16 v[30:33], v[152:155], v[218:221], v[30:33]
	v_mfma_f32_16x16x32_bf16 v[22:25], v[140:143], v[226:229], v[22:25]
	v_mfma_f32_16x16x32_bf16 v[14:17], v[152:155], v[226:229], v[14:17]
	v_mfma_f32_16x16x32_bf16 v[62:65], v[148:151], v[198:201], v[62:65]
	v_mfma_f32_16x16x32_bf16 v[58:61], v[156:159], v[198:201], v[58:61]
	v_mfma_f32_16x16x32_bf16 v[54:57], v[148:151], v[214:217], v[54:57]
	v_mfma_f32_16x16x32_bf16 v[46:49], v[156:159], v[214:217], v[46:49]
	v_mfma_f32_16x16x32_bf16 v[38:41], v[148:151], v[222:225], v[38:41]
	v_mfma_f32_16x16x32_bf16 v[30:33], v[156:159], v[222:225], v[30:33]
	v_mfma_f32_16x16x32_bf16 v[22:25], v[148:151], v[230:233], v[22:25]
	v_mfma_f32_16x16x32_bf16 v[14:17], v[156:159], v[230:233], v[14:17]
	s_setprio 0
	s_setprio 1
	v_mfma_f32_16x16x32_bf16 v[50:53], v[178:181], v[194:197], v[50:53]
	v_mfma_f32_16x16x32_bf16 v[42:45], v[186:189], v[194:197], v[42:45]
	v_mfma_f32_16x16x32_bf16 v[34:37], v[178:181], v[202:205], v[34:37]
	v_mfma_f32_16x16x32_bf16 v[26:29], v[186:189], v[202:205], v[26:29]
	v_mfma_f32_16x16x32_bf16 v[18:21], v[178:181], v[218:221], v[18:21]
	v_mfma_f32_16x16x32_bf16 v[10:13], v[186:189], v[218:221], v[10:13]
	v_mfma_f32_16x16x32_bf16 v[6:9], v[178:181], v[226:229], v[6:9]
	v_mfma_f32_16x16x32_bf16 v[2:5], v[186:189], v[226:229], v[2:5]
	v_mfma_f32_16x16x32_bf16 v[50:53], v[182:185], v[198:201], v[50:53]
	v_mfma_f32_16x16x32_bf16 v[42:45], v[190:193], v[198:201], v[42:45]
	v_mfma_f32_16x16x32_bf16 v[34:37], v[182:185], v[214:217], v[34:37]
	v_mfma_f32_16x16x32_bf16 v[26:29], v[190:193], v[214:217], v[26:29]
	v_mfma_f32_16x16x32_bf16 v[18:21], v[182:185], v[222:225], v[18:21]
	v_mfma_f32_16x16x32_bf16 v[10:13], v[190:193], v[222:225], v[10:13]
	v_mfma_f32_16x16x32_bf16 v[6:9], v[182:185], v[230:233], v[6:9]
	v_mfma_f32_16x16x32_bf16 v[2:5], v[190:193], v[230:233], v[2:5]
	s_setprio 0
	s_barrier
	s_add_i32 s72, 0, 0x18000
	s_add_i32 s73, 0, 0x1c000
	v_add_u32_e32 v156, s72, v145
	v_add_u32_e32 v168, s73, v145
	ds_read_b128 v[140:143], v156
	ds_read_b128 v[148:151], v156 offset:1024
	ds_read_b128 v[152:155], v156 offset:2048
	ds_read_b128 v[156:159], v156 offset:3072
	ds_read_b128 v[178:181], v168
	ds_read_b128 v[182:185], v168 offset:1024
	ds_read_b128 v[186:189], v168 offset:2048
	ds_read_b128 v[190:193], v168 offset:3072
	s_add_u32 s24, s24, 0x40000
	s_addc_u32 s25, s25, 0
	s_mov_b32 m0, s47
	v_lshl_add_u64 v[168:169], s[24:25], 0, v[130:131]
	ds_read_b128 v[194:197], v147 offset:32768
	ds_read_b128 v[198:201], v147 offset:33792
	ds_read_b128 v[202:205], v147 offset:34816
	ds_read_b128 v[214:217], v147 offset:35840
	ds_read_b128 v[218:221], v147 offset:36864
	ds_read_b128 v[222:225], v147 offset:37888
	ds_read_b128 v[226:229], v147 offset:38912
	ds_read_b128 v[230:233], v147 offset:39936
	global_load_lds_dwordx4 v[168:169], off
	v_lshl_add_u64 v[168:169], s[24:25], 0, v[132:133]
	s_mov_b32 m0, s48
	s_nop 0
	global_load_lds_dwordx4 v[168:169], off
	s_waitcnt vmcnt(8) lgkmcnt(0)
	s_barrier
	s_setprio 1
	v_mfma_f32_16x16x32_bf16 v[126:129], v[140:143], v[194:197], v[126:129]
	v_mfma_f32_16x16x32_bf16 v[122:125], v[152:155], v[194:197], v[122:125]
	v_mfma_f32_16x16x32_bf16 v[118:121], v[140:143], v[202:205], v[118:121]
	v_mfma_f32_16x16x32_bf16 v[110:113], v[152:155], v[202:205], v[110:113]
	v_mfma_f32_16x16x32_bf16 v[102:105], v[140:143], v[218:221], v[102:105]
	v_mfma_f32_16x16x32_bf16 v[94:97], v[152:155], v[218:221], v[94:97]
	v_mfma_f32_16x16x32_bf16 v[86:89], v[140:143], v[226:229], v[86:89]
	v_mfma_f32_16x16x32_bf16 v[78:81], v[152:155], v[226:229], v[78:81]
	v_mfma_f32_16x16x32_bf16 v[126:129], v[148:151], v[198:201], v[126:129]
	v_mfma_f32_16x16x32_bf16 v[122:125], v[156:159], v[198:201], v[122:125]
	v_mfma_f32_16x16x32_bf16 v[118:121], v[148:151], v[214:217], v[118:121]
	v_mfma_f32_16x16x32_bf16 v[110:113], v[156:159], v[214:217], v[110:113]
	v_mfma_f32_16x16x32_bf16 v[102:105], v[148:151], v[222:225], v[102:105]
	v_mfma_f32_16x16x32_bf16 v[94:97], v[156:159], v[222:225], v[94:97]
	v_mfma_f32_16x16x32_bf16 v[86:89], v[148:151], v[230:233], v[86:89]
	v_mfma_f32_16x16x32_bf16 v[78:81], v[156:159], v[230:233], v[78:81]
	s_setprio 0
	s_setprio 1
	v_mfma_f32_16x16x32_bf16 v[114:117], v[178:181], v[194:197], v[114:117]
	v_mfma_f32_16x16x32_bf16 v[106:109], v[186:189], v[194:197], v[106:109]
	v_mfma_f32_16x16x32_bf16 v[98:101], v[178:181], v[202:205], v[98:101]
	v_mfma_f32_16x16x32_bf16 v[90:93], v[186:189], v[202:205], v[90:93]
	v_mfma_f32_16x16x32_bf16 v[82:85], v[178:181], v[218:221], v[82:85]
	v_mfma_f32_16x16x32_bf16 v[74:77], v[186:189], v[218:221], v[74:77]
	v_mfma_f32_16x16x32_bf16 v[70:73], v[178:181], v[226:229], v[70:73]
	v_mfma_f32_16x16x32_bf16 v[66:69], v[186:189], v[226:229], v[66:69]
	v_mfma_f32_16x16x32_bf16 v[114:117], v[182:185], v[198:201], v[114:117]
	v_mfma_f32_16x16x32_bf16 v[106:109], v[190:193], v[198:201], v[106:109]
	v_mfma_f32_16x16x32_bf16 v[98:101], v[182:185], v[214:217], v[98:101]
	v_mfma_f32_16x16x32_bf16 v[90:93], v[190:193], v[214:217], v[90:93]
	v_mfma_f32_16x16x32_bf16 v[82:85], v[182:185], v[222:225], v[82:85]
	v_mfma_f32_16x16x32_bf16 v[74:77], v[190:193], v[222:225], v[74:77]
	v_mfma_f32_16x16x32_bf16 v[70:73], v[182:185], v[230:233], v[70:73]
	v_mfma_f32_16x16x32_bf16 v[66:69], v[190:193], v[230:233], v[66:69]
	s_setprio 0
	s_barrier
; #define PG8_STAGE(bufoff, gbase, voff) do { _Pragma("unroll") for (int _i = 0; _i < 2; ++_i) \
;         __builtin_amdgcn_global_load_lds((const unsigned*)((const char*)(gbase) + (voff)[_i]), (PG8_LAS unsigned*)(lds + (bufoff) + ldsw + _i * 8192), 16, 0, 0); } while (0)
; #define PG8_LDA(dst, b, h) do { _Pragma("unroll") for (int m = 0; m < 4; ++m) _Pragma("unroll") for (int k = 0; k < 2; ++k) dst[m][k] = *(const PG8_LAS bf16x8*)(lds + PG8_SA(b, h) + aoff + m * 2048 + k * 1024); } while (0)
; #define PG8_MMA(ai, bj, At, Bt) do { __builtin_amdgcn_s_setprio(1); _Pragma("unroll") for (int m = 0; m < 4; ++m) _Pragma("unroll") for (int n = 0; n < 2; ++n) _Pragma("unroll") for (int k = 0; k < 2; ++k) \
;         acc[ai][bj][m][n] = __builtin_amdgcn_mfma_f32_16x16x32_bf16(Bt[n][k], At[m][k], acc[ai][bj][m][n], 0, 0, 0); __builtin_amdgcn_s_setprio(0); } while (0)
; #define PG8_WAIT_V(n) asm volatile("s_waitcnt vmcnt(" #n ")" ::: "memory")
; #define PG8_WAIT_L(n) asm volatile("s_waitcnt lgkmcnt(" #n ")" ::: "memory")
; #define PG8_BAR __builtin_amdgcn_s_barrier()
; #define PG8_SCHED __builtin_amdgcn_sched_barrier(0)
; template <class Epi, class Sched, bool ALIGN_EPI = false, bool SP2 = false>
; __device__ __forceinline__ void gemm_phase(PG8_LAS unsigned char* lds, const Gemm g, const Sched& S, const Epi& E, int wave_s) {
;     ...
;         for (int t = 0; t < nt; t += 2) {
;     ...
;             PG8_LDA(At, 1, 1); PG8_STAGE(PG8_SB(1, 0), b3, voffB); PG8_STAGE(PG8_SB(1, 1), b3 + hstep, voffB); PG8_STAGE(PG8_SA(1, 0), a3, voffA);
;             PG8_WAIT_V(8); PG8_WAIT_L(0); PG8_BAR; PG8_MMA(1, 0, At, B0); PG8_MMA(1, 1, At, B1); PG8_BAR; PG8_SCHED;
	s_add_i32 s24, s72, s37
	v_lshl_add_u64 v[160:161], v[160:161], 0, s[60:61]
	s_mov_b32 m0, s24
	ds_read_b128 v[194:197], v147 offset:49152
	ds_read_b128 v[198:201], v147 offset:50176
	ds_read_b128 v[202:205], v147 offset:51200
	ds_read_b128 v[214:217], v147 offset:52224
	ds_read_b128 v[218:221], v147 offset:53248
	ds_read_b128 v[222:225], v147 offset:54272
	ds_read_b128 v[226:229], v147 offset:55296
	ds_read_b128 v[230:233], v147 offset:56320
	global_load_lds_dwordx4 v[160:161], off
	s_add_i32 m0, s24, 0x2000
	s_add_u32 s22, s22, 0x40080
	v_lshl_add_u64 v[160:161], v[162:163], 0, s[60:61]
	s_addc_u32 s23, s23, 0
	s_add_i32 s24, s73, s37
	global_load_lds_dwordx4 v[160:161], off
	v_lshl_add_u64 v[160:161], s[22:23], 0, v[0:1]
	s_mov_b32 m0, s24
	s_nop 0
	global_load_lds_dwordx4 v[160:161], off
	v_lshl_add_u64 v[160:161], s[22:23], 0, v[134:135]
	s_add_i32 m0, s24, 0x2000
	s_nop 0
	global_load_lds_dwordx4 v[160:161], off
	v_lshl_add_u64 v[160:161], v[164:165], 0, s[60:61]
	s_mov_b32 m0, s49
	s_nop 0
	global_load_lds_dwordx4 v[160:161], off
	v_lshl_add_u64 v[160:161], v[166:167], 0, s[60:61]
	s_mov_b32 m0, s50
	s_nop 0
	global_load_lds_dwordx4 v[160:161], off
	s_waitcnt vmcnt(8) lgkmcnt(0)
	s_barrier
	s_setprio 1
	v_mfma_f32_16x16x32_bf16 v[62:65], v[140:143], v[194:197], v[62:65]
	v_mfma_f32_16x16x32_bf16 v[58:61], v[152:155], v[194:197], v[58:61]
	v_mfma_f32_16x16x32_bf16 v[54:57], v[140:143], v[202:205], v[54:57]
	v_mfma_f32_16x16x32_bf16 v[46:49], v[152:155], v[202:205], v[46:49]
	v_mfma_f32_16x16x32_bf16 v[38:41], v[140:143], v[218:221], v[38:41]
	v_mfma_f32_16x16x32_bf16 v[30:33], v[152:155], v[218:221], v[30:33]
	v_mfma_f32_16x16x32_bf16 v[22:25], v[140:143], v[226:229], v[22:25]
	v_mfma_f32_16x16x32_bf16 v[14:17], v[152:155], v[226:229], v[14:17]
	v_mfma_f32_16x16x32_bf16 v[62:65], v[148:151], v[198:201], v[62:65]
	v_mfma_f32_16x16x32_bf16 v[58:61], v[156:159], v[198:201], v[58:61]
	v_mfma_f32_16x16x32_bf16 v[54:57], v[148:151], v[214:217], v[54:57]
	v_mfma_f32_16x16x32_bf16 v[46:49], v[156:159], v[214:217], v[46:49]
	v_mfma_f32_16x16x32_bf16 v[38:41], v[148:151], v[222:225], v[38:41]
	v_mfma_f32_16x16x32_bf16 v[30:33], v[156:159], v[222:225], v[30:33]
	v_mfma_f32_16x16x32_bf16 v[22:25], v[148:151], v[230:233], v[22:25]
	v_mfma_f32_16x16x32_bf16 v[14:17], v[156:159], v[230:233], v[14:17]
	s_setprio 0
	s_setprio 1
	v_mfma_f32_16x16x32_bf16 v[50:53], v[178:181], v[194:197], v[50:53]
	v_mfma_f32_16x16x32_bf16 v[42:45], v[186:189], v[194:197], v[42:45]
	v_mfma_f32_16x16x32_bf16 v[34:37], v[178:181], v[202:205], v[34:37]
	v_mfma_f32_16x16x32_bf16 v[26:29], v[186:189], v[202:205], v[26:29]
	v_mfma_f32_16x16x32_bf16 v[18:21], v[178:181], v[218:221], v[18:21]
	v_mfma_f32_16x16x32_bf16 v[10:13], v[186:189], v[218:221], v[10:13]
	v_mfma_f32_16x16x32_bf16 v[6:9], v[178:181], v[226:229], v[6:9]
	v_mfma_f32_16x16x32_bf16 v[2:5], v[186:189], v[226:229], v[2:5]
	v_mfma_f32_16x16x32_bf16 v[50:53], v[182:185], v[198:201], v[50:53]
	v_mfma_f32_16x16x32_bf16 v[42:45], v[190:193], v[198:201], v[42:45]
	v_mfma_f32_16x16x32_bf16 v[34:37], v[182:185], v[214:217], v[34:37]
	v_mfma_f32_16x16x32_bf16 v[26:29], v[190:193], v[214:217], v[26:29]
	v_mfma_f32_16x16x32_bf16 v[18:21], v[182:185], v[222:225], v[18:21]
	v_mfma_f32_16x16x32_bf16 v[10:13], v[190:193], v[222:225], v[10:13]
	v_mfma_f32_16x16x32_bf16 v[6:9], v[182:185], v[230:233], v[6:9]
	v_mfma_f32_16x16x32_bf16 v[2:5], v[190:193], v[230:233], v[2:5]
	s_setprio 0
	s_barrier
	s_add_i32 s70, s70, 2
	s_add_u32 s20, s20, 0x100
	s_addc_u32 s21, s21, 0
	s_add_u32 s62, s62, 0x100
	s_addc_u32 s63, s63, 0
	s_cmp_gt_u32 s70, 13
	s_cbranch_scc0 .LBB0_191
	s_and_b64 vcc, exec, s[8:9]
	s_cbranch_vccz .LBB0_194
	s_barrier

; __device__ __forceinline__ unsigned xb_add(unsigned* p, unsigned v) { return __hip_atomic_fetch_add(p, v, __ATOMIC_RELAXED, __HIP_MEMORY_SCOPE_AGENT); }
; __device__ __forceinline__ void xcd_barrier(const XcdBarrier& b, bool leader) {
;     ...
;         if (old + 1u == (gen + 1u) * nloc) {
;             __builtin_amdgcn_fence(__ATOMIC_RELEASE, "agent");
;             asm volatile("s_waitcnt vmcnt(0)" ::: "memory");
;             const unsigned og = xb_add(&bar[XB_TOP], 1u);
.LBB0_230:
	s_andn2_saveexec_b64 s[6:7], s[6:7]
	s_cbranch_execz .LBB0_250
	s_mov_b64 s[6:7], exec
	buffer_wbl2 sc1
	s_waitcnt vmcnt(0) lgkmcnt(0)
	v_mbcnt_lo_u32_b32 v0, s6, 0
	v_mbcnt_hi_u32_b32 v0, s7, v0
	v_cmp_eq_u32_e32 vcc, 0, v0
	s_and_saveexec_b64 s[8:9], vcc
	s_cbranch_execz .LBB0_233
	s_bcnt1_i32_b64 s6, s[6:7]
	v_mov_b32_e32 v3, s6
	v_readlane_b32 s6, v255, 6
	v_readlane_b32 s7, v255, 7
	s_nop 4
	global_atomic_add v3, v1, v3, s[6:7] sc0

; __device__ __forceinline__ unsigned xb_add(unsigned* p, unsigned v) { return __hip_atomic_fetch_add(p, v, __ATOMIC_RELAXED, __HIP_MEMORY_SCOPE_AGENT); }
; __device__ __forceinline__ void xcd_barrier(const XcdBarrier& b, bool leader) {
;     ...
;         if (old + 1u == (gen + 1u) * nloc) {
;             __builtin_amdgcn_fence(__ATOMIC_RELEASE, "agent");
;             asm volatile("s_waitcnt vmcnt(0)" ::: "memory");
;             const unsigned og = xb_add(&bar[XB_TOP], 1u);
.LBB0_344:
	s_andn2_saveexec_b64 s[4:5], s[4:5]
	s_cbranch_execz .LBB0_364
	s_mov_b64 s[4:5], exec
	buffer_wbl2 sc1
	s_waitcnt vmcnt(0) lgkmcnt(0)
	v_mbcnt_lo_u32_b32 v0, s4, 0
	v_mbcnt_hi_u32_b32 v0, s5, v0
	v_cmp_eq_u32_e32 vcc, 0, v0
	s_and_saveexec_b64 s[6:7], vcc
	s_cbranch_execz .LBB0_347
	s_bcnt1_i32_b64 s4, s[4:5]
	v_mov_b32_e32 v3, s4
	v_readlane_b32 s4, v255, 6
	v_readlane_b32 s5, v255, 7
	s_nop 4
	global_atomic_add v3, v1, v3, s[4:5] sc0

; #define PG8_STAGE(bufoff, gbase, voff) do { _Pragma("unroll") for (int _i = 0; _i < 2; ++_i) \
;         __builtin_amdgcn_global_load_lds((const unsigned*)((const char*)(gbase) + (voff)[_i]), (PG8_LAS unsigned*)(lds + (bufoff) + ldsw + _i * 8192), 16, 0, 0); } while (0)
; #define PG8_LDA(dst, b, h) do { _Pragma("unroll") for (int m = 0; m < 4; ++m) _Pragma("unroll") for (int k = 0; k < 2; ++k) dst[m][k] = *(const PG8_LAS bf16x8*)(lds + PG8_SA(b, h) + aoff + m * 2048 + k * 1024); } while (0)
; #define PG8_LDB(dst, b, h) do { _Pragma("unroll") for (int n = 0; n < 2; ++n) _Pragma("unroll") for (int k = 0; k < 2; ++k) dst[n][k] = *(const PG8_LAS bf16x8*)(lds + PG8_SB(b, h) + boff + n * 2048 + k * 1024); } while (0)
; #define PG8_BAR __builtin_amdgcn_s_barrier()
; template <class Epi, class Sched, bool ALIGN_EPI = false, bool SP2 = false>
; __device__ __forceinline__ void gemm_phase(PG8_LAS unsigned char* lds, const Gemm g, const Sched& S, const Epi& E, int wave_s) {
;     ...
;         const char* nA = has_next ? (const char*)g.A + (size_t)nxt.pm * tstep + (size_t)nxt.kq * kqstep : cA; const char* nB = has_next ? (const char*)g.Bt + (size_t)nxt.pn * tstep + (size_t)nxt.kq * kqstep : cB;
;         for (int t = 0; t < nt; t += 2) {
;             const bool last = (t == nt - 2);
;             const char* a1 = cA + (size_t)(t + 1) * kstep;
;             const char* a2 = last ? nA : cA + (size_t)(t + 2) * kstep; const char* b2 = last ? nB : cB + (size_t)(t + 2) * kstep;
;             const char* a3 = a2 + kstep; const char* b3 = b2 + kstep;
;             if (last && has_next) S.a_ready(nxt);
;             if constexpr (SP2) {
;             PG8_LDB(B0, 0, 0); PG8_LDB(B1, 0, 1); PG8_SCHED; PG8_LDA(At, 0, 0); PG8_STAGE(PG8_SA(1, 1), a1 + hstep, voffA);
;             PG8_WAIT_V(8); PG8_WAIT_L(0); PG8_BAR; PG8_MMA(0, 0, At, B0); PG8_MMA(0, 1, At, B1); PG8_BAR; PG8_SCHED;
;             PG8_LDA(At, 0, 1); PG8_STAGE(PG8_SB(0, 0), b2, voffB); PG8_STAGE(PG8_SB(0, 1), b2 + hstep, voffB); PG8_STAGE(PG8_SA(0, 0), a2, voffA);
;             PG8_WAIT_V(8); PG8_WAIT_L(0); PG8_BAR; PG8_MMA(1, 0, At, B0); PG8_MMA(1, 1, At, B1); PG8_BAR; PG8_SCHED;
;             PG8_LDB(B0, 1, 0); PG8_LDB(B1, 1, 1); PG8_SCHED; PG8_LDA(At, 1, 0); PG8_STAGE(PG8_SA(0, 1), a2 + hstep, voffA);
;             PG8_WAIT_V(8); PG8_WAIT_L(0); PG8_BAR; PG8_MMA(0, 0, At, B0); PG8_MMA(0, 1, At, B1); PG8_BAR; PG8_SCHED;
.LBB0_381:
	s_add_u32 s27, s20, s26
	s_addc_u32 s46, s21, 0
	s_add_u32 s34, s27, 0x100
	s_addc_u32 s35, s46, 0
	s_and_b64 s[28:29], s[24:25], exec
	s_cselect_b32 s29, s11, s35
	s_cselect_b32 s28, s77, s34
	s_add_u32 s26, s14, s26
	s_addc_u32 s34, s15, 0
	s_add_u32 s26, s26, 0x100
	s_addc_u32 s34, s34, 0
	s_add_i32 s87, 0, 0x10000
	s_and_b64 s[24:25], s[24:25], exec
	s_cselect_b32 s35, s9, s34
	s_cselect_b32 s34, s78, s26
	s_add_i32 s25, 0, 0x14000
	s_add_u32 s48, s27, 0x10080
	s_addc_u32 s49, s46, 0
	s_add_i32 s86, s87, s58
	s_add_i32 m0, s13, 0xc000
	s_add_i32 s89, s13, 0xe000
	s_add_i32 s83, s86, 0x2000
	s_add_u32 s46, s34, 0x10000
	v_add_u32_e32 v152, s87, v141
	v_add_u32_e32 v160, s25, v141
	s_addc_u32 s47, s35, 0
	s_add_i32 s85, s25, s58
	ds_read_b128 v[136:139], v152
	ds_read_b128 v[144:147], v152 offset:1024
	ds_read_b128 v[148:151], v152 offset:2048
	ds_read_b128 v[152:155], v152 offset:3072
	ds_read_b128 v[156:159], v160
	ds_read_b128 v[178:181], v160 offset:1024
	ds_read_b128 v[182:185], v160 offset:2048
	ds_read_b128 v[186:189], v160 offset:3072
	s_add_i32 s84, s85, 0x2000
	s_add_i32 s82, 0, 0x18000
	s_add_i32 s81, 0, 0x1c000
	s_add_u32 s26, s28, 0x10000
	s_addc_u32 s27, s29, 0
	s_add_i32 s80, s82, s58
	s_add_i32 s79, s80, 0x2000
	s_add_u32 s24, s34, 0x10080
	s_addc_u32 s25, s35, 0
	s_add_i32 s88, s81, s58
	s_add_i32 s87, s88, 0x2000
	v_lshl_add_u64 v[160:161], s[48:49], 0, v[130:131]
	ds_read_b128 v[190:193], v143
	ds_read_b128 v[194:197], v143 offset:1024
	ds_read_b128 v[198:201], v143 offset:2048
	ds_read_b128 v[202:205], v143 offset:3072
	ds_read_b128 v[214:217], v143 offset:4096
	ds_read_b128 v[218:221], v143 offset:5120
	ds_read_b128 v[222:225], v143 offset:6144
	ds_read_b128 v[226:229], v143 offset:7168
	global_load_lds_dwordx4 v[160:161], off
	v_lshl_add_u64 v[160:161], s[48:49], 0, v[132:133]
	s_mov_b32 m0, s89
	s_nop 0
	global_load_lds_dwordx4 v[160:161], off
	s_waitcnt vmcnt(8) lgkmcnt(0)
	s_barrier
	s_setprio 1
	v_mfma_f32_16x16x32_bf16 v[126:129], v[136:139], v[190:193], v[126:129]
	v_mfma_f32_16x16x32_bf16 v[122:125], v[148:151], v[190:193], v[122:125]
	v_mfma_f32_16x16x32_bf16 v[118:121], v[136:139], v[198:201], v[118:121]
	v_mfma_f32_16x16x32_bf16 v[110:113], v[148:151], v[198:201], v[110:113]
	v_mfma_f32_16x16x32_bf16 v[102:105], v[136:139], v[214:217], v[102:105]
	v_mfma_f32_16x16x32_bf16 v[94:97], v[148:151], v[214:217], v[94:97]
	v_mfma_f32_16x16x32_bf16 v[86:89], v[136:139], v[222:225], v[86:89]
	v_mfma_f32_16x16x32_bf16 v[78:81], v[148:151], v[222:225], v[78:81]
	v_mfma_f32_16x16x32_bf16 v[126:129], v[144:147], v[194:197], v[126:129]
	v_mfma_f32_16x16x32_bf16 v[122:125], v[152:155], v[194:197], v[122:125]
	v_mfma_f32_16x16x32_bf16 v[118:121], v[144:147], v[202:205], v[118:121]
	v_mfma_f32_16x16x32_bf16 v[110:113], v[152:155], v[202:205], v[110:113]
	v_mfma_f32_16x16x32_bf16 v[102:105], v[144:147], v[218:221], v[102:105]
	v_mfma_f32_16x16x32_bf16 v[94:97], v[152:155], v[218:221], v[94:97]
	v_mfma_f32_16x16x32_bf16 v[86:89], v[144:147], v[226:229], v[86:89]
	v_mfma_f32_16x16x32_bf16 v[78:81], v[152:155], v[226:229], v[78:81]
	s_setprio 0
	s_setprio 1
	v_mfma_f32_16x16x32_bf16 v[114:117], v[156:159], v[190:193], v[114:117]
	v_mfma_f32_16x16x32_bf16 v[106:109], v[182:185], v[190:193], v[106:109]
	v_mfma_f32_16x16x32_bf16 v[98:101], v[156:159], v[198:201], v[98:101]
	v_mfma_f32_16x16x32_bf16 v[90:93], v[182:185], v[198:201], v[90:93]
	v_mfma_f32_16x16x32_bf16 v[82:85], v[156:159], v[214:217], v[82:85]
	v_mfma_f32_16x16x32_bf16 v[74:77], v[182:185], v[214:217], v[74:77]
	v_mfma_f32_16x16x32_bf16 v[70:73], v[156:159], v[222:225], v[70:73]
	v_mfma_f32_16x16x32_bf16 v[66:69], v[182:185], v[222:225], v[66:69]
	v_mfma_f32_16x16x32_bf16 v[114:117], v[178:181], v[194:197], v[114:117]
	v_mfma_f32_16x16x32_bf16 v[106:109], v[186:189], v[194:197], v[106:109]
	v_mfma_f32_16x16x32_bf16 v[98:101], v[178:181], v[202:205], v[98:101]
	v_mfma_f32_16x16x32_bf16 v[90:93], v[186:189], v[202:205], v[90:93]
	v_mfma_f32_16x16x32_bf16 v[82:85], v[178:181], v[218:221], v[82:85]
	v_mfma_f32_16x16x32_bf16 v[74:77], v[186:189], v[218:221], v[74:77]
	v_mfma_f32_16x16x32_bf16 v[70:73], v[178:181], v[226:229], v[70:73]
	v_mfma_f32_16x16x32_bf16 v[66:69], v[186:189], v[226:229], v[66:69]
	s_setprio 0
	s_barrier
	s_mov_b32 m0, s86
	v_lshl_add_u64 v[160:161], s[34:35], 0, v[0:1]
	ds_read_b128 v[190:193], v143 offset:16384
	ds_read_b128 v[194:197], v143 offset:17408
	ds_read_b128 v[198:201], v143 offset:18432
	ds_read_b128 v[202:205], v143 offset:19456
	ds_read_b128 v[214:217], v143 offset:20480
	ds_read_b128 v[218:221], v143 offset:21504
	ds_read_b128 v[222:225], v143 offset:22528
	ds_read_b128 v[226:229], v143 offset:23552
	global_load_lds_dwordx4 v[160:161], off
	v_lshl_add_u64 v[162:163], s[34:35], 0, v[134:135]
	s_mov_b32 m0, s83
	v_lshl_add_u64 v[164:165], s[46:47], 0, v[0:1]
	global_load_lds_dwordx4 v[162:163], off
	s_mov_b32 m0, s85
	v_lshl_add_u64 v[166:167], s[28:29], 0, v[132:133]
	global_load_lds_dwordx4 v[164:165], off
	v_lshl_add_u64 v[164:165], s[46:47], 0, v[134:135]
	s_mov_b32 m0, s84
	s_nop 0
	global_load_lds_dwordx4 v[164:165], off
	v_lshl_add_u64 v[164:165], s[28:29], 0, v[130:131]
	s_mov_b32 m0, s13
	s_nop 0
	global_load_lds_dwordx4 v[164:165], off
	s_mov_b32 m0, s62
	s_nop 0
	global_load_lds_dwordx4 v[166:167], off
	s_waitcnt vmcnt(8) lgkmcnt(0)
	s_barrier
; #define PG8_STAGE(bufoff, gbase, voff) do { _Pragma("unroll") for (int _i = 0; _i < 2; ++_i) \
;         __builtin_amdgcn_global_load_lds((const unsigned*)((const char*)(gbase) + (voff)[_i]), (PG8_LAS unsigned*)(lds + (bufoff) + ldsw + _i * 8192), 16, 0, 0); } while (0)
; #define PG8_LDA(dst, b, h) do { _Pragma("unroll") for (int m = 0; m < 4; ++m) _Pragma("unroll") for (int k = 0; k < 2; ++k) dst[m][k] = *(const PG8_LAS bf16x8*)(lds + PG8_SA(b, h) + aoff + m * 2048 + k * 1024); } while (0)
; #define PG8_LDB(dst, b, h) do { _Pragma("unroll") for (int n = 0; n < 2; ++n) _Pragma("unroll") for (int k = 0; k < 2; ++k) dst[n][k] = *(const PG8_LAS bf16x8*)(lds + PG8_SB(b, h) + boff + n * 2048 + k * 1024); } while (0)
; #define PG8_MMA(ai, bj, At, Bt) do { __builtin_amdgcn_s_setprio(1); _Pragma("unroll") for (int m = 0; m < 4; ++m) _Pragma("unroll") for (int n = 0; n < 2; ++n) _Pragma("unroll") for (int k = 0; k < 2; ++k) \
;         acc[ai][bj][m][n] = __builtin_amdgcn_mfma_f32_16x16x32_bf16(Bt[n][k], At[m][k], acc[ai][bj][m][n], 0, 0, 0); __builtin_amdgcn_s_setprio(0); } while (0)
; #define PG8_WAIT_V(n) asm volatile("s_waitcnt vmcnt(" #n ")" ::: "memory")
; #define PG8_WAIT_L(n) asm volatile("s_waitcnt lgkmcnt(" #n ")" ::: "memory")
; #define PG8_BAR __builtin_amdgcn_s_barrier()
; #define PG8_SCHED __builtin_amdgcn_sched_barrier(0)
; template <class Epi, class Sched, bool ALIGN_EPI = false, bool SP2 = false>
; __device__ __forceinline__ void gemm_phase(PG8_LAS unsigned char* lds, const Gemm g, const Sched& S, const Epi& E, int wave_s) {
;     ...
;             PG8_WAIT_V(8); PG8_WAIT_L(0); PG8_BAR; PG8_MMA(1, 0, At, B0); PG8_MMA(1, 1, At, B1); PG8_BAR; PG8_SCHED;
;             PG8_LDB(B0, 1, 0); PG8_LDB(B1, 1, 1); PG8_SCHED; PG8_LDA(At, 1, 0); PG8_STAGE(PG8_SA(0, 1), a2 + hstep, voffA);
;             PG8_WAIT_V(8); PG8_WAIT_L(0); PG8_BAR; PG8_MMA(0, 0, At, B0); PG8_MMA(0, 1, At, B1); PG8_BAR; PG8_SCHED;
	s_setprio 1
	v_mfma_f32_16x16x32_bf16 v[62:65], v[136:139], v[190:193], v[62:65]
	v_mfma_f32_16x16x32_bf16 v[58:61], v[148:151], v[190:193], v[58:61]
	v_mfma_f32_16x16x32_bf16 v[54:57], v[136:139], v[198:201], v[54:57]
	v_mfma_f32_16x16x32_bf16 v[46:49], v[148:151], v[198:201], v[46:49]
	v_mfma_f32_16x16x32_bf16 v[38:41], v[136:139], v[214:217], v[38:41]
	v_mfma_f32_16x16x32_bf16 v[30:33], v[148:151], v[214:217], v[30:33]
	v_mfma_f32_16x16x32_bf16 v[22:25], v[136:139], v[222:225], v[22:25]
	v_mfma_f32_16x16x32_bf16 v[14:17], v[148:151], v[222:225], v[14:17]
	v_mfma_f32_16x16x32_bf16 v[62:65], v[144:147], v[194:197], v[62:65]
	v_mfma_f32_16x16x32_bf16 v[58:61], v[152:155], v[194:197], v[58:61]
	v_mfma_f32_16x16x32_bf16 v[54:57], v[144:147], v[202:205], v[54:57]
	v_mfma_f32_16x16x32_bf16 v[46:49], v[152:155], v[202:205], v[46:49]
	v_mfma_f32_16x16x32_bf16 v[38:41], v[144:147], v[218:221], v[38:41]
	v_mfma_f32_16x16x32_bf16 v[30:33], v[152:155], v[218:221], v[30:33]
	v_mfma_f32_16x16x32_bf16 v[22:25], v[144:147], v[226:229], v[22:25]
	v_mfma_f32_16x16x32_bf16 v[14:17], v[152:155], v[226:229], v[14:17]
	s_setprio 0
	s_setprio 1
	v_mfma_f32_16x16x32_bf16 v[50:53], v[156:159], v[190:193], v[50:53]
	v_mfma_f32_16x16x32_bf16 v[42:45], v[182:185], v[190:193], v[42:45]
	v_mfma_f32_16x16x32_bf16 v[34:37], v[156:159], v[198:201], v[34:37]
	v_mfma_f32_16x16x32_bf16 v[26:29], v[182:185], v[198:201], v[26:29]
	v_mfma_f32_16x16x32_bf16 v[18:21], v[156:159], v[214:217], v[18:21]
	v_mfma_f32_16x16x32_bf16 v[10:13], v[182:185], v[214:217], v[10:13]
	v_mfma_f32_16x16x32_bf16 v[6:9], v[156:159], v[222:225], v[6:9]
	v_mfma_f32_16x16x32_bf16 v[2:5], v[182:185], v[222:225], v[2:5]
	v_mfma_f32_16x16x32_bf16 v[50:53], v[178:181], v[194:197], v[50:53]
	v_mfma_f32_16x16x32_bf16 v[42:45], v[186:189], v[194:197], v[42:45]
	v_mfma_f32_16x16x32_bf16 v[34:37], v[178:181], v[202:205], v[34:37]
	v_mfma_f32_16x16x32_bf16 v[26:29], v[186:189], v[202:205], v[26:29]
	v_mfma_f32_16x16x32_bf16 v[18:21], v[178:181], v[218:221], v[18:21]
	v_mfma_f32_16x16x32_bf16 v[10:13], v[186:189], v[218:221], v[10:13]
	v_mfma_f32_16x16x32_bf16 v[6:9], v[178:181], v[226:229], v[6:9]
	v_mfma_f32_16x16x32_bf16 v[2:5], v[186:189], v[226:229], v[2:5]
	s_setprio 0
	s_barrier
	v_add_u32_e32 v152, s82, v141
	v_add_u32_e32 v168, s81, v141
	ds_read_b128 v[136:139], v152
	ds_read_b128 v[144:147], v152 offset:1024
	ds_read_b128 v[148:151], v152 offset:2048
	ds_read_b128 v[152:155], v152 offset:3072
	ds_read_b128 v[156:159], v168
	ds_read_b128 v[178:181], v168 offset:1024
	ds_read_b128 v[182:185], v168 offset:2048
	ds_read_b128 v[186:189], v168 offset:3072
	s_mov_b32 m0, s63
	v_lshl_add_u64 v[168:169], s[26:27], 0, v[130:131]
	ds_read_b128 v[190:193], v143 offset:32768
	ds_read_b128 v[194:197], v143 offset:33792
	ds_read_b128 v[198:201], v143 offset:34816
	ds_read_b128 v[202:205], v143 offset:35840
	ds_read_b128 v[214:217], v143 offset:36864
	ds_read_b128 v[218:221], v143 offset:37888
	ds_read_b128 v[222:225], v143 offset:38912
	ds_read_b128 v[226:229], v143 offset:39936
	global_load_lds_dwordx4 v[168:169], off
	v_lshl_add_u64 v[168:169], s[26:27], 0, v[132:133]
	s_mov_b32 m0, s70
	s_nop 0
	global_load_lds_dwordx4 v[168:169], off
	s_waitcnt vmcnt(8) lgkmcnt(0)
	s_barrier
	s_setprio 1
	v_mfma_f32_16x16x32_bf16 v[126:129], v[136:139], v[190:193], v[126:129]
	v_mfma_f32_16x16x32_bf16 v[122:125], v[148:151], v[190:193], v[122:125]
	v_mfma_f32_16x16x32_bf16 v[118:121], v[136:139], v[198:201], v[118:121]
	v_mfma_f32_16x16x32_bf16 v[110:113], v[148:151], v[198:201], v[110:113]
	v_mfma_f32_16x16x32_bf16 v[102:105], v[136:139], v[214:217], v[102:105]
	v_mfma_f32_16x16x32_bf16 v[94:97], v[148:151], v[214:217], v[94:97]
	v_mfma_f32_16x16x32_bf16 v[86:89], v[136:139], v[222:225], v[86:89]
	v_mfma_f32_16x16x32_bf16 v[78:81], v[148:151], v[222:225], v[78:81]
	v_mfma_f32_16x16x32_bf16 v[126:129], v[144:147], v[194:197], v[126:129]
	v_mfma_f32_16x16x32_bf16 v[122:125], v[152:155], v[194:197], v[122:125]
	v_mfma_f32_16x16x32_bf16 v[118:121], v[144:147], v[202:205], v[118:121]
	v_mfma_f32_16x16x32_bf16 v[110:113], v[152:155], v[202:205], v[110:113]
	v_mfma_f32_16x16x32_bf16 v[102:105], v[144:147], v[218:221], v[102:105]
	v_mfma_f32_16x16x32_bf16 v[94:97], v[152:155], v[218:221], v[94:97]
	v_mfma_f32_16x16x32_bf16 v[86:89], v[144:147], v[226:229], v[86:89]
	v_mfma_f32_16x16x32_bf16 v[78:81], v[152:155], v[226:229], v[78:81]
	s_setprio 0
	s_setprio 1
	v_mfma_f32_16x16x32_bf16 v[114:117], v[156:159], v[190:193], v[114:117]
	v_mfma_f32_16x16x32_bf16 v[106:109], v[182:185], v[190:193], v[106:109]
	v_mfma_f32_16x16x32_bf16 v[98:101], v[156:159], v[198:201], v[98:101]
	v_mfma_f32_16x16x32_bf16 v[90:93], v[182:185], v[198:201], v[90:93]
	v_mfma_f32_16x16x32_bf16 v[82:85], v[156:159], v[214:217], v[82:85]
	v_mfma_f32_16x16x32_bf16 v[74:77], v[182:185], v[214:217], v[74:77]
	v_mfma_f32_16x16x32_bf16 v[70:73], v[156:159], v[222:225], v[70:73]
	v_mfma_f32_16x16x32_bf16 v[66:69], v[182:185], v[222:225], v[66:69]
	v_mfma_f32_16x16x32_bf16 v[114:117], v[178:181], v[194:197], v[114:117]
	v_mfma_f32_16x16x32_bf16 v[106:109], v[186:189], v[194:197], v[106:109]
	v_mfma_f32_16x16x32_bf16 v[98:101], v[178:181], v[202:205], v[98:101]
	v_mfma_f32_16x16x32_bf16 v[90:93], v[186:189], v[202:205], v[90:93]
	v_mfma_f32_16x16x32_bf16 v[82:85], v[178:181], v[218:221], v[82:85]
	v_mfma_f32_16x16x32_bf16 v[74:77], v[186:189], v[218:221], v[74:77]
	v_mfma_f32_16x16x32_bf16 v[70:73], v[178:181], v[226:229], v[70:73]
	v_mfma_f32_16x16x32_bf16 v[66:69], v[186:189], v[226:229], v[66:69]
	s_setprio 0
	s_barrier
; #define PG8_STAGE(bufoff, gbase, voff) do { _Pragma("unroll") for (int _i = 0; _i < 2; ++_i) \
;         __builtin_amdgcn_global_load_lds((const unsigned*)((const char*)(gbase) + (voff)[_i]), (PG8_LAS unsigned*)(lds + (bufoff) + ldsw + _i * 8192), 16, 0, 0); } while (0)
; #define PG8_LDA(dst, b, h) do { _Pragma("unroll") for (int m = 0; m < 4; ++m) _Pragma("unroll") for (int k = 0; k < 2; ++k) dst[m][k] = *(const PG8_LAS bf16x8*)(lds + PG8_SA(b, h) + aoff + m * 2048 + k * 1024); } while (0)
; #define PG8_MMA(ai, bj, At, Bt) do { __builtin_amdgcn_s_setprio(1); _Pragma("unroll") for (int m = 0; m < 4; ++m) _Pragma("unroll") for (int n = 0; n < 2; ++n) _Pragma("unroll") for (int k = 0; k < 2; ++k) \
;         acc[ai][bj][m][n] = __builtin_amdgcn_mfma_f32_16x16x32_bf16(Bt[n][k], At[m][k], acc[ai][bj][m][n], 0, 0, 0); __builtin_amdgcn_s_setprio(0); } while (0)
; #define PG8_WAIT_V(n) asm volatile("s_waitcnt vmcnt(" #n ")" ::: "memory")
; #define PG8_WAIT_L(n) asm volatile("s_waitcnt lgkmcnt(" #n ")" ::: "memory")
; #define PG8_BAR __builtin_amdgcn_s_barrier()
; #define PG8_SCHED __builtin_amdgcn_sched_barrier(0)
; template <class Epi, class Sched, bool ALIGN_EPI = false, bool SP2 = false>
; __device__ __forceinline__ void gemm_phase(PG8_LAS unsigned char* lds, const Gemm g, const Sched& S, const Epi& E, int wave_s) {
;     ...
;             PG8_LDA(At, 1, 1); PG8_STAGE(PG8_SB(1, 0), b3, voffB); PG8_STAGE(PG8_SB(1, 1), b3 + hstep, voffB); PG8_STAGE(PG8_SA(1, 0), a3, voffA);
;             PG8_WAIT_V(8); PG8_WAIT_L(0); PG8_BAR; PG8_MMA(1, 0, At, B0); PG8_MMA(1, 1, At, B1); PG8_BAR; PG8_SCHED;
	s_mov_b32 m0, s80
	v_lshl_add_u64 v[160:161], v[160:161], 0, s[60:61]
	ds_read_b128 v[190:193], v143 offset:49152
	ds_read_b128 v[194:197], v143 offset:50176
	ds_read_b128 v[198:201], v143 offset:51200
	ds_read_b128 v[202:205], v143 offset:52224
	ds_read_b128 v[214:217], v143 offset:53248
	ds_read_b128 v[218:221], v143 offset:54272
	ds_read_b128 v[222:225], v143 offset:55296
	ds_read_b128 v[226:229], v143 offset:56320
	global_load_lds_dwordx4 v[160:161], off
	v_lshl_add_u64 v[160:161], v[162:163], 0, s[60:61]
	s_mov_b32 m0, s79
	s_nop 0
	global_load_lds_dwordx4 v[160:161], off
	v_lshl_add_u64 v[160:161], s[24:25], 0, v[0:1]
	s_mov_b32 m0, s88
	s_nop 0
	global_load_lds_dwordx4 v[160:161], off
	v_lshl_add_u64 v[160:161], s[24:25], 0, v[134:135]
	s_mov_b32 m0, s87
	s_nop 0
	global_load_lds_dwordx4 v[160:161], off
	v_lshl_add_u64 v[160:161], v[164:165], 0, s[60:61]
	s_mov_b32 m0, s72
	s_nop 0
	global_load_lds_dwordx4 v[160:161], off
	v_lshl_add_u64 v[160:161], v[166:167], 0, s[60:61]
	s_mov_b32 m0, s73
	s_nop 0
	global_load_lds_dwordx4 v[160:161], off
	s_waitcnt vmcnt(8) lgkmcnt(0)
	s_barrier
	s_setprio 1
	v_mfma_f32_16x16x32_bf16 v[62:65], v[136:139], v[190:193], v[62:65]
	v_mfma_f32_16x16x32_bf16 v[58:61], v[148:151], v[190:193], v[58:61]
	v_mfma_f32_16x16x32_bf16 v[54:57], v[136:139], v[198:201], v[54:57]
	v_mfma_f32_16x16x32_bf16 v[46:49], v[148:151], v[198:201], v[46:49]
	v_mfma_f32_16x16x32_bf16 v[38:41], v[136:139], v[214:217], v[38:41]
	v_mfma_f32_16x16x32_bf16 v[30:33], v[148:151], v[214:217], v[30:33]
	v_mfma_f32_16x16x32_bf16 v[22:25], v[136:139], v[222:225], v[22:25]
	v_mfma_f32_16x16x32_bf16 v[14:17], v[148:151], v[222:225], v[14:17]
	v_mfma_f32_16x16x32_bf16 v[62:65], v[144:147], v[194:197], v[62:65]
	v_mfma_f32_16x16x32_bf16 v[58:61], v[152:155], v[194:197], v[58:61]
	v_mfma_f32_16x16x32_bf16 v[54:57], v[144:147], v[202:205], v[54:57]
	v_mfma_f32_16x16x32_bf16 v[46:49], v[152:155], v[202:205], v[46:49]
	v_mfma_f32_16x16x32_bf16 v[38:41], v[144:147], v[218:221], v[38:41]
	v_mfma_f32_16x16x32_bf16 v[30:33], v[152:155], v[218:221], v[30:33]
	v_mfma_f32_16x16x32_bf16 v[22:25], v[144:147], v[226:229], v[22:25]
	v_mfma_f32_16x16x32_bf16 v[14:17], v[152:155], v[226:229], v[14:17]
	s_setprio 0
	s_setprio 1
	v_mfma_f32_16x16x32_bf16 v[50:53], v[156:159], v[190:193], v[50:53]
	v_mfma_f32_16x16x32_bf16 v[42:45], v[182:185], v[190:193], v[42:45]
	v_mfma_f32_16x16x32_bf16 v[34:37], v[156:159], v[198:201], v[34:37]
	v_mfma_f32_16x16x32_bf16 v[26:29], v[182:185], v[198:201], v[26:29]
	v_mfma_f32_16x16x32_bf16 v[18:21], v[156:159], v[214:217], v[18:21]
	v_mfma_f32_16x16x32_bf16 v[10:13], v[182:185], v[214:217], v[10:13]
	v_mfma_f32_16x16x32_bf16 v[6:9], v[156:159], v[222:225], v[6:9]
	v_mfma_f32_16x16x32_bf16 v[2:5], v[182:185], v[222:225], v[2:5]
	v_mfma_f32_16x16x32_bf16 v[50:53], v[178:181], v[194:197], v[50:53]
	v_mfma_f32_16x16x32_bf16 v[42:45], v[186:189], v[194:197], v[42:45]
	v_mfma_f32_16x16x32_bf16 v[34:37], v[178:181], v[202:205], v[34:37]
	v_mfma_f32_16x16x32_bf16 v[26:29], v[186:189], v[202:205], v[26:29]
	v_mfma_f32_16x16x32_bf16 v[18:21], v[178:181], v[218:221], v[18:21]
	v_mfma_f32_16x16x32_bf16 v[10:13], v[186:189], v[218:221], v[10:13]
	v_mfma_f32_16x16x32_bf16 v[6:9], v[178:181], v[226:229], v[6:9]
	v_mfma_f32_16x16x32_bf16 v[2:5], v[186:189], v[226:229], v[2:5]
	s_setprio 0
	s_barrier
	s_movk_i32 s26, 0x100
	s_andn2_b64 vcc, exec, s[22:23]
	s_mov_b64 s[24:25], -1
	s_mov_b64 s[22:23], 0
	s_cbranch_vccz .LBB0_381
	s_and_b64 vcc, exec, s[6:7]
	s_cbranch_vccz .LBB0_384
	s_barrier

; #define PG8_STAGE(bufoff, gbase, voff) do { _Pragma("unroll") for (int _i = 0; _i < 2; ++_i) \
;         __builtin_amdgcn_global_load_lds((const unsigned*)((const char*)(gbase) + (voff)[_i]), (PG8_LAS unsigned*)(lds + (bufoff) + ldsw + _i * 8192), 16, 0, 0); } while (0)
; #define PG8_LDA(dst, b, h) do { _Pragma("unroll") for (int m = 0; m < 4; ++m) _Pragma("unroll") for (int k = 0; k < 2; ++k) dst[m][k] = *(const PG8_LAS bf16x8*)(lds + PG8_SA(b, h) + aoff + m * 2048 + k * 1024); } while (0)
; #define PG8_LDB(dst, b, h) do { _Pragma("unroll") for (int n = 0; n < 2; ++n) _Pragma("unroll") for (int k = 0; k < 2; ++k) dst[n][k] = *(const PG8_LAS bf16x8*)(lds + PG8_SB(b, h) + boff + n * 2048 + k * 1024); } while (0)
; #define PG8_MMA(ai, bj, At, Bt) do { __builtin_amdgcn_s_setprio(1); _Pragma("unroll") for (int m = 0; m < 4; ++m) _Pragma("unroll") for (int n = 0; n < 2; ++n) _Pragma("unroll") for (int k = 0; k < 2; ++k) \
;         acc[ai][bj][m][n] = __builtin_amdgcn_mfma_f32_16x16x32_bf16(Bt[n][k], At[m][k], acc[ai][bj][m][n], 0, 0, 0); __builtin_amdgcn_s_setprio(0); } while (0)
; #define PG8_WAIT_V(n) asm volatile("s_waitcnt vmcnt(" #n ")" ::: "memory")
; #define PG8_WAIT_L(n) asm volatile("s_waitcnt lgkmcnt(" #n ")" ::: "memory")
; #define PG8_BAR __builtin_amdgcn_s_barrier()
; #define PG8_SCHED __builtin_amdgcn_sched_barrier(0)
; template <class Epi, class Sched, bool ALIGN_EPI = false, bool SP2 = false>
; __device__ __forceinline__ void gemm_phase(PG8_LAS unsigned char* lds, const Gemm g, const Sched& S, const Epi& E, int wave_s) {
;     ...
;             PG8_LDB(B0, 0, 0); PG8_LDB(B1, 0, 1); PG8_SCHED; PG8_LDA(At, 0, 0); PG8_STAGE(PG8_SA(1, 1), a1 + hstep, voffA);
;             PG8_WAIT_V(8); PG8_WAIT_L(0); PG8_BAR; PG8_MMA(0, 0, At, B0); PG8_MMA(0, 1, At, B1); PG8_BAR; PG8_SCHED;
;             PG8_LDA(At, 0, 1); PG8_STAGE(PG8_SB(0, 0), b2, voffB); PG8_STAGE(PG8_SB(0, 1), b2 + hstep, voffB); PG8_STAGE(PG8_SA(0, 0), a2, voffA);
;             PG8_WAIT_V(8); PG8_WAIT_L(0); PG8_BAR; PG8_MMA(1, 0, At, B0); PG8_MMA(1, 1, At, B1); PG8_BAR; PG8_SCHED;
;             PG8_LDB(B0, 1, 0); PG8_LDB(B1, 1, 1); PG8_SCHED; PG8_LDA(At, 1, 0); PG8_STAGE(PG8_SA(0, 1), a2 + hstep, voffA);
;             PG8_WAIT_V(8); PG8_WAIT_L(0); PG8_BAR; PG8_MMA(0, 0, At, B0); PG8_MMA(0, 1, At, B1); PG8_BAR; PG8_SCHED;
.LBB0_396:
	s_ashr_i32 s13, s12, 31
	s_lshl_b64 s[14:15], s[12:13], 16
	s_add_u32 s14, s27, s14
	s_addc_u32 s15, s28, s15
	s_and_b64 s[16:17], s[2:3], exec
	s_cselect_b32 s25, s15, s23
	s_cselect_b32 s24, s14, s22
	s_ashr_i32 s11, s10, 31
	s_lshl_b64 s[16:17], s[10:11], 16
	s_add_u32 s16, s29, s16
	s_addc_u32 s17, s34, s17
	s_and_b64 s[56:57], s[2:3], exec
	s_cselect_b32 s21, s17, s21
	s_cselect_b32 s20, s16, s20
	s_add_i32 s11, 0, 0x10000
	s_add_i32 s13, 0, 0x14000
	v_add_u32_e32 v14, s11, v139
	v_add_u32_e32 v30, s13, v139
	ds_read_b128 v[2:5], v14
	ds_read_b128 v[6:9], v14 offset:1024
	ds_read_b128 v[10:13], v14 offset:2048
	ds_read_b128 v[14:17], v14 offset:3072
	ds_read_b128 v[18:21], v30
	ds_read_b128 v[22:25], v30 offset:1024
	ds_read_b128 v[26:29], v30 offset:2048
	ds_read_b128 v[30:33], v30 offset:3072
	s_add_u32 s22, s22, 0x8080
	s_addc_u32 s23, s23, 0
	v_lshl_add_u64 v[66:67], s[22:23], 0, v[134:135]
	s_add_i32 m0, s19, 0xc000
	ds_read_b128 v[34:37], v141
	ds_read_b128 v[38:41], v141 offset:1024
	ds_read_b128 v[42:45], v141 offset:2048
	ds_read_b128 v[46:49], v141 offset:3072
	ds_read_b128 v[50:53], v141 offset:4096
	ds_read_b128 v[54:57], v141 offset:5120
	ds_read_b128 v[58:61], v141 offset:6144
	ds_read_b128 v[62:65], v141 offset:7168
	global_load_lds_dwordx4 v[66:67], off
	v_lshl_add_u64 v[66:67], s[22:23], 0, v[132:133]
	s_add_i32 m0, s19, 0xe000
	s_nop 0
	global_load_lds_dwordx4 v[66:67], off
	s_waitcnt vmcnt(8) lgkmcnt(0)
	s_barrier
	s_setprio 1
	v_mfma_f32_16x16x32_bf16 v[90:93], v[2:5], v[58:61], 0
	v_mfma_f32_16x16x32_bf16 v[66:69], v[2:5], v[34:37], 0
	v_mfma_f32_16x16x32_bf16 v[70:73], v[10:13], v[34:37], 0
	v_mfma_f32_16x16x32_bf16 v[74:77], v[2:5], v[42:45], 0
	v_mfma_f32_16x16x32_bf16 v[78:81], v[10:13], v[42:45], 0
	v_mfma_f32_16x16x32_bf16 v[82:85], v[2:5], v[50:53], 0
	v_mfma_f32_16x16x32_bf16 v[86:89], v[10:13], v[50:53], 0
	v_mfma_f32_16x16x32_bf16 v[94:97], v[6:9], v[62:65], v[90:93]
	v_mfma_f32_16x16x32_bf16 v[90:93], v[10:13], v[58:61], 0
	v_mfma_f32_16x16x32_bf16 v[66:69], v[6:9], v[38:41], v[66:69]
	v_mfma_f32_16x16x32_bf16 v[70:73], v[14:17], v[38:41], v[70:73]
	v_mfma_f32_16x16x32_bf16 v[74:77], v[6:9], v[46:49], v[74:77]
	v_mfma_f32_16x16x32_bf16 v[78:81], v[14:17], v[46:49], v[78:81]
	v_mfma_f32_16x16x32_bf16 v[82:85], v[6:9], v[54:57], v[82:85]
	v_mfma_f32_16x16x32_bf16 v[86:89], v[14:17], v[54:57], v[86:89]
	v_mfma_f32_16x16x32_bf16 v[102:105], v[14:17], v[62:65], v[90:93]
	s_setprio 0
	s_setprio 1
	v_mfma_f32_16x16x32_bf16 v[90:93], v[18:21], v[34:37], 0
	v_mfma_f32_16x16x32_bf16 v[34:37], v[26:29], v[34:37], 0
	v_mfma_f32_16x16x32_bf16 v[110:113], v[22:25], v[38:41], v[90:93]
	v_mfma_f32_16x16x32_bf16 v[34:37], v[30:33], v[38:41], v[34:37]
	v_mfma_f32_16x16x32_bf16 v[38:41], v[18:21], v[42:45], 0
	v_mfma_f32_16x16x32_bf16 v[42:45], v[26:29], v[42:45], 0
	v_mfma_f32_16x16x32_bf16 v[38:41], v[22:25], v[46:49], v[38:41]
	v_mfma_f32_16x16x32_bf16 v[42:45], v[30:33], v[46:49], v[42:45]
	v_mfma_f32_16x16x32_bf16 v[46:49], v[18:21], v[50:53], 0
	v_mfma_f32_16x16x32_bf16 v[50:53], v[26:29], v[50:53], 0
	v_mfma_f32_16x16x32_bf16 v[46:49], v[22:25], v[54:57], v[46:49]
	v_mfma_f32_16x16x32_bf16 v[54:57], v[30:33], v[54:57], v[50:53]
	v_mfma_f32_16x16x32_bf16 v[50:53], v[18:21], v[58:61], 0
	v_mfma_f32_16x16x32_bf16 v[142:145], v[22:25], v[62:65], v[50:53]
	v_mfma_f32_16x16x32_bf16 v[50:53], v[26:29], v[58:61], 0
	v_mfma_f32_16x16x32_bf16 v[146:149], v[30:33], v[62:65], v[50:53]
	s_setprio 0
	s_barrier
	s_add_i32 s11, s11, s35
	v_lshl_add_u64 v[136:137], s[20:21], 0, v[0:1]
	s_mov_b32 m0, s11
	s_nop 1
	ds_read_b128 v[50:53], v141 offset:16384
	ds_read_b128 v[58:61], v141 offset:17408
	ds_read_b128 v[62:65], v141 offset:18432
	ds_read_b128 v[90:93], v141 offset:19456
	ds_read_b128 v[98:101], v141 offset:20480
	ds_read_b128 v[106:109], v141 offset:21504
	ds_read_b128 v[114:117], v141 offset:22528
	ds_read_b128 v[118:121], v141 offset:23552
	global_load_lds_dwordx4 v[136:137], off
	s_add_i32 m0, s11, 0x2000
	s_add_u32 s22, s20, 0x8000
	v_lshl_add_u64 v[208:209], s[20:21], 0, v[130:131]
	s_addc_u32 s23, s21, 0
	s_add_i32 s11, s13, s35
	global_load_lds_dwordx4 v[208:209], off
	v_lshl_add_u64 v[122:123], s[22:23], 0, v[0:1]
	s_mov_b32 m0, s11
	v_lshl_add_u64 v[212:213], s[24:25], 0, v[134:135]
	global_load_lds_dwordx4 v[122:123], off
	v_lshl_add_u64 v[122:123], s[22:23], 0, v[130:131]
	s_add_i32 m0, s11, 0x2000
	v_lshl_add_u64 v[174:175], s[24:25], 0, v[132:133]
	global_load_lds_dwordx4 v[122:123], off
	s_mov_b32 m0, s19
	s_nop 0
	global_load_lds_dwordx4 v[212:213], off
	s_mov_b32 m0, s36
	s_nop 0
	global_load_lds_dwordx4 v[174:175], off
	s_waitcnt vmcnt(8) lgkmcnt(0)
	s_barrier
; #define PG8_STAGE(bufoff, gbase, voff) do { _Pragma("unroll") for (int _i = 0; _i < 2; ++_i) \
;         __builtin_amdgcn_global_load_lds((const unsigned*)((const char*)(gbase) + (voff)[_i]), (PG8_LAS unsigned*)(lds + (bufoff) + ldsw + _i * 8192), 16, 0, 0); } while (0)
; #define PG8_LDA(dst, b, h) do { _Pragma("unroll") for (int m = 0; m < 4; ++m) _Pragma("unroll") for (int k = 0; k < 2; ++k) dst[m][k] = *(const PG8_LAS bf16x8*)(lds + PG8_SA(b, h) + aoff + m * 2048 + k * 1024); } while (0)
; #define PG8_LDB(dst, b, h) do { _Pragma("unroll") for (int n = 0; n < 2; ++n) _Pragma("unroll") for (int k = 0; k < 2; ++k) dst[n][k] = *(const PG8_LAS bf16x8*)(lds + PG8_SB(b, h) + boff + n * 2048 + k * 1024); } while (0)
; #define PG8_MMA(ai, bj, At, Bt) do { __builtin_amdgcn_s_setprio(1); _Pragma("unroll") for (int m = 0; m < 4; ++m) _Pragma("unroll") for (int n = 0; n < 2; ++n) _Pragma("unroll") for (int k = 0; k < 2; ++k) \
;         acc[ai][bj][m][n] = __builtin_amdgcn_mfma_f32_16x16x32_bf16(Bt[n][k], At[m][k], acc[ai][bj][m][n], 0, 0, 0); __builtin_amdgcn_s_setprio(0); } while (0)
; #define PG8_WAIT_V(n) asm volatile("s_waitcnt vmcnt(" #n ")" ::: "memory")
; #define PG8_WAIT_L(n) asm volatile("s_waitcnt lgkmcnt(" #n ")" ::: "memory")
; #define PG8_BAR __builtin_amdgcn_s_barrier()
; #define PG8_SCHED __builtin_amdgcn_sched_barrier(0)
; template <class Epi, class Sched, bool ALIGN_EPI = false, bool SP2 = false>
; __device__ __forceinline__ void gemm_phase(PG8_LAS unsigned char* lds, const Gemm g, const Sched& S, const Epi& E, int wave_s) {
;     ...
;             PG8_WAIT_V(8); PG8_WAIT_L(0); PG8_BAR; PG8_MMA(1, 0, At, B0); PG8_MMA(1, 1, At, B1); PG8_BAR; PG8_SCHED;
;             PG8_LDB(B0, 1, 0); PG8_LDB(B1, 1, 1); PG8_SCHED; PG8_LDA(At, 1, 0); PG8_STAGE(PG8_SA(0, 1), a2 + hstep, voffA);
;             PG8_WAIT_V(8); PG8_WAIT_L(0); PG8_BAR; PG8_MMA(0, 0, At, B0); PG8_MMA(0, 1, At, B1); PG8_BAR; PG8_SCHED;
	s_setprio 1
	v_mfma_f32_16x16x32_bf16 v[122:125], v[2:5], v[50:53], 0
	v_mfma_f32_16x16x32_bf16 v[150:153], v[6:9], v[58:61], v[122:125]
	v_mfma_f32_16x16x32_bf16 v[122:125], v[10:13], v[50:53], 0
	v_mfma_f32_16x16x32_bf16 v[154:157], v[14:17], v[58:61], v[122:125]
	v_mfma_f32_16x16x32_bf16 v[122:125], v[2:5], v[62:65], 0
	v_mfma_f32_16x16x32_bf16 v[158:161], v[6:9], v[90:93], v[122:125]
	v_mfma_f32_16x16x32_bf16 v[122:125], v[10:13], v[62:65], 0
	v_mfma_f32_16x16x32_bf16 v[178:181], v[14:17], v[90:93], v[122:125]
	v_mfma_f32_16x16x32_bf16 v[122:125], v[2:5], v[98:101], 0
	v_mfma_f32_16x16x32_bf16 v[2:5], v[2:5], v[114:117], 0
	v_mfma_f32_16x16x32_bf16 v[182:185], v[6:9], v[106:109], v[122:125]
	v_mfma_f32_16x16x32_bf16 v[2:5], v[6:9], v[118:121], v[2:5]
	v_mfma_f32_16x16x32_bf16 v[6:9], v[10:13], v[114:117], 0
	v_mfma_f32_16x16x32_bf16 v[122:125], v[10:13], v[98:101], 0
	v_mfma_f32_16x16x32_bf16 v[6:9], v[14:17], v[118:121], v[6:9]
	v_mfma_f32_16x16x32_bf16 v[186:189], v[14:17], v[106:109], v[122:125]
	s_setprio 0
	s_setprio 1
	v_mfma_f32_16x16x32_bf16 v[14:17], v[26:29], v[50:53], 0
	v_mfma_f32_16x16x32_bf16 v[190:193], v[30:33], v[58:61], v[14:17]
	v_mfma_f32_16x16x32_bf16 v[14:17], v[18:21], v[62:65], 0
	v_mfma_f32_16x16x32_bf16 v[194:197], v[22:25], v[90:93], v[14:17]
	v_mfma_f32_16x16x32_bf16 v[14:17], v[26:29], v[62:65], 0
	v_mfma_f32_16x16x32_bf16 v[198:201], v[30:33], v[90:93], v[14:17]
	v_mfma_f32_16x16x32_bf16 v[14:17], v[18:21], v[98:101], 0
	v_mfma_f32_16x16x32_bf16 v[202:205], v[22:25], v[106:109], v[14:17]
	v_mfma_f32_16x16x32_bf16 v[14:17], v[26:29], v[98:101], 0
	v_mfma_f32_16x16x32_bf16 v[10:13], v[18:21], v[50:53], 0
	v_mfma_f32_16x16x32_bf16 v[214:217], v[30:33], v[106:109], v[14:17]
	v_mfma_f32_16x16x32_bf16 v[14:17], v[18:21], v[114:117], 0
	v_mfma_f32_16x16x32_bf16 v[10:13], v[22:25], v[58:61], v[10:13]
	v_mfma_f32_16x16x32_bf16 v[218:221], v[22:25], v[118:121], v[14:17]
	v_mfma_f32_16x16x32_bf16 v[14:17], v[26:29], v[114:117], 0
	v_mfma_f32_16x16x32_bf16 v[222:225], v[30:33], v[118:121], v[14:17]
	s_setprio 0
	s_barrier
	s_add_i32 s11, 0, 0x18000
	v_add_u32_e32 v22, s11, v139
	s_add_i32 s13, 0, 0x1c000
	s_nop 1
	ds_read_b128 v[14:17], v22
	ds_read_b128 v[18:21], v22 offset:1024
	ds_read_b128 v[26:29], v22 offset:2048
	ds_read_b128 v[226:229], v22 offset:3072
	v_add_u32_e32 v22, s13, v139
	ds_read_b128 v[230:233], v22
	ds_read_b128 v[234:237], v22 offset:1024
	ds_read_b128 v[238:241], v22 offset:2048
	ds_read_b128 v[242:245], v22 offset:3072
	s_add_u32 s22, s24, 0x8000
	s_addc_u32 s23, s25, 0
	s_mov_b32 m0, s37
	v_lshl_add_u64 v[50:51], s[22:23], 0, v[134:135]
	ds_read_b128 v[22:25], v141 offset:32768
	ds_read_b128 v[30:33], v141 offset:33792
	ds_read_b128 v[62:65], v141 offset:34816
	ds_read_b128 v[246:249], v141 offset:35840
	ds_read_b128 v[250:253], v141 offset:36864
	ds_read_b128 v[162:165], v141 offset:37888
	ds_read_b128 v[166:169], v141 offset:38912
	ds_read_b128 v[170:173], v141 offset:39936
	global_load_lds_dwordx4 v[50:51], off
	v_lshl_add_u64 v[50:51], s[22:23], 0, v[132:133]
	s_mov_b32 m0, s46
	s_nop 0
	global_load_lds_dwordx4 v[50:51], off
	s_waitcnt vmcnt(8) lgkmcnt(0)
	s_barrier
	s_setprio 1
	v_mfma_f32_16x16x32_bf16 v[50:53], v[14:17], v[22:25], v[66:69]
	v_mfma_f32_16x16x32_bf16 v[122:125], v[18:21], v[30:33], v[50:53]
	v_mfma_f32_16x16x32_bf16 v[50:53], v[26:29], v[22:25], v[70:73]
	v_mfma_f32_16x16x32_bf16 v[114:117], v[226:229], v[30:33], v[50:53]
	v_mfma_f32_16x16x32_bf16 v[50:53], v[14:17], v[62:65], v[74:77]
	v_mfma_f32_16x16x32_bf16 v[106:109], v[18:21], v[246:249], v[50:53]
	v_mfma_f32_16x16x32_bf16 v[50:53], v[26:29], v[62:65], v[78:81]
	v_mfma_f32_16x16x32_bf16 v[98:101], v[226:229], v[246:249], v[50:53]
	v_mfma_f32_16x16x32_bf16 v[50:53], v[14:17], v[250:253], v[82:85]
	v_mfma_f32_16x16x32_bf16 v[90:93], v[18:21], v[162:165], v[50:53]
	v_mfma_f32_16x16x32_bf16 v[50:53], v[26:29], v[250:253], v[86:89]
	v_mfma_f32_16x16x32_bf16 v[82:85], v[226:229], v[162:165], v[50:53]
	v_mfma_f32_16x16x32_bf16 v[50:53], v[14:17], v[166:169], v[94:97]
	v_mfma_f32_16x16x32_bf16 v[58:61], v[18:21], v[170:173], v[50:53]
	v_mfma_f32_16x16x32_bf16 v[50:53], v[26:29], v[166:169], v[102:105]
	v_mfma_f32_16x16x32_bf16 v[50:53], v[226:229], v[170:173], v[50:53]
	s_setprio 0
	s_setprio 1
	v_mfma_f32_16x16x32_bf16 v[66:69], v[230:233], v[22:25], v[110:113]
	v_mfma_f32_16x16x32_bf16 v[22:25], v[238:241], v[22:25], v[34:37]
	v_mfma_f32_16x16x32_bf16 v[118:121], v[242:245], v[30:33], v[22:25]
	v_mfma_f32_16x16x32_bf16 v[22:25], v[230:233], v[62:65], v[38:41]
	v_mfma_f32_16x16x32_bf16 v[110:113], v[234:237], v[246:249], v[22:25]
	v_mfma_f32_16x16x32_bf16 v[22:25], v[238:241], v[62:65], v[42:45]
	v_mfma_f32_16x16x32_bf16 v[102:105], v[242:245], v[246:249], v[22:25]
	v_mfma_f32_16x16x32_bf16 v[22:25], v[230:233], v[250:253], v[46:49]
	v_mfma_f32_16x16x32_bf16 v[94:97], v[234:237], v[162:165], v[22:25]
	v_mfma_f32_16x16x32_bf16 v[22:25], v[238:241], v[250:253], v[54:57]
	v_mfma_f32_16x16x32_bf16 v[86:89], v[242:245], v[162:165], v[22:25]
	v_mfma_f32_16x16x32_bf16 v[22:25], v[230:233], v[166:169], v[142:145]
	v_mfma_f32_16x16x32_bf16 v[62:65], v[234:237], v[170:173], v[22:25]
	v_mfma_f32_16x16x32_bf16 v[22:25], v[238:241], v[166:169], v[146:149]
	v_mfma_f32_16x16x32_bf16 v[126:129], v[234:237], v[30:33], v[66:69]
	v_mfma_f32_16x16x32_bf16 v[54:57], v[242:245], v[170:173], v[22:25]
	s_setprio 0
	s_barrier
; #define PG8_STAGE(bufoff, gbase, voff) do { _Pragma("unroll") for (int _i = 0; _i < 2; ++_i) \
;         __builtin_amdgcn_global_load_lds((const unsigned*)((const char*)(gbase) + (voff)[_i]), (PG8_LAS unsigned*)(lds + (bufoff) + ldsw + _i * 8192), 16, 0, 0); } while (0)
; #define PG8_LDA(dst, b, h) do { _Pragma("unroll") for (int m = 0; m < 4; ++m) _Pragma("unroll") for (int k = 0; k < 2; ++k) dst[m][k] = *(const PG8_LAS bf16x8*)(lds + PG8_SA(b, h) + aoff + m * 2048 + k * 1024); } while (0)
; #define PG8_MMA(ai, bj, At, Bt) do { __builtin_amdgcn_s_setprio(1); _Pragma("unroll") for (int m = 0; m < 4; ++m) _Pragma("unroll") for (int n = 0; n < 2; ++n) _Pragma("unroll") for (int k = 0; k < 2; ++k) \
;         acc[ai][bj][m][n] = __builtin_amdgcn_mfma_f32_16x16x32_bf16(Bt[n][k], At[m][k], acc[ai][bj][m][n], 0, 0, 0); __builtin_amdgcn_s_setprio(0); } while (0)
; #define PG8_WAIT_V(n) asm volatile("s_waitcnt vmcnt(" #n ")" ::: "memory")
; #define PG8_WAIT_L(n) asm volatile("s_waitcnt lgkmcnt(" #n ")" ::: "memory")
; #define PG8_BAR __builtin_amdgcn_s_barrier()
; #define PG8_SCHED __builtin_amdgcn_sched_barrier(0)
; template <class Epi, class Sched, bool ALIGN_EPI = false, bool SP2 = false>
; __device__ __forceinline__ void gemm_phase(PG8_LAS unsigned char* lds, const Gemm g, const Sched& S, const Epi& E, int wave_s) {
;     ...
;             PG8_LDA(At, 1, 1); PG8_STAGE(PG8_SB(1, 0), b3, voffB); PG8_STAGE(PG8_SB(1, 1), b3 + hstep, voffB); PG8_STAGE(PG8_SA(1, 0), a3, voffA);
;             PG8_WAIT_V(8); PG8_WAIT_L(0); PG8_BAR; PG8_MMA(1, 0, At, B0); PG8_MMA(1, 1, At, B1); PG8_BAR; PG8_SCHED;
;     ...
;         if constexpr (ALIGN_EPI) { if (wr == 0) PG8_BAR; }
;         if constexpr (!Epi::AFTER_DRAIN) { E(acc, cur, wr, wc, fr, fq); S.done(cur); }
;         if (!has_next) break;
	s_add_i32 s11, s11, s35
	s_nop 2
	v_lshl_add_u64 v[22:23], v[136:137], 0, s[60:61]
	s_mov_b32 m0, s11
	ds_read_b128 v[34:37], v141 offset:49152
	ds_read_b128 v[42:45], v141 offset:50176
	ds_read_b128 v[142:145], v141 offset:51200
	ds_read_b128 v[146:149], v141 offset:52224
	ds_read_b128 v[162:165], v141 offset:53248
	ds_read_b128 v[166:169], v141 offset:54272
	ds_read_b128 v[170:173], v141 offset:55296
	ds_read_b128 v[246:249], v141 offset:56320
	global_load_lds_dwordx4 v[22:23], off
	s_add_i32 m0, s11, 0x2000
	s_add_u32 s20, s20, 0x8080
	v_lshl_add_u64 v[22:23], v[208:209], 0, s[60:61]
	s_addc_u32 s21, s21, 0
	s_add_i32 s11, s13, s35
	global_load_lds_dwordx4 v[22:23], off
	v_lshl_add_u64 v[22:23], s[20:21], 0, v[0:1]
	s_mov_b32 m0, s11
	s_nop 0
	global_load_lds_dwordx4 v[22:23], off
	v_lshl_add_u64 v[22:23], s[20:21], 0, v[130:131]
	s_add_i32 m0, s11, 0x2000
	s_nop 0
	global_load_lds_dwordx4 v[22:23], off
	v_lshl_add_u64 v[22:23], v[212:213], 0, s[60:61]
	s_mov_b32 m0, s47
	s_nop 0
	global_load_lds_dwordx4 v[22:23], off
	v_lshl_add_u64 v[22:23], v[174:175], 0, s[60:61]
	s_mov_b32 m0, s48
	s_nop 0
	global_load_lds_dwordx4 v[22:23], off
	s_waitcnt vmcnt(8) lgkmcnt(0)
	s_barrier
	s_setprio 1
	v_mfma_f32_16x16x32_bf16 v[22:25], v[14:17], v[34:37], v[150:153]
	v_mfma_f32_16x16x32_bf16 v[78:81], v[18:21], v[42:45], v[22:25]
	v_mfma_f32_16x16x32_bf16 v[22:25], v[26:29], v[34:37], v[154:157]
	v_mfma_f32_16x16x32_bf16 v[70:73], v[226:229], v[42:45], v[22:25]
	v_mfma_f32_16x16x32_bf16 v[22:25], v[14:17], v[142:145], v[158:161]
	v_mfma_f32_16x16x32_bf16 v[46:49], v[18:21], v[146:149], v[22:25]
	v_mfma_f32_16x16x32_bf16 v[22:25], v[26:29], v[142:145], v[178:181]
	v_mfma_f32_16x16x32_bf16 v[38:41], v[226:229], v[146:149], v[22:25]
	v_mfma_f32_16x16x32_bf16 v[22:25], v[14:17], v[162:165], v[182:185]
	v_mfma_f32_16x16x32_bf16 v[2:5], v[14:17], v[170:173], v[2:5]
	v_mfma_f32_16x16x32_bf16 v[30:33], v[18:21], v[166:169], v[22:25]
	v_mfma_f32_16x16x32_bf16 v[22:25], v[26:29], v[162:165], v[186:189]
	v_mfma_f32_16x16x32_bf16 v[14:17], v[18:21], v[246:249], v[2:5]
	v_mfma_f32_16x16x32_bf16 v[2:5], v[26:29], v[170:173], v[6:9]
	v_mfma_f32_16x16x32_bf16 v[22:25], v[226:229], v[166:169], v[22:25]
	v_mfma_f32_16x16x32_bf16 v[6:9], v[226:229], v[246:249], v[2:5]
	s_setprio 0
	s_setprio 1
	v_mfma_f32_16x16x32_bf16 v[2:5], v[230:233], v[34:37], v[10:13]
	v_mfma_f32_16x16x32_bf16 v[74:77], v[234:237], v[42:45], v[2:5]
	v_mfma_f32_16x16x32_bf16 v[2:5], v[238:241], v[34:37], v[190:193]
	v_mfma_f32_16x16x32_bf16 v[66:69], v[242:245], v[42:45], v[2:5]
	v_mfma_f32_16x16x32_bf16 v[2:5], v[230:233], v[142:145], v[194:197]
	v_mfma_f32_16x16x32_bf16 v[42:45], v[234:237], v[146:149], v[2:5]
	v_mfma_f32_16x16x32_bf16 v[2:5], v[238:241], v[142:145], v[198:201]
	v_mfma_f32_16x16x32_bf16 v[34:37], v[242:245], v[146:149], v[2:5]
	v_mfma_f32_16x16x32_bf16 v[2:5], v[230:233], v[162:165], v[202:205]
	v_mfma_f32_16x16x32_bf16 v[26:29], v[234:237], v[166:169], v[2:5]
	v_mfma_f32_16x16x32_bf16 v[2:5], v[238:241], v[162:165], v[214:217]
	v_mfma_f32_16x16x32_bf16 v[18:21], v[242:245], v[166:169], v[2:5]
	v_mfma_f32_16x16x32_bf16 v[2:5], v[230:233], v[170:173], v[218:221]
	v_mfma_f32_16x16x32_bf16 v[10:13], v[234:237], v[246:249], v[2:5]
	v_mfma_f32_16x16x32_bf16 v[2:5], v[238:241], v[170:173], v[222:225]
	v_mfma_f32_16x16x32_bf16 v[2:5], v[242:245], v[246:249], v[2:5]
	s_setprio 0
	s_barrier
	s_andn2_b64 vcc, exec, s[6:7]
	s_cbranch_vccnz .LBB0_398
	s_barrier

; #define PG8_STAGE(bufoff, gbase, voff) do { _Pragma("unroll") for (int _i = 0; _i < 2; ++_i) \
;         __builtin_amdgcn_global_load_lds((const unsigned*)((const char*)(gbase) + (voff)[_i]), (PG8_LAS unsigned*)(lds + (bufoff) + ldsw + _i * 8192), 16, 0, 0); } while (0)
; #define PG8_LDA(dst, b, h) do { _Pragma("unroll") for (int m = 0; m < 4; ++m) _Pragma("unroll") for (int k = 0; k < 2; ++k) dst[m][k] = *(const PG8_LAS bf16x8*)(lds + PG8_SA(b, h) + aoff + m * 2048 + k * 1024); } while (0)
; #define PG8_LDB(dst, b, h) do { _Pragma("unroll") for (int n = 0; n < 2; ++n) _Pragma("unroll") for (int k = 0; k < 2; ++k) dst[n][k] = *(const PG8_LAS bf16x8*)(lds + PG8_SB(b, h) + boff + n * 2048 + k * 1024); } while (0)
; #define PG8_BAR __builtin_amdgcn_s_barrier()
; template <class Epi, class Sched, bool ALIGN_EPI = false, bool SP2 = false>
; __device__ __forceinline__ void gemm_phase(PG8_LAS unsigned char* lds, const Gemm g, const Sched& S, const Epi& E, int wave_s) {
;     ...
;         const char* nA = has_next ? (const char*)g.A + (size_t)nxt.pm * tstep + (size_t)nxt.kq * kqstep : cA; const char* nB = has_next ? (const char*)g.Bt + (size_t)nxt.pn * tstep + (size_t)nxt.kq * kqstep : cB;
;         for (int t = 0; t < nt; t += 2) {
;             const bool last = (t == nt - 2);
;             const char* a1 = cA + (size_t)(t + 1) * kstep;
;             const char* a2 = last ? nA : cA + (size_t)(t + 2) * kstep; const char* b2 = last ? nB : cB + (size_t)(t + 2) * kstep;
;             const char* a3 = a2 + kstep; const char* b3 = b2 + kstep;
;             if (last && has_next) S.a_ready(nxt);
;             if constexpr (SP2) {
;             PG8_LDB(B0, 0, 0); PG8_LDB(B1, 0, 1); PG8_SCHED; PG8_LDA(At, 0, 0); PG8_STAGE(PG8_SA(1, 1), a1 + hstep, voffA);
;             PG8_WAIT_V(8); PG8_WAIT_L(0); PG8_BAR; PG8_MMA(0, 0, At, B0); PG8_MMA(0, 1, At, B1); PG8_BAR; PG8_SCHED;
;             PG8_LDA(At, 0, 1); PG8_STAGE(PG8_SB(0, 0), b2, voffB); PG8_STAGE(PG8_SB(0, 1), b2 + hstep, voffB); PG8_STAGE(PG8_SA(0, 0), a2, voffA);
;             PG8_WAIT_V(8); PG8_WAIT_L(0); PG8_BAR; PG8_MMA(1, 0, At, B0); PG8_MMA(1, 1, At, B1); PG8_BAR; PG8_SCHED;
;             PG8_LDB(B0, 1, 0); PG8_LDB(B1, 1, 1); PG8_SCHED; PG8_LDA(At, 1, 0); PG8_STAGE(PG8_SA(0, 1), a2 + hstep, voffA);
;             PG8_WAIT_V(8); PG8_WAIT_L(0); PG8_BAR; PG8_MMA(0, 0, At, B0); PG8_MMA(0, 1, At, B1); PG8_BAR; PG8_SCHED;
.LBB0_690:
	s_add_u32 s20, s18, 0xfffc0080
	s_addc_u32 s21, s19, -1
	s_add_i32 s70, 0, 0x10000
	s_cmp_eq_u32 s63, 12
	s_cselect_b32 s23, s11, s21
	s_cselect_b32 s22, s56, s20
	v_add_u32_e32 v140, s70, v143
	s_cselect_b32 s21, s9, s62
	s_cselect_b32 s20, s57, s58
	s_add_i32 s74, 0, 0x14000
	ds_read_b128 v[146:149], v140
	ds_read_b128 v[150:153], v140 offset:1024
	ds_read_b128 v[154:157], v140 offset:2048
	ds_read_b128 v[158:161], v140 offset:3072
	v_add_u32_e32 v140, s74, v143
	ds_read_b128 v[162:165], v140
	ds_read_b128 v[166:169], v140 offset:1024
	ds_read_b128 v[170:173], v140 offset:2048
	ds_read_b128 v[178:181], v140 offset:3072
	v_lshl_add_u64 v[140:141], s[18:19], 0, v[136:137]
	s_add_i32 m0, s13, 0xc000
	ds_read_b128 v[182:185], v145
	ds_read_b128 v[186:189], v145 offset:1024
	ds_read_b128 v[190:193], v145 offset:2048
	ds_read_b128 v[194:197], v145 offset:3072
	ds_read_b128 v[198:201], v145 offset:4096
	ds_read_b128 v[202:205], v145 offset:5120
	ds_read_b128 v[214:217], v145 offset:6144
	ds_read_b128 v[218:221], v145 offset:7168
	global_load_lds_dwordx4 v[140:141], off
	v_lshl_add_u64 v[140:141], s[18:19], 0, v[138:139]
	s_add_i32 m0, s13, 0xe000
	s_nop 0
	global_load_lds_dwordx4 v[140:141], off
	s_waitcnt vmcnt(8) lgkmcnt(0)
	s_barrier
	s_setprio 1
	v_mfma_f32_16x16x32_bf16 v[126:129], v[146:149], v[182:185], v[126:129]
	v_mfma_f32_16x16x32_bf16 v[122:125], v[154:157], v[182:185], v[122:125]
	v_mfma_f32_16x16x32_bf16 v[118:121], v[146:149], v[190:193], v[118:121]
	v_mfma_f32_16x16x32_bf16 v[110:113], v[154:157], v[190:193], v[110:113]
	v_mfma_f32_16x16x32_bf16 v[102:105], v[146:149], v[198:201], v[102:105]
	v_mfma_f32_16x16x32_bf16 v[94:97], v[154:157], v[198:201], v[94:97]
	v_mfma_f32_16x16x32_bf16 v[86:89], v[146:149], v[214:217], v[86:89]
	v_mfma_f32_16x16x32_bf16 v[78:81], v[154:157], v[214:217], v[78:81]
	v_mfma_f32_16x16x32_bf16 v[126:129], v[150:153], v[186:189], v[126:129]
	v_mfma_f32_16x16x32_bf16 v[122:125], v[158:161], v[186:189], v[122:125]
	v_mfma_f32_16x16x32_bf16 v[118:121], v[150:153], v[194:197], v[118:121]
	v_mfma_f32_16x16x32_bf16 v[110:113], v[158:161], v[194:197], v[110:113]
	v_mfma_f32_16x16x32_bf16 v[102:105], v[150:153], v[202:205], v[102:105]
	v_mfma_f32_16x16x32_bf16 v[94:97], v[158:161], v[202:205], v[94:97]
	v_mfma_f32_16x16x32_bf16 v[86:89], v[150:153], v[218:221], v[86:89]
	v_mfma_f32_16x16x32_bf16 v[78:81], v[158:161], v[218:221], v[78:81]
	s_setprio 0
	s_setprio 1
	v_mfma_f32_16x16x32_bf16 v[114:117], v[162:165], v[182:185], v[114:117]
	v_mfma_f32_16x16x32_bf16 v[106:109], v[170:173], v[182:185], v[106:109]
	v_mfma_f32_16x16x32_bf16 v[98:101], v[162:165], v[190:193], v[98:101]
	v_mfma_f32_16x16x32_bf16 v[90:93], v[170:173], v[190:193], v[90:93]
	v_mfma_f32_16x16x32_bf16 v[82:85], v[162:165], v[198:201], v[82:85]
	v_mfma_f32_16x16x32_bf16 v[74:77], v[170:173], v[198:201], v[74:77]
	v_mfma_f32_16x16x32_bf16 v[70:73], v[162:165], v[214:217], v[70:73]
	v_mfma_f32_16x16x32_bf16 v[66:69], v[170:173], v[214:217], v[66:69]
	v_mfma_f32_16x16x32_bf16 v[114:117], v[166:169], v[186:189], v[114:117]
	v_mfma_f32_16x16x32_bf16 v[106:109], v[178:181], v[186:189], v[106:109]
	v_mfma_f32_16x16x32_bf16 v[98:101], v[166:169], v[194:197], v[98:101]
	v_mfma_f32_16x16x32_bf16 v[90:93], v[178:181], v[194:197], v[90:93]
	v_mfma_f32_16x16x32_bf16 v[82:85], v[166:169], v[202:205], v[82:85]
	v_mfma_f32_16x16x32_bf16 v[74:77], v[178:181], v[202:205], v[74:77]
	v_mfma_f32_16x16x32_bf16 v[70:73], v[166:169], v[218:221], v[70:73]
	v_mfma_f32_16x16x32_bf16 v[66:69], v[178:181], v[218:221], v[66:69]
	s_setprio 0
	s_barrier
	s_add_i32 s70, s70, s35
	v_lshl_add_u64 v[140:141], s[20:21], 0, v[0:1]
	s_mov_b32 m0, s70
	ds_read_b128 v[182:185], v145 offset:16384
	ds_read_b128 v[186:189], v145 offset:17408
	ds_read_b128 v[190:193], v145 offset:18432
	ds_read_b128 v[194:197], v145 offset:19456
	ds_read_b128 v[198:201], v145 offset:20480
	ds_read_b128 v[202:205], v145 offset:21504
	ds_read_b128 v[214:217], v145 offset:22528
	ds_read_b128 v[218:221], v145 offset:23552
	global_load_lds_dwordx4 v[140:141], off
	s_add_i32 m0, s70, 0x2000
	s_add_u32 s72, s20, 0x40000
	v_lshl_add_u64 v[174:175], s[20:21], 0, v[134:135]
	s_addc_u32 s73, s21, 0
	s_add_i32 s70, s74, s35
	global_load_lds_dwordx4 v[174:175], off
	v_lshl_add_u64 v[208:209], s[72:73], 0, v[0:1]
	s_mov_b32 m0, s70
	v_lshl_add_u64 v[212:213], s[22:23], 0, v[132:133]
	global_load_lds_dwordx4 v[208:209], off
	v_lshl_add_u64 v[208:209], s[72:73], 0, v[134:135]
	s_add_i32 m0, s70, 0x2000
	s_nop 0
	global_load_lds_dwordx4 v[208:209], off
	v_lshl_add_u64 v[208:209], s[22:23], 0, v[130:131]
	s_mov_b32 m0, s13
	s_nop 0
	global_load_lds_dwordx4 v[208:209], off
	s_mov_b32 m0, s36
	s_nop 0
	global_load_lds_dwordx4 v[212:213], off
	s_waitcnt vmcnt(8) lgkmcnt(0)
	s_barrier
; #define PG8_STAGE(bufoff, gbase, voff) do { _Pragma("unroll") for (int _i = 0; _i < 2; ++_i) \
;         __builtin_amdgcn_global_load_lds((const unsigned*)((const char*)(gbase) + (voff)[_i]), (PG8_LAS unsigned*)(lds + (bufoff) + ldsw + _i * 8192), 16, 0, 0); } while (0)
; #define PG8_LDA(dst, b, h) do { _Pragma("unroll") for (int m = 0; m < 4; ++m) _Pragma("unroll") for (int k = 0; k < 2; ++k) dst[m][k] = *(const PG8_LAS bf16x8*)(lds + PG8_SA(b, h) + aoff + m * 2048 + k * 1024); } while (0)
; #define PG8_LDB(dst, b, h) do { _Pragma("unroll") for (int n = 0; n < 2; ++n) _Pragma("unroll") for (int k = 0; k < 2; ++k) dst[n][k] = *(const PG8_LAS bf16x8*)(lds + PG8_SB(b, h) + boff + n * 2048 + k * 1024); } while (0)
; #define PG8_MMA(ai, bj, At, Bt) do { __builtin_amdgcn_s_setprio(1); _Pragma("unroll") for (int m = 0; m < 4; ++m) _Pragma("unroll") for (int n = 0; n < 2; ++n) _Pragma("unroll") for (int k = 0; k < 2; ++k) \
;         acc[ai][bj][m][n] = __builtin_amdgcn_mfma_f32_16x16x32_bf16(Bt[n][k], At[m][k], acc[ai][bj][m][n], 0, 0, 0); __builtin_amdgcn_s_setprio(0); } while (0)
; #define PG8_WAIT_V(n) asm volatile("s_waitcnt vmcnt(" #n ")" ::: "memory")
; #define PG8_WAIT_L(n) asm volatile("s_waitcnt lgkmcnt(" #n ")" ::: "memory")
; #define PG8_BAR __builtin_amdgcn_s_barrier()
; #define PG8_SCHED __builtin_amdgcn_sched_barrier(0)
; template <class Epi, class Sched, bool ALIGN_EPI = false, bool SP2 = false>
; __device__ __forceinline__ void gemm_phase(PG8_LAS unsigned char* lds, const Gemm g, const Sched& S, const Epi& E, int wave_s) {
;     ...
;             PG8_WAIT_V(8); PG8_WAIT_L(0); PG8_BAR; PG8_MMA(1, 0, At, B0); PG8_MMA(1, 1, At, B1); PG8_BAR; PG8_SCHED;
;             PG8_LDB(B0, 1, 0); PG8_LDB(B1, 1, 1); PG8_SCHED; PG8_LDA(At, 1, 0); PG8_STAGE(PG8_SA(0, 1), a2 + hstep, voffA);
;             PG8_WAIT_V(8); PG8_WAIT_L(0); PG8_BAR; PG8_MMA(0, 0, At, B0); PG8_MMA(0, 1, At, B1); PG8_BAR; PG8_SCHED;
	s_setprio 1
	v_mfma_f32_16x16x32_bf16 v[62:65], v[146:149], v[182:185], v[62:65]
	v_mfma_f32_16x16x32_bf16 v[58:61], v[154:157], v[182:185], v[58:61]
	v_mfma_f32_16x16x32_bf16 v[54:57], v[146:149], v[190:193], v[54:57]
	v_mfma_f32_16x16x32_bf16 v[46:49], v[154:157], v[190:193], v[46:49]
	v_mfma_f32_16x16x32_bf16 v[38:41], v[146:149], v[198:201], v[38:41]
	v_mfma_f32_16x16x32_bf16 v[30:33], v[154:157], v[198:201], v[30:33]
	v_mfma_f32_16x16x32_bf16 v[22:25], v[146:149], v[214:217], v[22:25]
	v_mfma_f32_16x16x32_bf16 v[14:17], v[154:157], v[214:217], v[14:17]
	v_mfma_f32_16x16x32_bf16 v[62:65], v[150:153], v[186:189], v[62:65]
	v_mfma_f32_16x16x32_bf16 v[58:61], v[158:161], v[186:189], v[58:61]
	v_mfma_f32_16x16x32_bf16 v[54:57], v[150:153], v[194:197], v[54:57]
	v_mfma_f32_16x16x32_bf16 v[46:49], v[158:161], v[194:197], v[46:49]
	v_mfma_f32_16x16x32_bf16 v[38:41], v[150:153], v[202:205], v[38:41]
	v_mfma_f32_16x16x32_bf16 v[30:33], v[158:161], v[202:205], v[30:33]
	v_mfma_f32_16x16x32_bf16 v[22:25], v[150:153], v[218:221], v[22:25]
	v_mfma_f32_16x16x32_bf16 v[14:17], v[158:161], v[218:221], v[14:17]
	s_setprio 0
	s_setprio 1
	v_mfma_f32_16x16x32_bf16 v[50:53], v[162:165], v[182:185], v[50:53]
	v_mfma_f32_16x16x32_bf16 v[42:45], v[170:173], v[182:185], v[42:45]
	v_mfma_f32_16x16x32_bf16 v[34:37], v[162:165], v[190:193], v[34:37]
	v_mfma_f32_16x16x32_bf16 v[26:29], v[170:173], v[190:193], v[26:29]
	v_mfma_f32_16x16x32_bf16 v[18:21], v[162:165], v[198:201], v[18:21]
	v_mfma_f32_16x16x32_bf16 v[10:13], v[170:173], v[198:201], v[10:13]
	v_mfma_f32_16x16x32_bf16 v[6:9], v[162:165], v[214:217], v[6:9]
	v_mfma_f32_16x16x32_bf16 v[2:5], v[170:173], v[214:217], v[2:5]
	v_mfma_f32_16x16x32_bf16 v[50:53], v[166:169], v[186:189], v[50:53]
	v_mfma_f32_16x16x32_bf16 v[42:45], v[178:181], v[186:189], v[42:45]
	v_mfma_f32_16x16x32_bf16 v[34:37], v[166:169], v[194:197], v[34:37]
	v_mfma_f32_16x16x32_bf16 v[26:29], v[178:181], v[194:197], v[26:29]
	v_mfma_f32_16x16x32_bf16 v[18:21], v[166:169], v[202:205], v[18:21]
	v_mfma_f32_16x16x32_bf16 v[10:13], v[178:181], v[202:205], v[10:13]
	v_mfma_f32_16x16x32_bf16 v[6:9], v[166:169], v[218:221], v[6:9]
	v_mfma_f32_16x16x32_bf16 v[2:5], v[178:181], v[218:221], v[2:5]
	s_setprio 0
	s_barrier
	s_add_i32 s70, 0, 0x18000
	s_add_i32 s72, 0, 0x1c000
	v_add_u32_e32 v158, s70, v143
	v_add_u32_e32 v178, s72, v143
	ds_read_b128 v[146:149], v158
	ds_read_b128 v[150:153], v158 offset:1024
	ds_read_b128 v[154:157], v158 offset:2048
	ds_read_b128 v[158:161], v158 offset:3072
	ds_read_b128 v[162:165], v178
	ds_read_b128 v[166:169], v178 offset:1024
	ds_read_b128 v[170:173], v178 offset:2048
	ds_read_b128 v[178:181], v178 offset:3072
	s_add_u32 s22, s22, 0x40000
	s_addc_u32 s23, s23, 0
	s_mov_b32 m0, s37
	v_lshl_add_u64 v[222:223], s[22:23], 0, v[130:131]
	ds_read_b128 v[182:185], v145 offset:32768
	ds_read_b128 v[186:189], v145 offset:33792
	ds_read_b128 v[190:193], v145 offset:34816
	ds_read_b128 v[194:197], v145 offset:35840
	ds_read_b128 v[198:201], v145 offset:36864
	ds_read_b128 v[202:205], v145 offset:37888
	ds_read_b128 v[214:217], v145 offset:38912
	ds_read_b128 v[218:221], v145 offset:39936
	global_load_lds_dwordx4 v[222:223], off
	v_lshl_add_u64 v[222:223], s[22:23], 0, v[132:133]
	s_mov_b32 m0, s46
	s_nop 0
	global_load_lds_dwordx4 v[222:223], off
	s_waitcnt vmcnt(8) lgkmcnt(0)
	s_barrier
	s_setprio 1
	v_mfma_f32_16x16x32_bf16 v[126:129], v[146:149], v[182:185], v[126:129]
	v_mfma_f32_16x16x32_bf16 v[122:125], v[154:157], v[182:185], v[122:125]
	v_mfma_f32_16x16x32_bf16 v[118:121], v[146:149], v[190:193], v[118:121]
	v_mfma_f32_16x16x32_bf16 v[110:113], v[154:157], v[190:193], v[110:113]
	v_mfma_f32_16x16x32_bf16 v[102:105], v[146:149], v[198:201], v[102:105]
	v_mfma_f32_16x16x32_bf16 v[94:97], v[154:157], v[198:201], v[94:97]
	v_mfma_f32_16x16x32_bf16 v[86:89], v[146:149], v[214:217], v[86:89]
	v_mfma_f32_16x16x32_bf16 v[78:81], v[154:157], v[214:217], v[78:81]
	v_mfma_f32_16x16x32_bf16 v[126:129], v[150:153], v[186:189], v[126:129]
	v_mfma_f32_16x16x32_bf16 v[122:125], v[158:161], v[186:189], v[122:125]
	v_mfma_f32_16x16x32_bf16 v[118:121], v[150:153], v[194:197], v[118:121]
	v_mfma_f32_16x16x32_bf16 v[110:113], v[158:161], v[194:197], v[110:113]
	v_mfma_f32_16x16x32_bf16 v[102:105], v[150:153], v[202:205], v[102:105]
	v_mfma_f32_16x16x32_bf16 v[94:97], v[158:161], v[202:205], v[94:97]
	v_mfma_f32_16x16x32_bf16 v[86:89], v[150:153], v[218:221], v[86:89]
	v_mfma_f32_16x16x32_bf16 v[78:81], v[158:161], v[218:221], v[78:81]
	s_setprio 0
	s_setprio 1
	v_mfma_f32_16x16x32_bf16 v[114:117], v[162:165], v[182:185], v[114:117]
	v_mfma_f32_16x16x32_bf16 v[106:109], v[170:173], v[182:185], v[106:109]
	v_mfma_f32_16x16x32_bf16 v[98:101], v[162:165], v[190:193], v[98:101]
	v_mfma_f32_16x16x32_bf16 v[90:93], v[170:173], v[190:193], v[90:93]
	v_mfma_f32_16x16x32_bf16 v[82:85], v[162:165], v[198:201], v[82:85]
	v_mfma_f32_16x16x32_bf16 v[74:77], v[170:173], v[198:201], v[74:77]
	v_mfma_f32_16x16x32_bf16 v[70:73], v[162:165], v[214:217], v[70:73]
	v_mfma_f32_16x16x32_bf16 v[66:69], v[170:173], v[214:217], v[66:69]
	v_mfma_f32_16x16x32_bf16 v[114:117], v[166:169], v[186:189], v[114:117]
	v_mfma_f32_16x16x32_bf16 v[106:109], v[178:181], v[186:189], v[106:109]
	v_mfma_f32_16x16x32_bf16 v[98:101], v[166:169], v[194:197], v[98:101]
	v_mfma_f32_16x16x32_bf16 v[90:93], v[178:181], v[194:197], v[90:93]
	v_mfma_f32_16x16x32_bf16 v[82:85], v[166:169], v[202:205], v[82:85]
	v_mfma_f32_16x16x32_bf16 v[74:77], v[178:181], v[202:205], v[74:77]
	v_mfma_f32_16x16x32_bf16 v[70:73], v[166:169], v[218:221], v[70:73]
	v_mfma_f32_16x16x32_bf16 v[66:69], v[178:181], v[218:221], v[66:69]
	s_setprio 0
	s_barrier
; #define PG8_STAGE(bufoff, gbase, voff) do { _Pragma("unroll") for (int _i = 0; _i < 2; ++_i) \
;         __builtin_amdgcn_global_load_lds((const unsigned*)((const char*)(gbase) + (voff)[_i]), (PG8_LAS unsigned*)(lds + (bufoff) + ldsw + _i * 8192), 16, 0, 0); } while (0)
; #define PG8_LDA(dst, b, h) do { _Pragma("unroll") for (int m = 0; m < 4; ++m) _Pragma("unroll") for (int k = 0; k < 2; ++k) dst[m][k] = *(const PG8_LAS bf16x8*)(lds + PG8_SA(b, h) + aoff + m * 2048 + k * 1024); } while (0)
; #define PG8_MMA(ai, bj, At, Bt) do { __builtin_amdgcn_s_setprio(1); _Pragma("unroll") for (int m = 0; m < 4; ++m) _Pragma("unroll") for (int n = 0; n < 2; ++n) _Pragma("unroll") for (int k = 0; k < 2; ++k) \
;         acc[ai][bj][m][n] = __builtin_amdgcn_mfma_f32_16x16x32_bf16(Bt[n][k], At[m][k], acc[ai][bj][m][n], 0, 0, 0); __builtin_amdgcn_s_setprio(0); } while (0)
; #define PG8_WAIT_V(n) asm volatile("s_waitcnt vmcnt(" #n ")" ::: "memory")
; #define PG8_WAIT_L(n) asm volatile("s_waitcnt lgkmcnt(" #n ")" ::: "memory")
; #define PG8_BAR __builtin_amdgcn_s_barrier()
; #define PG8_SCHED __builtin_amdgcn_sched_barrier(0)
; template <class Epi, class Sched, bool ALIGN_EPI = false, bool SP2 = false>
; __device__ __forceinline__ void gemm_phase(PG8_LAS unsigned char* lds, const Gemm g, const Sched& S, const Epi& E, int wave_s) {
;     ...
;         for (int t = 0; t < nt; t += 2) {
;     ...
;             PG8_LDA(At, 1, 1); PG8_STAGE(PG8_SB(1, 0), b3, voffB); PG8_STAGE(PG8_SB(1, 1), b3 + hstep, voffB); PG8_STAGE(PG8_SA(1, 0), a3, voffA);
;             PG8_WAIT_V(8); PG8_WAIT_L(0); PG8_BAR; PG8_MMA(1, 0, At, B0); PG8_MMA(1, 1, At, B1); PG8_BAR; PG8_SCHED;
	s_add_i32 s22, s70, s35
	v_lshl_add_u64 v[140:141], v[140:141], 0, s[60:61]
	s_mov_b32 m0, s22
	ds_read_b128 v[182:185], v145 offset:49152
	ds_read_b128 v[186:189], v145 offset:50176
	ds_read_b128 v[190:193], v145 offset:51200
	ds_read_b128 v[194:197], v145 offset:52224
	ds_read_b128 v[198:201], v145 offset:53248
	ds_read_b128 v[202:205], v145 offset:54272
	ds_read_b128 v[214:217], v145 offset:55296
	ds_read_b128 v[218:221], v145 offset:56320
	global_load_lds_dwordx4 v[140:141], off
	s_add_i32 m0, s22, 0x2000
	s_add_u32 s20, s20, 0x40080
	v_lshl_add_u64 v[140:141], v[174:175], 0, s[60:61]
	s_addc_u32 s21, s21, 0
	s_add_i32 s22, s72, s35
	global_load_lds_dwordx4 v[140:141], off
	v_lshl_add_u64 v[140:141], s[20:21], 0, v[0:1]
	s_mov_b32 m0, s22
	s_nop 0
	global_load_lds_dwordx4 v[140:141], off
	v_lshl_add_u64 v[140:141], s[20:21], 0, v[134:135]
	s_add_i32 m0, s22, 0x2000
	s_nop 0
	global_load_lds_dwordx4 v[140:141], off
	v_lshl_add_u64 v[140:141], v[208:209], 0, s[60:61]
	s_mov_b32 m0, s47
	s_nop 0
	global_load_lds_dwordx4 v[140:141], off
	v_lshl_add_u64 v[140:141], v[212:213], 0, s[60:61]
	s_mov_b32 m0, s48
	s_nop 0
	global_load_lds_dwordx4 v[140:141], off
	s_waitcnt vmcnt(8) lgkmcnt(0)
	s_barrier
	s_setprio 1
	v_mfma_f32_16x16x32_bf16 v[62:65], v[146:149], v[182:185], v[62:65]
	v_mfma_f32_16x16x32_bf16 v[58:61], v[154:157], v[182:185], v[58:61]
	v_mfma_f32_16x16x32_bf16 v[54:57], v[146:149], v[190:193], v[54:57]
	v_mfma_f32_16x16x32_bf16 v[46:49], v[154:157], v[190:193], v[46:49]
	v_mfma_f32_16x16x32_bf16 v[38:41], v[146:149], v[198:201], v[38:41]
	v_mfma_f32_16x16x32_bf16 v[30:33], v[154:157], v[198:201], v[30:33]
	v_mfma_f32_16x16x32_bf16 v[22:25], v[146:149], v[214:217], v[22:25]
	v_mfma_f32_16x16x32_bf16 v[14:17], v[154:157], v[214:217], v[14:17]
	v_mfma_f32_16x16x32_bf16 v[62:65], v[150:153], v[186:189], v[62:65]
	v_mfma_f32_16x16x32_bf16 v[58:61], v[158:161], v[186:189], v[58:61]
	v_mfma_f32_16x16x32_bf16 v[54:57], v[150:153], v[194:197], v[54:57]
	v_mfma_f32_16x16x32_bf16 v[46:49], v[158:161], v[194:197], v[46:49]
	v_mfma_f32_16x16x32_bf16 v[38:41], v[150:153], v[202:205], v[38:41]
	v_mfma_f32_16x16x32_bf16 v[30:33], v[158:161], v[202:205], v[30:33]
	v_mfma_f32_16x16x32_bf16 v[22:25], v[150:153], v[218:221], v[22:25]
	v_mfma_f32_16x16x32_bf16 v[14:17], v[158:161], v[218:221], v[14:17]
	s_setprio 0
	s_setprio 1
	v_mfma_f32_16x16x32_bf16 v[50:53], v[162:165], v[182:185], v[50:53]
	v_mfma_f32_16x16x32_bf16 v[42:45], v[170:173], v[182:185], v[42:45]
	v_mfma_f32_16x16x32_bf16 v[34:37], v[162:165], v[190:193], v[34:37]
	v_mfma_f32_16x16x32_bf16 v[26:29], v[170:173], v[190:193], v[26:29]
	v_mfma_f32_16x16x32_bf16 v[18:21], v[162:165], v[198:201], v[18:21]
	v_mfma_f32_16x16x32_bf16 v[10:13], v[170:173], v[198:201], v[10:13]
	v_mfma_f32_16x16x32_bf16 v[6:9], v[162:165], v[214:217], v[6:9]
	v_mfma_f32_16x16x32_bf16 v[2:5], v[170:173], v[214:217], v[2:5]
	v_mfma_f32_16x16x32_bf16 v[50:53], v[166:169], v[186:189], v[50:53]
	v_mfma_f32_16x16x32_bf16 v[42:45], v[178:181], v[186:189], v[42:45]
	v_mfma_f32_16x16x32_bf16 v[34:37], v[166:169], v[194:197], v[34:37]
	v_mfma_f32_16x16x32_bf16 v[26:29], v[178:181], v[194:197], v[26:29]
	v_mfma_f32_16x16x32_bf16 v[18:21], v[166:169], v[202:205], v[18:21]
	v_mfma_f32_16x16x32_bf16 v[10:13], v[178:181], v[202:205], v[10:13]
	v_mfma_f32_16x16x32_bf16 v[6:9], v[166:169], v[218:221], v[6:9]
	v_mfma_f32_16x16x32_bf16 v[2:5], v[178:181], v[218:221], v[2:5]
	s_setprio 0
	s_barrier
	s_add_i32 s63, s63, 2
	s_add_u32 s18, s18, 0x100
	s_addc_u32 s19, s19, 0
	s_add_u32 s58, s58, 0x100
	s_addc_u32 s62, s62, 0
	s_cmp_gt_u32 s63, 13
	s_cbranch_scc0 .LBB0_690
	s_and_b64 vcc, exec, s[6:7]
	s_cbranch_vccz .LBB0_693
	s_barrier

; #define PG8_STAGE(bufoff, gbase, voff) do { _Pragma("unroll") for (int _i = 0; _i < 2; ++_i) \
;         __builtin_amdgcn_global_load_lds((const unsigned*)((const char*)(gbase) + (voff)[_i]), (PG8_LAS unsigned*)(lds + (bufoff) + ldsw + _i * 8192), 16, 0, 0); } while (0)
; #define PG8_LDA(dst, b, h) do { _Pragma("unroll") for (int m = 0; m < 4; ++m) _Pragma("unroll") for (int k = 0; k < 2; ++k) dst[m][k] = *(const PG8_LAS bf16x8*)(lds + PG8_SA(b, h) + aoff + m * 2048 + k * 1024); } while (0)
; #define PG8_LDB(dst, b, h) do { _Pragma("unroll") for (int n = 0; n < 2; ++n) _Pragma("unroll") for (int k = 0; k < 2; ++k) dst[n][k] = *(const PG8_LAS bf16x8*)(lds + PG8_SB(b, h) + boff + n * 2048 + k * 1024); } while (0)
; #define PG8_MMA(ai, bj, At, Bt) do { __builtin_amdgcn_s_setprio(1); _Pragma("unroll") for (int m = 0; m < 4; ++m) _Pragma("unroll") for (int n = 0; n < 2; ++n) _Pragma("unroll") for (int k = 0; k < 2; ++k) \
;         acc[ai][bj][m][n] = __builtin_amdgcn_mfma_f32_16x16x32_bf16(Bt[n][k], At[m][k], acc[ai][bj][m][n], 0, 0, 0); __builtin_amdgcn_s_setprio(0); } while (0)
; #define PG8_WAIT_V(n) asm volatile("s_waitcnt vmcnt(" #n ")" ::: "memory")
; #define PG8_WAIT_L(n) asm volatile("s_waitcnt lgkmcnt(" #n ")" ::: "memory")
; #define PG8_BAR __builtin_amdgcn_s_barrier()
; #define PG8_SCHED __builtin_amdgcn_sched_barrier(0)
; template <class Epi, class Sched, bool ALIGN_EPI = false, bool SP2 = false>
; __device__ __forceinline__ void gemm_phase(PG8_LAS unsigned char* lds, const Gemm g, const Sched& S, const Epi& E, int wave_s) {
;     ...
;             PG8_LDB(B0, 0, 0); PG8_LDB(B1, 0, 1); PG8_SCHED; PG8_LDA(At, 0, 0); PG8_STAGE(PG8_SA(1, 1), a1 + hstep, voffA);
;             PG8_WAIT_V(8); PG8_WAIT_L(0); PG8_BAR; PG8_MMA(0, 0, At, B0); PG8_MMA(0, 1, At, B1); PG8_BAR; PG8_SCHED;
;             PG8_LDA(At, 0, 1); PG8_STAGE(PG8_SB(0, 0), b2, voffB); PG8_STAGE(PG8_SB(0, 1), b2 + hstep, voffB); PG8_STAGE(PG8_SA(0, 0), a2, voffA);
.LBB0_710:
	s_add_i32 s57, 0, 0x10000
	s_add_i32 s17, 0, 0x14000
	v_add_u32_e32 v220, s57, v136
	v_add_u32_e32 v221, s17, v136
	ds_read_b128 v[2:5], v220
	ds_read_b128 v[6:9], v220 offset:1024
	ds_read_b128 v[10:13], v220 offset:2048
	ds_read_b128 v[14:17], v220 offset:3072
	ds_read_b128 v[18:21], v221
	ds_read_b128 v[22:25], v221 offset:1024
	ds_read_b128 v[26:29], v221 offset:2048
	ds_read_b128 v[30:33], v221 offset:3072
	s_add_u32 s72, s24, 0x40080
	s_addc_u32 s73, s25, 0
	s_add_i32 s62, s9, 0xc000
	v_lshl_add_u64 v[66:67], s[72:73], 0, v[134:135]
	s_mov_b32 m0, s62
	s_add_i32 s7, s9, 0xe000
	ds_read_b128 v[34:37], v139
	ds_read_b128 v[38:41], v139 offset:1024
	ds_read_b128 v[42:45], v139 offset:2048
	ds_read_b128 v[46:49], v139 offset:3072
	ds_read_b128 v[50:53], v139 offset:4096
	ds_read_b128 v[54:57], v139 offset:5120
	ds_read_b128 v[58:61], v139 offset:6144
	ds_read_b128 v[62:65], v139 offset:7168
	global_load_lds_dwordx4 v[66:67], off
	v_lshl_add_u64 v[66:67], s[72:73], 0, v[132:133]
	s_mov_b32 m0, s7
	s_nop 0
	global_load_lds_dwordx4 v[66:67], off
	s_waitcnt vmcnt(8) lgkmcnt(0)
	s_barrier
	s_setprio 1
	v_mfma_f32_16x16x32_bf16 v[66:69], v[2:5], v[34:37], 0
	v_mfma_f32_16x16x32_bf16 v[70:73], v[10:13], v[34:37], 0
	v_mfma_f32_16x16x32_bf16 v[74:77], v[2:5], v[42:45], 0
	v_mfma_f32_16x16x32_bf16 v[78:81], v[10:13], v[42:45], 0
	v_mfma_f32_16x16x32_bf16 v[82:85], v[2:5], v[50:53], 0
	v_mfma_f32_16x16x32_bf16 v[86:89], v[10:13], v[50:53], 0
	v_mfma_f32_16x16x32_bf16 v[90:93], v[2:5], v[58:61], 0
	v_mfma_f32_16x16x32_bf16 v[94:97], v[10:13], v[58:61], 0
	v_mfma_f32_16x16x32_bf16 v[66:69], v[6:9], v[38:41], v[66:69]
	v_mfma_f32_16x16x32_bf16 v[70:73], v[14:17], v[38:41], v[70:73]
	v_mfma_f32_16x16x32_bf16 v[74:77], v[6:9], v[46:49], v[74:77]
	v_mfma_f32_16x16x32_bf16 v[78:81], v[14:17], v[46:49], v[78:81]
	v_mfma_f32_16x16x32_bf16 v[82:85], v[6:9], v[54:57], v[82:85]
	v_mfma_f32_16x16x32_bf16 v[86:89], v[14:17], v[54:57], v[86:89]
	v_mfma_f32_16x16x32_bf16 v[90:93], v[6:9], v[62:65], v[90:93]
	v_mfma_f32_16x16x32_bf16 v[94:97], v[14:17], v[62:65], v[94:97]
	s_setprio 0
	s_setprio 1
	v_mfma_f32_16x16x32_bf16 v[98:101], v[18:21], v[34:37], 0
	v_mfma_f32_16x16x32_bf16 v[34:37], v[26:29], v[34:37], 0
	v_mfma_f32_16x16x32_bf16 v[98:101], v[22:25], v[38:41], v[98:101]
	v_mfma_f32_16x16x32_bf16 v[34:37], v[30:33], v[38:41], v[34:37]
	v_mfma_f32_16x16x32_bf16 v[38:41], v[18:21], v[42:45], 0
	v_mfma_f32_16x16x32_bf16 v[42:45], v[26:29], v[42:45], 0
	v_mfma_f32_16x16x32_bf16 v[38:41], v[22:25], v[46:49], v[38:41]
	v_mfma_f32_16x16x32_bf16 v[42:45], v[30:33], v[46:49], v[42:45]
	v_mfma_f32_16x16x32_bf16 v[46:49], v[18:21], v[50:53], 0
	v_mfma_f32_16x16x32_bf16 v[50:53], v[26:29], v[50:53], 0
	v_mfma_f32_16x16x32_bf16 v[46:49], v[22:25], v[54:57], v[46:49]
	v_mfma_f32_16x16x32_bf16 v[50:53], v[30:33], v[54:57], v[50:53]
	v_mfma_f32_16x16x32_bf16 v[54:57], v[18:21], v[58:61], 0
	v_mfma_f32_16x16x32_bf16 v[58:61], v[26:29], v[58:61], 0
	v_mfma_f32_16x16x32_bf16 v[54:57], v[22:25], v[62:65], v[54:57]
	v_mfma_f32_16x16x32_bf16 v[58:61], v[30:33], v[62:65], v[58:61]
	s_setprio 0
	s_barrier
	s_add_i32 s57, s57, s37
	v_lshl_add_u64 v[172:173], s[26:27], 0, v[0:1]
	s_mov_b64 s[74:75], 0x100
	s_add_i32 s15, s57, 0x2000
	v_lshl_add_u64 v[140:141], v[172:173], 0, s[74:75]
	s_mov_b32 m0, s57
	v_lshl_add_u64 v[174:175], s[26:27], 0, v[130:131]
	s_add_u32 s72, s26, 0x40100
	ds_read_b128 v[62:65], v139 offset:16384
	ds_read_b128 v[102:105], v139 offset:17408
	ds_read_b128 v[106:109], v139 offset:18432
	ds_read_b128 v[110:113], v139 offset:19456
	ds_read_b128 v[114:117], v139 offset:20480
	ds_read_b128 v[118:121], v139 offset:21504
	ds_read_b128 v[122:125], v139 offset:22528
	ds_read_b128 v[126:129], v139 offset:23552
	global_load_lds_dwordx4 v[140:141], off
	v_lshl_add_u64 v[140:141], v[174:175], 0, s[74:75]
	s_mov_b32 m0, s15
	s_addc_u32 s73, s27, 0
	s_add_i32 s17, s17, s37
	global_load_lds_dwordx4 v[140:141], off
	v_lshl_add_u64 v[140:141], s[72:73], 0, v[0:1]
	s_mov_b32 m0, s17
	s_add_i32 s19, s17, 0x2000
	global_load_lds_dwordx4 v[140:141], off
	v_lshl_add_u64 v[140:141], s[72:73], 0, v[130:131]
	s_mov_b32 m0, s19
	v_lshl_add_u64 v[208:209], s[24:25], 0, v[134:135]
	global_load_lds_dwordx4 v[140:141], off
	v_lshl_add_u64 v[140:141], v[208:209], 0, s[74:75]
	s_mov_b32 m0, s9
	v_lshl_add_u64 v[212:213], s[24:25], 0, v[132:133]
	global_load_lds_dwordx4 v[140:141], off
	v_lshl_add_u64 v[140:141], v[212:213], 0, s[74:75]
	s_mov_b32 m0, s11
	s_nop 0
	global_load_lds_dwordx4 v[140:141], off
	s_waitcnt vmcnt(8) lgkmcnt(0)
	s_barrier
; #define PG8_STAGE(bufoff, gbase, voff) do { _Pragma("unroll") for (int _i = 0; _i < 2; ++_i) \
;         __builtin_amdgcn_global_load_lds((const unsigned*)((const char*)(gbase) + (voff)[_i]), (PG8_LAS unsigned*)(lds + (bufoff) + ldsw + _i * 8192), 16, 0, 0); } while (0)
; #define PG8_LDA(dst, b, h) do { _Pragma("unroll") for (int m = 0; m < 4; ++m) _Pragma("unroll") for (int k = 0; k < 2; ++k) dst[m][k] = *(const PG8_LAS bf16x8*)(lds + PG8_SA(b, h) + aoff + m * 2048 + k * 1024); } while (0)
; #define PG8_LDB(dst, b, h) do { _Pragma("unroll") for (int n = 0; n < 2; ++n) _Pragma("unroll") for (int k = 0; k < 2; ++k) dst[n][k] = *(const PG8_LAS bf16x8*)(lds + PG8_SB(b, h) + boff + n * 2048 + k * 1024); } while (0)
; #define PG8_MMA(ai, bj, At, Bt) do { __builtin_amdgcn_s_setprio(1); _Pragma("unroll") for (int m = 0; m < 4; ++m) _Pragma("unroll") for (int n = 0; n < 2; ++n) _Pragma("unroll") for (int k = 0; k < 2; ++k) \
;         acc[ai][bj][m][n] = __builtin_amdgcn_mfma_f32_16x16x32_bf16(Bt[n][k], At[m][k], acc[ai][bj][m][n], 0, 0, 0); __builtin_amdgcn_s_setprio(0); } while (0)
; #define PG8_WAIT_V(n) asm volatile("s_waitcnt vmcnt(" #n ")" ::: "memory")
; #define PG8_WAIT_L(n) asm volatile("s_waitcnt lgkmcnt(" #n ")" ::: "memory")
; #define PG8_BAR __builtin_amdgcn_s_barrier()
; #define PG8_SCHED __builtin_amdgcn_sched_barrier(0)
; template <class Epi, class Sched, bool ALIGN_EPI = false, bool SP2 = false>
; __device__ __forceinline__ void gemm_phase(PG8_LAS unsigned char* lds, const Gemm g, const Sched& S, const Epi& E, int wave_s) {
;     ...
;             PG8_WAIT_V(8); PG8_WAIT_L(0); PG8_BAR; PG8_MMA(1, 0, At, B0); PG8_MMA(1, 1, At, B1); PG8_BAR; PG8_SCHED;
;             PG8_LDB(B0, 1, 0); PG8_LDB(B1, 1, 1); PG8_SCHED; PG8_LDA(At, 1, 0); PG8_STAGE(PG8_SA(0, 1), a2 + hstep, voffA);
;             PG8_WAIT_V(8); PG8_WAIT_L(0); PG8_BAR; PG8_MMA(0, 0, At, B0); PG8_MMA(0, 1, At, B1); PG8_BAR; PG8_SCHED;
	s_setprio 1
	v_mfma_f32_16x16x32_bf16 v[140:143], v[2:5], v[62:65], 0
	v_mfma_f32_16x16x32_bf16 v[148:151], v[2:5], v[106:109], 0
	v_mfma_f32_16x16x32_bf16 v[156:159], v[2:5], v[114:117], 0
	v_mfma_f32_16x16x32_bf16 v[2:5], v[2:5], v[122:125], 0
	v_mfma_f32_16x16x32_bf16 v[140:143], v[6:9], v[102:105], v[140:143]
	v_mfma_f32_16x16x32_bf16 v[148:151], v[6:9], v[110:113], v[148:151]
	v_mfma_f32_16x16x32_bf16 v[156:159], v[6:9], v[118:121], v[156:159]
	v_mfma_f32_16x16x32_bf16 v[2:5], v[6:9], v[126:129], v[2:5]
	v_mfma_f32_16x16x32_bf16 v[6:9], v[10:13], v[122:125], 0
	v_mfma_f32_16x16x32_bf16 v[144:147], v[10:13], v[62:65], 0
	v_mfma_f32_16x16x32_bf16 v[152:155], v[10:13], v[106:109], 0
	v_mfma_f32_16x16x32_bf16 v[160:163], v[10:13], v[114:117], 0
	v_mfma_f32_16x16x32_bf16 v[6:9], v[14:17], v[126:129], v[6:9]
	v_mfma_f32_16x16x32_bf16 v[144:147], v[14:17], v[102:105], v[144:147]
	v_mfma_f32_16x16x32_bf16 v[152:155], v[14:17], v[110:113], v[152:155]
	v_mfma_f32_16x16x32_bf16 v[160:163], v[14:17], v[118:121], v[160:163]
	s_setprio 0
	s_setprio 1
	v_mfma_f32_16x16x32_bf16 v[10:13], v[18:21], v[62:65], 0
	v_mfma_f32_16x16x32_bf16 v[14:17], v[26:29], v[62:65], 0
	v_mfma_f32_16x16x32_bf16 v[10:13], v[22:25], v[102:105], v[10:13]
	v_mfma_f32_16x16x32_bf16 v[14:17], v[30:33], v[102:105], v[14:17]
	v_mfma_f32_16x16x32_bf16 v[62:65], v[18:21], v[106:109], 0
	v_mfma_f32_16x16x32_bf16 v[102:105], v[26:29], v[106:109], 0
	v_mfma_f32_16x16x32_bf16 v[106:109], v[18:21], v[114:117], 0
	v_mfma_f32_16x16x32_bf16 v[18:21], v[18:21], v[122:125], 0
	v_mfma_f32_16x16x32_bf16 v[62:65], v[22:25], v[110:113], v[62:65]
	v_mfma_f32_16x16x32_bf16 v[102:105], v[30:33], v[110:113], v[102:105]
	v_mfma_f32_16x16x32_bf16 v[106:109], v[22:25], v[118:121], v[106:109]
	v_mfma_f32_16x16x32_bf16 v[110:113], v[26:29], v[114:117], 0
	v_mfma_f32_16x16x32_bf16 v[18:21], v[22:25], v[126:129], v[18:21]
	v_mfma_f32_16x16x32_bf16 v[22:25], v[26:29], v[122:125], 0
	v_mfma_f32_16x16x32_bf16 v[110:113], v[30:33], v[118:121], v[110:113]
	v_mfma_f32_16x16x32_bf16 v[22:25], v[30:33], v[126:129], v[22:25]
	s_setprio 0
	s_barrier
	s_add_i32 s63, 0, 0x18000
	s_add_i32 s70, 0, 0x1c000
	v_add_u32_e32 v230, s63, v136
	v_add_u32_e32 v234, s70, v136
	ds_read_b128 v[26:29], v230
	ds_read_b128 v[30:33], v230 offset:1024
	ds_read_b128 v[114:117], v230 offset:2048
	ds_read_b128 v[118:121], v230 offset:3072
	ds_read_b128 v[122:125], v234
	ds_read_b128 v[126:129], v234 offset:1024
	ds_read_b128 v[164:167], v234 offset:2048
	ds_read_b128 v[168:171], v234 offset:3072
	s_add_u32 s72, s24, 0x40100
	s_addc_u32 s73, s25, 0
	s_mov_b32 m0, s46
	v_lshl_add_u64 v[218:219], s[72:73], 0, v[134:135]
	ds_read_b128 v[178:181], v139 offset:32768
	ds_read_b128 v[182:185], v139 offset:33792
	ds_read_b128 v[186:189], v139 offset:34816
	ds_read_b128 v[190:193], v139 offset:35840
	ds_read_b128 v[194:197], v139 offset:36864
	ds_read_b128 v[198:201], v139 offset:37888
	ds_read_b128 v[202:205], v139 offset:38912
	ds_read_b128 v[214:217], v139 offset:39936
	global_load_lds_dwordx4 v[218:219], off
	v_lshl_add_u64 v[218:219], s[72:73], 0, v[132:133]
	s_mov_b32 m0, s47
	s_nop 0
	global_load_lds_dwordx4 v[218:219], off
	s_waitcnt vmcnt(8) lgkmcnt(0)
	s_barrier
	s_setprio 1
	v_mfma_f32_16x16x32_bf16 v[66:69], v[26:29], v[178:181], v[66:69]
	v_mfma_f32_16x16x32_bf16 v[70:73], v[114:117], v[178:181], v[70:73]
	v_mfma_f32_16x16x32_bf16 v[74:77], v[26:29], v[186:189], v[74:77]
	v_mfma_f32_16x16x32_bf16 v[78:81], v[114:117], v[186:189], v[78:81]
	v_mfma_f32_16x16x32_bf16 v[82:85], v[26:29], v[194:197], v[82:85]
	v_mfma_f32_16x16x32_bf16 v[86:89], v[114:117], v[194:197], v[86:89]
	v_mfma_f32_16x16x32_bf16 v[90:93], v[26:29], v[202:205], v[90:93]
	v_mfma_f32_16x16x32_bf16 v[94:97], v[114:117], v[202:205], v[94:97]
	v_mfma_f32_16x16x32_bf16 v[66:69], v[30:33], v[182:185], v[66:69]
	v_mfma_f32_16x16x32_bf16 v[70:73], v[118:121], v[182:185], v[70:73]
	v_mfma_f32_16x16x32_bf16 v[74:77], v[30:33], v[190:193], v[74:77]
	v_mfma_f32_16x16x32_bf16 v[78:81], v[118:121], v[190:193], v[78:81]
	v_mfma_f32_16x16x32_bf16 v[82:85], v[30:33], v[198:201], v[82:85]
	v_mfma_f32_16x16x32_bf16 v[86:89], v[118:121], v[198:201], v[86:89]
	v_mfma_f32_16x16x32_bf16 v[90:93], v[30:33], v[214:217], v[90:93]
	v_mfma_f32_16x16x32_bf16 v[94:97], v[118:121], v[214:217], v[94:97]
	s_setprio 0
	s_setprio 1
	v_mfma_f32_16x16x32_bf16 v[98:101], v[122:125], v[178:181], v[98:101]
	v_mfma_f32_16x16x32_bf16 v[34:37], v[164:167], v[178:181], v[34:37]
	v_mfma_f32_16x16x32_bf16 v[38:41], v[122:125], v[186:189], v[38:41]
	v_mfma_f32_16x16x32_bf16 v[42:45], v[164:167], v[186:189], v[42:45]
	v_mfma_f32_16x16x32_bf16 v[46:49], v[122:125], v[194:197], v[46:49]
	v_mfma_f32_16x16x32_bf16 v[50:53], v[164:167], v[194:197], v[50:53]
	v_mfma_f32_16x16x32_bf16 v[54:57], v[122:125], v[202:205], v[54:57]
	v_mfma_f32_16x16x32_bf16 v[58:61], v[164:167], v[202:205], v[58:61]
	v_mfma_f32_16x16x32_bf16 v[98:101], v[126:129], v[182:185], v[98:101]
	v_mfma_f32_16x16x32_bf16 v[34:37], v[168:171], v[182:185], v[34:37]
	v_mfma_f32_16x16x32_bf16 v[38:41], v[126:129], v[190:193], v[38:41]
	v_mfma_f32_16x16x32_bf16 v[42:45], v[168:171], v[190:193], v[42:45]
	v_mfma_f32_16x16x32_bf16 v[46:49], v[126:129], v[198:201], v[46:49]
	v_mfma_f32_16x16x32_bf16 v[50:53], v[168:171], v[198:201], v[50:53]
	v_mfma_f32_16x16x32_bf16 v[54:57], v[126:129], v[214:217], v[54:57]
	v_mfma_f32_16x16x32_bf16 v[58:61], v[168:171], v[214:217], v[58:61]
	s_setprio 0
	s_barrier
; #define PG8_STAGE(bufoff, gbase, voff) do { _Pragma("unroll") for (int _i = 0; _i < 2; ++_i) \
;         __builtin_amdgcn_global_load_lds((const unsigned*)((const char*)(gbase) + (voff)[_i]), (PG8_LAS unsigned*)(lds + (bufoff) + ldsw + _i * 8192), 16, 0, 0); } while (0)
; #define PG8_LDA(dst, b, h) do { _Pragma("unroll") for (int m = 0; m < 4; ++m) _Pragma("unroll") for (int k = 0; k < 2; ++k) dst[m][k] = *(const PG8_LAS bf16x8*)(lds + PG8_SA(b, h) + aoff + m * 2048 + k * 1024); } while (0)
; #define PG8_LDB(dst, b, h) do { _Pragma("unroll") for (int n = 0; n < 2; ++n) _Pragma("unroll") for (int k = 0; k < 2; ++k) dst[n][k] = *(const PG8_LAS bf16x8*)(lds + PG8_SB(b, h) + boff + n * 2048 + k * 1024); } while (0)
; #define PG8_MMA(ai, bj, At, Bt) do { __builtin_amdgcn_s_setprio(1); _Pragma("unroll") for (int m = 0; m < 4; ++m) _Pragma("unroll") for (int n = 0; n < 2; ++n) _Pragma("unroll") for (int k = 0; k < 2; ++k) \
;         acc[ai][bj][m][n] = __builtin_amdgcn_mfma_f32_16x16x32_bf16(Bt[n][k], At[m][k], acc[ai][bj][m][n], 0, 0, 0); __builtin_amdgcn_s_setprio(0); } while (0)
; #define PG8_WAIT_V(n) asm volatile("s_waitcnt vmcnt(" #n ")" ::: "memory")
; #define PG8_WAIT_L(n) asm volatile("s_waitcnt lgkmcnt(" #n ")" ::: "memory")
; #define PG8_BAR __builtin_amdgcn_s_barrier()
; #define PG8_SCHED __builtin_amdgcn_sched_barrier(0)
; template <class Epi, class Sched, bool ALIGN_EPI = false, bool SP2 = false>
; __device__ __forceinline__ void gemm_phase(PG8_LAS unsigned char* lds, const Gemm g, const Sched& S, const Epi& E, int wave_s) {
;     ...
;             PG8_LDB(B0, 0, 0); PG8_LDB(B1, 0, 1); PG8_SCHED; PG8_LDA(At, 0, 0); PG8_STAGE(PG8_SA(1, 1), a1 + hstep, voffA);
;             PG8_WAIT_V(8); PG8_WAIT_L(0); PG8_BAR; PG8_MMA(0, 0, At, B0); PG8_MMA(0, 1, At, B1); PG8_BAR; PG8_SCHED;
;             PG8_LDA(At, 0, 1); PG8_STAGE(PG8_SB(0, 0), b2, voffB); PG8_STAGE(PG8_SB(0, 1), b2 + hstep, voffB); PG8_STAGE(PG8_SA(0, 0), a2, voffA);
;     ...
;             PG8_LDA(At, 1, 1); PG8_STAGE(PG8_SB(1, 0), b3, voffB); PG8_STAGE(PG8_SB(1, 1), b3 + hstep, voffB); PG8_STAGE(PG8_SA(1, 0), a3, voffA);
;             PG8_WAIT_V(8); PG8_WAIT_L(0); PG8_BAR; PG8_MMA(1, 0, At, B0); PG8_MMA(1, 1, At, B1); PG8_BAR; PG8_SCHED;
	s_add_i32 s63, s63, s37
	s_mov_b64 s[74:75], 0x180
	s_add_i32 s58, s63, 0x2000
	v_lshl_add_u64 v[172:173], v[172:173], 0, s[74:75]
	s_mov_b32 m0, s63
	s_add_u32 s72, s26, 0x40180
	ds_read_b128 v[178:181], v139 offset:49152
	ds_read_b128 v[182:185], v139 offset:50176
	ds_read_b128 v[186:189], v139 offset:51200
	ds_read_b128 v[190:193], v139 offset:52224
	ds_read_b128 v[194:197], v139 offset:53248
	ds_read_b128 v[198:201], v139 offset:54272
	ds_read_b128 v[202:205], v139 offset:55296
	ds_read_b128 v[214:217], v139 offset:56320
	global_load_lds_dwordx4 v[172:173], off
	v_lshl_add_u64 v[172:173], v[174:175], 0, s[74:75]
	s_mov_b32 m0, s58
	s_addc_u32 s73, s27, 0
	s_add_i32 s26, s70, s37
	global_load_lds_dwordx4 v[172:173], off
	v_lshl_add_u64 v[172:173], s[72:73], 0, v[0:1]
	s_mov_b32 m0, s26
	s_add_i32 s27, s26, 0x2000
	global_load_lds_dwordx4 v[172:173], off
	v_lshl_add_u64 v[172:173], s[72:73], 0, v[130:131]
	s_mov_b32 m0, s27
	s_nop 0
	global_load_lds_dwordx4 v[172:173], off
	v_lshl_add_u64 v[172:173], v[208:209], 0, s[74:75]
	s_mov_b32 m0, s50
	s_nop 0
	global_load_lds_dwordx4 v[172:173], off
	v_lshl_add_u64 v[172:173], v[212:213], 0, s[74:75]
	s_mov_b32 m0, s51
	s_nop 0
	global_load_lds_dwordx4 v[172:173], off
	s_waitcnt vmcnt(8) lgkmcnt(0)
	s_barrier
	s_setprio 1
	v_mfma_f32_16x16x32_bf16 v[2:5], v[26:29], v[202:205], v[2:5]
	v_mfma_f32_16x16x32_bf16 v[6:9], v[114:117], v[202:205], v[6:9]
	v_mfma_f32_16x16x32_bf16 v[140:143], v[26:29], v[178:181], v[140:143]
	v_mfma_f32_16x16x32_bf16 v[144:147], v[114:117], v[178:181], v[144:147]
	v_mfma_f32_16x16x32_bf16 v[148:151], v[26:29], v[186:189], v[148:151]
	v_mfma_f32_16x16x32_bf16 v[152:155], v[114:117], v[186:189], v[152:155]
	v_mfma_f32_16x16x32_bf16 v[156:159], v[26:29], v[194:197], v[156:159]
	v_mfma_f32_16x16x32_bf16 v[160:163], v[114:117], v[194:197], v[160:163]
	v_mfma_f32_16x16x32_bf16 v[2:5], v[30:33], v[214:217], v[2:5]
	v_mfma_f32_16x16x32_bf16 v[6:9], v[118:121], v[214:217], v[6:9]
	v_mfma_f32_16x16x32_bf16 v[140:143], v[30:33], v[182:185], v[140:143]
	v_mfma_f32_16x16x32_bf16 v[144:147], v[118:121], v[182:185], v[144:147]
	v_mfma_f32_16x16x32_bf16 v[148:151], v[30:33], v[190:193], v[148:151]
	v_mfma_f32_16x16x32_bf16 v[152:155], v[118:121], v[190:193], v[152:155]
	v_mfma_f32_16x16x32_bf16 v[156:159], v[30:33], v[198:201], v[156:159]
	v_mfma_f32_16x16x32_bf16 v[160:163], v[118:121], v[198:201], v[160:163]
	s_setprio 0
	s_setprio 1
	v_mfma_f32_16x16x32_bf16 v[10:13], v[122:125], v[178:181], v[10:13]
	v_mfma_f32_16x16x32_bf16 v[14:17], v[164:167], v[178:181], v[14:17]
	v_mfma_f32_16x16x32_bf16 v[26:29], v[122:125], v[186:189], v[62:65]
	v_mfma_f32_16x16x32_bf16 v[30:33], v[164:167], v[186:189], v[102:105]
	v_mfma_f32_16x16x32_bf16 v[62:65], v[122:125], v[194:197], v[106:109]
	v_mfma_f32_16x16x32_bf16 v[102:105], v[164:167], v[194:197], v[110:113]
	v_mfma_f32_16x16x32_bf16 v[18:21], v[122:125], v[202:205], v[18:21]
	v_mfma_f32_16x16x32_bf16 v[22:25], v[164:167], v[202:205], v[22:25]
	v_mfma_f32_16x16x32_bf16 v[10:13], v[126:129], v[182:185], v[10:13]
	v_mfma_f32_16x16x32_bf16 v[14:17], v[168:171], v[182:185], v[14:17]
	v_mfma_f32_16x16x32_bf16 v[26:29], v[126:129], v[190:193], v[26:29]
	v_mfma_f32_16x16x32_bf16 v[30:33], v[168:171], v[190:193], v[30:33]
	v_mfma_f32_16x16x32_bf16 v[62:65], v[126:129], v[198:201], v[62:65]
	v_mfma_f32_16x16x32_bf16 v[102:105], v[168:171], v[198:201], v[102:105]
	v_mfma_f32_16x16x32_bf16 v[18:21], v[126:129], v[214:217], v[18:21]
	v_mfma_f32_16x16x32_bf16 v[22:25], v[168:171], v[214:217], v[22:25]
	s_setprio 0
	s_barrier
	ds_read_b128 v[106:109], v220
	ds_read_b128 v[110:113], v220 offset:1024
	ds_read_b128 v[114:117], v220 offset:2048
	ds_read_b128 v[118:121], v220 offset:3072
	ds_read_b128 v[122:125], v221
	ds_read_b128 v[126:129], v221 offset:1024
	ds_read_b128 v[164:167], v221 offset:2048
	ds_read_b128 v[168:171], v221 offset:3072
	s_add_u32 s24, s24, 0x40180
	s_addc_u32 s25, s25, 0
	s_mov_b32 m0, s62
	v_lshl_add_u64 v[172:173], s[24:25], 0, v[134:135]
	ds_read_b128 v[178:181], v139
	ds_read_b128 v[182:185], v139 offset:1024
	ds_read_b128 v[186:189], v139 offset:2048
	ds_read_b128 v[190:193], v139 offset:3072
	ds_read_b128 v[194:197], v139 offset:4096
	ds_read_b128 v[198:201], v139 offset:5120
	ds_read_b128 v[202:205], v139 offset:6144
	ds_read_b128 v[214:217], v139 offset:7168
	global_load_lds_dwordx4 v[172:173], off
	v_lshl_add_u64 v[172:173], s[24:25], 0, v[132:133]
	s_mov_b32 m0, s7
	s_nop 0
	global_load_lds_dwordx4 v[172:173], off
	s_waitcnt vmcnt(8) lgkmcnt(0)
	s_barrier
; #define PG8_STAGE(bufoff, gbase, voff) do { _Pragma("unroll") for (int _i = 0; _i < 2; ++_i) \
;         __builtin_amdgcn_global_load_lds((const unsigned*)((const char*)(gbase) + (voff)[_i]), (PG8_LAS unsigned*)(lds + (bufoff) + ldsw + _i * 8192), 16, 0, 0); } while (0)
; #define PG8_LDA(dst, b, h) do { _Pragma("unroll") for (int m = 0; m < 4; ++m) _Pragma("unroll") for (int k = 0; k < 2; ++k) dst[m][k] = *(const PG8_LAS bf16x8*)(lds + PG8_SA(b, h) + aoff + m * 2048 + k * 1024); } while (0)
; #define PG8_LDB(dst, b, h) do { _Pragma("unroll") for (int n = 0; n < 2; ++n) _Pragma("unroll") for (int k = 0; k < 2; ++k) dst[n][k] = *(const PG8_LAS bf16x8*)(lds + PG8_SB(b, h) + boff + n * 2048 + k * 1024); } while (0)
; #define PG8_MMA(ai, bj, At, Bt) do { __builtin_amdgcn_s_setprio(1); _Pragma("unroll") for (int m = 0; m < 4; ++m) _Pragma("unroll") for (int n = 0; n < 2; ++n) _Pragma("unroll") for (int k = 0; k < 2; ++k) \
;         acc[ai][bj][m][n] = __builtin_amdgcn_mfma_f32_16x16x32_bf16(Bt[n][k], At[m][k], acc[ai][bj][m][n], 0, 0, 0); __builtin_amdgcn_s_setprio(0); } while (0)
; #define PG8_WAIT_V(n) asm volatile("s_waitcnt vmcnt(" #n ")" ::: "memory")
; #define PG8_WAIT_L(n) asm volatile("s_waitcnt lgkmcnt(" #n ")" ::: "memory")
; #define PG8_BAR __builtin_amdgcn_s_barrier()
; #define PG8_SCHED __builtin_amdgcn_sched_barrier(0)
; template <class Epi, class Sched, bool ALIGN_EPI = false, bool SP2 = false>
; __device__ __forceinline__ void gemm_phase(PG8_LAS unsigned char* lds, const Gemm g, const Sched& S, const Epi& E, int wave_s) {
;     ...
;             PG8_LDB(B0, 0, 0); PG8_LDB(B1, 0, 1); PG8_SCHED; PG8_LDA(At, 0, 0); PG8_STAGE(PG8_SA(1, 1), a1 + hstep, voffA);
;             PG8_WAIT_V(8); PG8_WAIT_L(0); PG8_BAR; PG8_MMA(0, 0, At, B0); PG8_MMA(0, 1, At, B1); PG8_BAR; PG8_SCHED;
;             PG8_LDA(At, 0, 1); PG8_STAGE(PG8_SB(0, 0), b2, voffB); PG8_STAGE(PG8_SB(0, 1), b2 + hstep, voffB); PG8_STAGE(PG8_SA(0, 0), a2, voffA);
;             PG8_WAIT_V(8); PG8_WAIT_L(0); PG8_BAR; PG8_MMA(1, 0, At, B0); PG8_MMA(1, 1, At, B1); PG8_BAR; PG8_SCHED;
;             PG8_LDB(B0, 1, 0); PG8_LDB(B1, 1, 1); PG8_SCHED; PG8_LDA(At, 1, 0); PG8_STAGE(PG8_SA(0, 1), a2 + hstep, voffA);
;             PG8_WAIT_V(8); PG8_WAIT_L(0); PG8_BAR; PG8_MMA(0, 0, At, B0); PG8_MMA(0, 1, At, B1); PG8_BAR; PG8_SCHED;
	s_setprio 1
	v_mfma_f32_16x16x32_bf16 v[66:69], v[106:109], v[178:181], v[66:69]
	v_mfma_f32_16x16x32_bf16 v[70:73], v[114:117], v[178:181], v[70:73]
	v_mfma_f32_16x16x32_bf16 v[74:77], v[106:109], v[186:189], v[74:77]
	v_mfma_f32_16x16x32_bf16 v[78:81], v[114:117], v[186:189], v[78:81]
	v_mfma_f32_16x16x32_bf16 v[82:85], v[106:109], v[194:197], v[82:85]
	v_mfma_f32_16x16x32_bf16 v[86:89], v[114:117], v[194:197], v[86:89]
	v_mfma_f32_16x16x32_bf16 v[90:93], v[106:109], v[202:205], v[90:93]
	v_mfma_f32_16x16x32_bf16 v[94:97], v[114:117], v[202:205], v[94:97]
	v_mfma_f32_16x16x32_bf16 v[66:69], v[110:113], v[182:185], v[66:69]
	v_mfma_f32_16x16x32_bf16 v[70:73], v[118:121], v[182:185], v[70:73]
	v_mfma_f32_16x16x32_bf16 v[74:77], v[110:113], v[190:193], v[74:77]
	v_mfma_f32_16x16x32_bf16 v[78:81], v[118:121], v[190:193], v[78:81]
	v_mfma_f32_16x16x32_bf16 v[82:85], v[110:113], v[198:201], v[82:85]
	v_mfma_f32_16x16x32_bf16 v[86:89], v[118:121], v[198:201], v[86:89]
	v_mfma_f32_16x16x32_bf16 v[90:93], v[110:113], v[214:217], v[90:93]
	v_mfma_f32_16x16x32_bf16 v[94:97], v[118:121], v[214:217], v[94:97]
	s_setprio 0
	s_setprio 1
	v_mfma_f32_16x16x32_bf16 v[34:37], v[164:167], v[178:181], v[34:37]
	v_mfma_f32_16x16x32_bf16 v[98:101], v[122:125], v[178:181], v[98:101]
	v_mfma_f32_16x16x32_bf16 v[178:181], v[168:171], v[182:185], v[34:37]
	v_mfma_f32_16x16x32_bf16 v[34:37], v[122:125], v[186:189], v[38:41]
	v_mfma_f32_16x16x32_bf16 v[98:101], v[126:129], v[182:185], v[98:101]
	v_mfma_f32_16x16x32_bf16 v[182:185], v[126:129], v[190:193], v[34:37]
	v_mfma_f32_16x16x32_bf16 v[34:37], v[164:167], v[186:189], v[42:45]
	v_mfma_f32_16x16x32_bf16 v[42:45], v[168:171], v[190:193], v[34:37]
	v_mfma_f32_16x16x32_bf16 v[34:37], v[122:125], v[194:197], v[46:49]
	v_mfma_f32_16x16x32_bf16 v[46:49], v[126:129], v[198:201], v[34:37]
	v_mfma_f32_16x16x32_bf16 v[34:37], v[164:167], v[194:197], v[50:53]
	v_mfma_f32_16x16x32_bf16 v[50:53], v[168:171], v[198:201], v[34:37]
	v_mfma_f32_16x16x32_bf16 v[34:37], v[122:125], v[202:205], v[54:57]
	v_mfma_f32_16x16x32_bf16 v[54:57], v[126:129], v[214:217], v[34:37]
	v_mfma_f32_16x16x32_bf16 v[34:37], v[164:167], v[202:205], v[58:61]
	v_mfma_f32_16x16x32_bf16 v[186:189], v[168:171], v[214:217], v[34:37]
	s_setprio 0
	s_barrier
	s_mov_b32 m0, s57
	v_lshl_add_u64 v[172:173], s[22:23], 0, v[0:1]
	s_add_u32 s24, s22, 0x40000
	s_nop 1
	ds_read_b128 v[34:37], v139 offset:16384
	ds_read_b128 v[38:41], v139 offset:17408
	ds_read_b128 v[58:61], v139 offset:18432
	ds_read_b128 v[190:193], v139 offset:19456
	ds_read_b128 v[194:197], v139 offset:20480
	ds_read_b128 v[198:201], v139 offset:21504
	ds_read_b128 v[202:205], v139 offset:22528
	ds_read_b128 v[214:217], v139 offset:23552
	global_load_lds_dwordx4 v[172:173], off
	v_lshl_add_u64 v[174:175], s[22:23], 0, v[130:131]
	s_mov_b32 m0, s15
	s_addc_u32 s25, s23, 0
	global_load_lds_dwordx4 v[174:175], off
	v_lshl_add_u64 v[208:209], s[24:25], 0, v[0:1]
	s_mov_b32 m0, s17
	v_lshl_add_u64 v[212:213], s[20:21], 0, v[132:133]
	global_load_lds_dwordx4 v[208:209], off
	v_lshl_add_u64 v[208:209], s[24:25], 0, v[130:131]
	s_mov_b32 m0, s19
	s_nop 0
	global_load_lds_dwordx4 v[208:209], off
	v_lshl_add_u64 v[208:209], s[20:21], 0, v[134:135]
	s_mov_b32 m0, s9
	s_nop 0
	global_load_lds_dwordx4 v[208:209], off
	s_mov_b32 m0, s11
	s_nop 0
	global_load_lds_dwordx4 v[212:213], off
	s_waitcnt vmcnt(8) lgkmcnt(0)
	s_barrier
	s_setprio 1
	v_mfma_f32_16x16x32_bf16 v[140:143], v[106:109], v[34:37], v[140:143]
	v_mfma_f32_16x16x32_bf16 v[148:151], v[106:109], v[58:61], v[148:151]
	v_mfma_f32_16x16x32_bf16 v[156:159], v[106:109], v[194:197], v[156:159]
	v_mfma_f32_16x16x32_bf16 v[2:5], v[106:109], v[202:205], v[2:5]
	v_mfma_f32_16x16x32_bf16 v[140:143], v[110:113], v[38:41], v[140:143]
	v_mfma_f32_16x16x32_bf16 v[148:151], v[110:113], v[190:193], v[148:151]
	v_mfma_f32_16x16x32_bf16 v[156:159], v[110:113], v[198:201], v[156:159]
	v_mfma_f32_16x16x32_bf16 v[110:113], v[110:113], v[214:217], v[2:5]
	v_mfma_f32_16x16x32_bf16 v[2:5], v[114:117], v[202:205], v[6:9]
	v_mfma_f32_16x16x32_bf16 v[144:147], v[114:117], v[34:37], v[144:147]
	v_mfma_f32_16x16x32_bf16 v[152:155], v[114:117], v[58:61], v[152:155]
	v_mfma_f32_16x16x32_bf16 v[160:163], v[114:117], v[194:197], v[160:163]
	v_mfma_f32_16x16x32_bf16 v[114:117], v[118:121], v[214:217], v[2:5]
	v_mfma_f32_16x16x32_bf16 v[144:147], v[118:121], v[38:41], v[144:147]
	v_mfma_f32_16x16x32_bf16 v[152:155], v[118:121], v[190:193], v[152:155]
	v_mfma_f32_16x16x32_bf16 v[160:163], v[118:121], v[198:201], v[160:163]
	s_setprio 0
	s_setprio 1
	v_mfma_f32_16x16x32_bf16 v[2:5], v[122:125], v[34:37], v[10:13]
	v_mfma_f32_16x16x32_bf16 v[118:121], v[126:129], v[38:41], v[2:5]
	v_mfma_f32_16x16x32_bf16 v[2:5], v[164:167], v[34:37], v[14:17]
	v_mfma_f32_16x16x32_bf16 v[218:221], v[168:171], v[38:41], v[2:5]
	v_mfma_f32_16x16x32_bf16 v[2:5], v[122:125], v[58:61], v[26:29]
	v_mfma_f32_16x16x32_bf16 v[222:225], v[126:129], v[190:193], v[2:5]
	v_mfma_f32_16x16x32_bf16 v[2:5], v[164:167], v[58:61], v[30:33]
	v_mfma_f32_16x16x32_bf16 v[190:193], v[168:171], v[190:193], v[2:5]
	v_mfma_f32_16x16x32_bf16 v[2:5], v[122:125], v[194:197], v[62:65]
	v_mfma_f32_16x16x32_bf16 v[226:229], v[126:129], v[198:201], v[2:5]
	v_mfma_f32_16x16x32_bf16 v[2:5], v[164:167], v[194:197], v[102:105]
	v_mfma_f32_16x16x32_bf16 v[194:197], v[168:171], v[198:201], v[2:5]
	v_mfma_f32_16x16x32_bf16 v[2:5], v[122:125], v[202:205], v[18:21]
	v_mfma_f32_16x16x32_bf16 v[198:201], v[126:129], v[214:217], v[2:5]
	v_mfma_f32_16x16x32_bf16 v[2:5], v[164:167], v[202:205], v[22:25]
	v_mfma_f32_16x16x32_bf16 v[164:167], v[168:171], v[214:217], v[2:5]
	s_setprio 0
	s_barrier
; #define PG8_STAGE(bufoff, gbase, voff) do { _Pragma("unroll") for (int _i = 0; _i < 2; ++_i) \
;         __builtin_amdgcn_global_load_lds((const unsigned*)((const char*)(gbase) + (voff)[_i]), (PG8_LAS unsigned*)(lds + (bufoff) + ldsw + _i * 8192), 16, 0, 0); } while (0)
; #define PG8_LDA(dst, b, h) do { _Pragma("unroll") for (int m = 0; m < 4; ++m) _Pragma("unroll") for (int k = 0; k < 2; ++k) dst[m][k] = *(const PG8_LAS bf16x8*)(lds + PG8_SA(b, h) + aoff + m * 2048 + k * 1024); } while (0)
; #define PG8_LDB(dst, b, h) do { _Pragma("unroll") for (int n = 0; n < 2; ++n) _Pragma("unroll") for (int k = 0; k < 2; ++k) dst[n][k] = *(const PG8_LAS bf16x8*)(lds + PG8_SB(b, h) + boff + n * 2048 + k * 1024); } while (0)
; #define PG8_MMA(ai, bj, At, Bt) do { __builtin_amdgcn_s_setprio(1); _Pragma("unroll") for (int m = 0; m < 4; ++m) _Pragma("unroll") for (int n = 0; n < 2; ++n) _Pragma("unroll") for (int k = 0; k < 2; ++k) \
;         acc[ai][bj][m][n] = __builtin_amdgcn_mfma_f32_16x16x32_bf16(Bt[n][k], At[m][k], acc[ai][bj][m][n], 0, 0, 0); __builtin_amdgcn_s_setprio(0); } while (0)
; #define PG8_WAIT_V(n) asm volatile("s_waitcnt vmcnt(" #n ")" ::: "memory")
; #define PG8_WAIT_L(n) asm volatile("s_waitcnt lgkmcnt(" #n ")" ::: "memory")
; #define PG8_BAR __builtin_amdgcn_s_barrier()
; #define PG8_SCHED __builtin_amdgcn_sched_barrier(0)
; template <class Epi, class Sched, bool ALIGN_EPI = false, bool SP2 = false>
; __device__ __forceinline__ void gemm_phase(PG8_LAS unsigned char* lds, const Gemm g, const Sched& S, const Epi& E, int wave_s) {
;     ...
;             PG8_LDB(B0, 1, 0); PG8_LDB(B1, 1, 1); PG8_SCHED; PG8_LDA(At, 1, 0); PG8_STAGE(PG8_SA(0, 1), a2 + hstep, voffA);
;             PG8_WAIT_V(8); PG8_WAIT_L(0); PG8_BAR; PG8_MMA(0, 0, At, B0); PG8_MMA(0, 1, At, B1); PG8_BAR; PG8_SCHED;
;             PG8_LDA(At, 1, 1); PG8_STAGE(PG8_SB(1, 0), b3, voffB); PG8_STAGE(PG8_SB(1, 1), b3 + hstep, voffB); PG8_STAGE(PG8_SA(1, 0), a3, voffA);
;             PG8_WAIT_V(8); PG8_WAIT_L(0); PG8_BAR; PG8_MMA(1, 0, At, B0); PG8_MMA(1, 1, At, B1); PG8_BAR; PG8_SCHED;
;     ...
;         if constexpr (ALIGN_EPI) { if (wr == 0) PG8_BAR; }
;         if constexpr (!Epi::AFTER_DRAIN) { E(acc, cur, wr, wc, fr, fq); S.done(cur); }
;         if (!has_next) break;
	ds_read_b128 v[102:105], v230
	ds_read_b128 v[122:125], v230 offset:1024
	ds_read_b128 v[126:129], v230 offset:2048
	ds_read_b128 v[168:171], v230 offset:3072
	ds_read_b128 v[202:205], v234
	ds_read_b128 v[214:217], v234 offset:1024
	ds_read_b128 v[230:233], v234 offset:2048
	ds_read_b128 v[234:237], v234 offset:3072
	s_add_u32 s24, s20, 0x40000
	s_addc_u32 s25, s21, 0
	s_mov_b32 m0, s46
	v_lshl_add_u64 v[2:3], s[24:25], 0, v[134:135]
	ds_read_b128 v[26:29], v139 offset:32768
	ds_read_b128 v[30:33], v139 offset:33792
	ds_read_b128 v[62:65], v139 offset:34816
	ds_read_b128 v[106:109], v139 offset:35840
	ds_read_b128 v[238:241], v139 offset:36864
	ds_read_b128 v[242:245], v139 offset:37888
	ds_read_b128 v[246:249], v139 offset:38912
	ds_read_b128 v[250:253], v139 offset:39936
	global_load_lds_dwordx4 v[2:3], off
	v_lshl_add_u64 v[2:3], s[24:25], 0, v[132:133]
	s_mov_b32 m0, s47
	s_nop 0
	global_load_lds_dwordx4 v[2:3], off
	s_waitcnt vmcnt(8) lgkmcnt(0)
	s_barrier
	s_setprio 1
	v_mfma_f32_16x16x32_bf16 v[2:5], v[102:105], v[26:29], v[66:69]
	v_mfma_f32_16x16x32_bf16 v[34:37], v[122:125], v[30:33], v[2:5]
	v_mfma_f32_16x16x32_bf16 v[2:5], v[126:129], v[26:29], v[70:73]
	v_mfma_f32_16x16x32_bf16 v[38:41], v[168:171], v[30:33], v[2:5]
	v_mfma_f32_16x16x32_bf16 v[2:5], v[102:105], v[62:65], v[74:77]
	v_mfma_f32_16x16x32_bf16 v[18:21], v[122:125], v[106:109], v[2:5]
	v_mfma_f32_16x16x32_bf16 v[2:5], v[126:129], v[62:65], v[78:81]
	v_mfma_f32_16x16x32_bf16 v[22:25], v[168:171], v[106:109], v[2:5]
	v_mfma_f32_16x16x32_bf16 v[2:5], v[102:105], v[238:241], v[82:85]
	v_mfma_f32_16x16x32_bf16 v[10:13], v[122:125], v[242:245], v[2:5]
	v_mfma_f32_16x16x32_bf16 v[2:5], v[126:129], v[238:241], v[86:89]
	v_mfma_f32_16x16x32_bf16 v[14:17], v[168:171], v[242:245], v[2:5]
	v_mfma_f32_16x16x32_bf16 v[2:5], v[102:105], v[246:249], v[90:93]
	v_mfma_f32_16x16x32_bf16 v[6:9], v[126:129], v[246:249], v[94:97]
	v_mfma_f32_16x16x32_bf16 v[2:5], v[122:125], v[250:253], v[2:5]
	v_mfma_f32_16x16x32_bf16 v[6:9], v[168:171], v[250:253], v[6:9]
	s_setprio 0
	s_setprio 1
	v_mfma_f32_16x16x32_bf16 v[58:61], v[202:205], v[26:29], v[98:101]
	v_mfma_f32_16x16x32_bf16 v[26:29], v[230:233], v[26:29], v[178:181]
	v_mfma_f32_16x16x32_bf16 v[78:81], v[234:237], v[30:33], v[26:29]
	v_mfma_f32_16x16x32_bf16 v[26:29], v[202:205], v[62:65], v[182:185]
	v_mfma_f32_16x16x32_bf16 v[70:73], v[214:217], v[30:33], v[58:61]
	v_mfma_f32_16x16x32_bf16 v[58:61], v[214:217], v[106:109], v[26:29]
	v_mfma_f32_16x16x32_bf16 v[26:29], v[230:233], v[62:65], v[42:45]
	v_mfma_f32_16x16x32_bf16 v[62:65], v[234:237], v[106:109], v[26:29]
	v_mfma_f32_16x16x32_bf16 v[26:29], v[202:205], v[238:241], v[46:49]
	v_mfma_f32_16x16x32_bf16 v[42:45], v[214:217], v[242:245], v[26:29]
	v_mfma_f32_16x16x32_bf16 v[26:29], v[230:233], v[238:241], v[50:53]
	v_mfma_f32_16x16x32_bf16 v[46:49], v[234:237], v[242:245], v[26:29]
	v_mfma_f32_16x16x32_bf16 v[26:29], v[202:205], v[246:249], v[54:57]
	v_mfma_f32_16x16x32_bf16 v[30:33], v[230:233], v[246:249], v[186:189]
	v_mfma_f32_16x16x32_bf16 v[26:29], v[214:217], v[250:253], v[26:29]
	v_mfma_f32_16x16x32_bf16 v[30:33], v[234:237], v[250:253], v[30:33]
	s_setprio 0
	s_barrier
	s_mov_b32 m0, s63
	v_lshl_add_u64 v[50:51], v[172:173], 0, s[60:61]
	s_add_u32 s24, s22, 0x40080
	ds_read_b128 v[82:85], v139 offset:49152
	ds_read_b128 v[90:93], v139 offset:50176
	ds_read_b128 v[178:181], v139 offset:51200
	ds_read_b128 v[182:185], v139 offset:52224
	ds_read_b128 v[186:189], v139 offset:53248
	ds_read_b128 v[238:241], v139 offset:54272
	ds_read_b128 v[242:245], v139 offset:55296
	ds_read_b128 v[246:249], v139 offset:56320
	global_load_lds_dwordx4 v[50:51], off
	v_lshl_add_u64 v[50:51], v[174:175], 0, s[60:61]
	s_mov_b32 m0, s58
	s_addc_u32 s25, s23, 0
	global_load_lds_dwordx4 v[50:51], off
	v_lshl_add_u64 v[50:51], s[24:25], 0, v[0:1]
	s_mov_b32 m0, s26
	s_nop 0
	global_load_lds_dwordx4 v[50:51], off
	v_lshl_add_u64 v[50:51], s[24:25], 0, v[130:131]
	s_mov_b32 m0, s27
	s_nop 0
	global_load_lds_dwordx4 v[50:51], off
	v_lshl_add_u64 v[50:51], v[208:209], 0, s[60:61]
	s_mov_b32 m0, s50
	s_nop 0
	global_load_lds_dwordx4 v[50:51], off
	v_lshl_add_u64 v[50:51], v[212:213], 0, s[60:61]
	s_mov_b32 m0, s51
	s_nop 0
	global_load_lds_dwordx4 v[50:51], off
	s_waitcnt vmcnt(8) lgkmcnt(0)
	s_barrier
	s_setprio 1
	v_mfma_f32_16x16x32_bf16 v[50:53], v[102:105], v[82:85], v[140:143]
	v_mfma_f32_16x16x32_bf16 v[98:101], v[122:125], v[90:93], v[50:53]
	v_mfma_f32_16x16x32_bf16 v[50:53], v[126:129], v[82:85], v[144:147]
	v_mfma_f32_16x16x32_bf16 v[106:109], v[168:171], v[90:93], v[50:53]
	v_mfma_f32_16x16x32_bf16 v[50:53], v[102:105], v[178:181], v[148:151]
	v_mfma_f32_16x16x32_bf16 v[86:89], v[122:125], v[182:185], v[50:53]
	v_mfma_f32_16x16x32_bf16 v[50:53], v[126:129], v[178:181], v[152:155]
	v_mfma_f32_16x16x32_bf16 v[94:97], v[168:171], v[182:185], v[50:53]
	v_mfma_f32_16x16x32_bf16 v[50:53], v[102:105], v[186:189], v[156:159]
	v_mfma_f32_16x16x32_bf16 v[66:69], v[122:125], v[238:241], v[50:53]
	v_mfma_f32_16x16x32_bf16 v[50:53], v[126:129], v[186:189], v[160:163]
	v_mfma_f32_16x16x32_bf16 v[74:77], v[168:171], v[238:241], v[50:53]
	v_mfma_f32_16x16x32_bf16 v[50:53], v[102:105], v[242:245], v[110:113]
	v_mfma_f32_16x16x32_bf16 v[54:57], v[126:129], v[242:245], v[114:117]
	v_mfma_f32_16x16x32_bf16 v[50:53], v[122:125], v[246:249], v[50:53]
	v_mfma_f32_16x16x32_bf16 v[54:57], v[168:171], v[246:249], v[54:57]
	s_setprio 0
	s_setprio 1
	v_mfma_f32_16x16x32_bf16 v[102:105], v[202:205], v[82:85], v[118:121]
	v_mfma_f32_16x16x32_bf16 v[82:85], v[230:233], v[82:85], v[218:221]
	v_mfma_f32_16x16x32_bf16 v[126:129], v[234:237], v[90:93], v[82:85]
	v_mfma_f32_16x16x32_bf16 v[82:85], v[202:205], v[178:181], v[222:225]
	v_mfma_f32_16x16x32_bf16 v[114:117], v[214:217], v[182:185], v[82:85]
	v_mfma_f32_16x16x32_bf16 v[82:85], v[230:233], v[178:181], v[190:193]
	v_mfma_f32_16x16x32_bf16 v[118:121], v[234:237], v[182:185], v[82:85]
	v_mfma_f32_16x16x32_bf16 v[82:85], v[202:205], v[186:189], v[226:229]
	v_mfma_f32_16x16x32_bf16 v[122:125], v[214:217], v[90:93], v[102:105]
	v_mfma_f32_16x16x32_bf16 v[102:105], v[214:217], v[238:241], v[82:85]
	v_mfma_f32_16x16x32_bf16 v[82:85], v[230:233], v[186:189], v[194:197]
	v_mfma_f32_16x16x32_bf16 v[110:113], v[234:237], v[238:241], v[82:85]
	v_mfma_f32_16x16x32_bf16 v[82:85], v[202:205], v[242:245], v[198:201]
	v_mfma_f32_16x16x32_bf16 v[90:93], v[230:233], v[242:245], v[164:167]
	v_mfma_f32_16x16x32_bf16 v[82:85], v[214:217], v[246:249], v[82:85]
	v_mfma_f32_16x16x32_bf16 v[90:93], v[234:237], v[246:249], v[90:93]
	s_setprio 0
	s_barrier
	s_andn2_b64 vcc, exec, s[12:13]
	s_cbranch_vccnz .LBB0_712
	s_barrier

; #define PG8_STAGE(bufoff, gbase, voff) do { _Pragma("unroll") for (int _i = 0; _i < 2; ++_i) \
;         __builtin_amdgcn_global_load_lds((const unsigned*)((const char*)(gbase) + (voff)[_i]), (PG8_LAS unsigned*)(lds + (bufoff) + ldsw + _i * 8192), 16, 0, 0); } while (0)
; #define PG8_LDA(dst, b, h) do { _Pragma("unroll") for (int m = 0; m < 4; ++m) _Pragma("unroll") for (int k = 0; k < 2; ++k) dst[m][k] = *(const PG8_LAS bf16x8*)(lds + PG8_SA(b, h) + aoff + m * 2048 + k * 1024); } while (0)
; #define PG8_LDB(dst, b, h) do { _Pragma("unroll") for (int n = 0; n < 2; ++n) _Pragma("unroll") for (int k = 0; k < 2; ++k) dst[n][k] = *(const PG8_LAS bf16x8*)(lds + PG8_SB(b, h) + boff + n * 2048 + k * 1024); } while (0)
; #define PG8_MMA(ai, bj, At, Bt) do { __builtin_amdgcn_s_setprio(1); _Pragma("unroll") for (int m = 0; m < 4; ++m) _Pragma("unroll") for (int n = 0; n < 2; ++n) _Pragma("unroll") for (int k = 0; k < 2; ++k) \
;         acc[ai][bj][m][n] = __builtin_amdgcn_mfma_f32_16x16x32_bf16(Bt[n][k], At[m][k], acc[ai][bj][m][n], 0, 0, 0); __builtin_amdgcn_s_setprio(0); } while (0)
; #define PG8_WAIT_V(n) asm volatile("s_waitcnt vmcnt(" #n ")" ::: "memory")
; #define PG8_BAR __builtin_amdgcn_s_barrier()
; template <class Epi, class Sched, bool ALIGN_EPI = false, bool SP2 = false>
; __device__ __forceinline__ void gemm_phase(PG8_LAS unsigned char* lds, const Gemm g, const Sched& S, const Epi& E, int wave_s) {
;     ...
;         for (int t = 0; t < nt; t += 2) {
;             const bool last = (t == nt - 2);
;             const char* a1 = cA + (size_t)(t + 1) * kstep;
;             const char* a2 = last ? nA : cA + (size_t)(t + 2) * kstep; const char* b2 = last ? nB : cB + (size_t)(t + 2) * kstep;
;             const char* a3 = a2 + kstep; const char* b3 = b2 + kstep;
;             if (last && has_next) S.a_ready(nxt);
;             if constexpr (SP2) {
;             PG8_LDB(B0, 0, 0); PG8_LDB(B1, 0, 1); PG8_SCHED; PG8_LDA(At, 0, 0); PG8_STAGE(PG8_SA(1, 1), a1 + hstep, voffA);
;             PG8_WAIT_V(8); PG8_WAIT_L(0); PG8_BAR; PG8_MMA(0, 0, At, B0); PG8_MMA(0, 1, At, B1); PG8_BAR; PG8_SCHED;
;             PG8_LDA(At, 0, 1); PG8_STAGE(PG8_SB(0, 0), b2, voffB); PG8_STAGE(PG8_SB(0, 1), b2 + hstep, voffB); PG8_STAGE(PG8_SA(0, 0), a2, voffA);
;             PG8_WAIT_V(8); PG8_WAIT_L(0); PG8_BAR; PG8_MMA(1, 0, At, B0); PG8_MMA(1, 1, At, B1); PG8_BAR; PG8_SCHED;
.LBB0_1008:
	s_add_u32 s26, s24, 0xfffc0080
	s_addc_u32 s27, s25, -1
	s_add_i32 s79, 0, 0x10000
	s_cmp_eq_u32 s78, 12
	s_cselect_b32 s29, s13, s27
	s_cselect_b32 s28, s74, s26
	v_add_u32_e32 v140, s79, v143
	s_cselect_b32 s27, s11, s77
	s_cselect_b32 s26, s75, s76
	s_add_i32 s82, 0, 0x14000
	ds_read_b128 v[146:149], v140
	ds_read_b128 v[150:153], v140 offset:1024
	ds_read_b128 v[154:157], v140 offset:2048
	ds_read_b128 v[158:161], v140 offset:3072
	v_add_u32_e32 v140, s82, v143
	ds_read_b128 v[162:165], v140
	ds_read_b128 v[166:169], v140 offset:1024
	ds_read_b128 v[170:173], v140 offset:2048
	ds_read_b128 v[178:181], v140 offset:3072
	v_lshl_add_u64 v[140:141], s[24:25], 0, v[136:137]
	s_add_i32 m0, s21, 0xc000
	ds_read_b128 v[182:185], v145
	ds_read_b128 v[186:189], v145 offset:1024
	ds_read_b128 v[190:193], v145 offset:2048
	ds_read_b128 v[194:197], v145 offset:3072
	ds_read_b128 v[198:201], v145 offset:4096
	ds_read_b128 v[202:205], v145 offset:5120
	ds_read_b128 v[214:217], v145 offset:6144
	ds_read_b128 v[218:221], v145 offset:7168
	global_load_lds_dwordx4 v[140:141], off
	v_lshl_add_u64 v[140:141], s[24:25], 0, v[138:139]
	s_add_i32 m0, s21, 0xe000
	s_nop 0
	global_load_lds_dwordx4 v[140:141], off
	s_waitcnt vmcnt(8) lgkmcnt(0)
	s_barrier
	s_setprio 1
	v_mfma_f32_16x16x32_bf16 v[126:129], v[146:149], v[182:185], v[126:129]
	v_mfma_f32_16x16x32_bf16 v[122:125], v[154:157], v[182:185], v[122:125]
	v_mfma_f32_16x16x32_bf16 v[110:113], v[146:149], v[190:193], v[110:113]
	v_mfma_f32_16x16x32_bf16 v[106:109], v[154:157], v[190:193], v[106:109]
	v_mfma_f32_16x16x32_bf16 v[94:97], v[146:149], v[198:201], v[94:97]
	v_mfma_f32_16x16x32_bf16 v[90:93], v[154:157], v[198:201], v[90:93]
	v_mfma_f32_16x16x32_bf16 v[78:81], v[146:149], v[214:217], v[78:81]
	v_mfma_f32_16x16x32_bf16 v[74:77], v[154:157], v[214:217], v[74:77]
	v_mfma_f32_16x16x32_bf16 v[126:129], v[150:153], v[186:189], v[126:129]
	v_mfma_f32_16x16x32_bf16 v[122:125], v[158:161], v[186:189], v[122:125]
	v_mfma_f32_16x16x32_bf16 v[110:113], v[150:153], v[194:197], v[110:113]
	v_mfma_f32_16x16x32_bf16 v[106:109], v[158:161], v[194:197], v[106:109]
	v_mfma_f32_16x16x32_bf16 v[94:97], v[150:153], v[202:205], v[94:97]
	v_mfma_f32_16x16x32_bf16 v[90:93], v[158:161], v[202:205], v[90:93]
	v_mfma_f32_16x16x32_bf16 v[78:81], v[150:153], v[218:221], v[78:81]
	v_mfma_f32_16x16x32_bf16 v[74:77], v[158:161], v[218:221], v[74:77]
	s_setprio 0
	s_setprio 1
	v_mfma_f32_16x16x32_bf16 v[118:121], v[162:165], v[182:185], v[118:121]
	v_mfma_f32_16x16x32_bf16 v[114:117], v[170:173], v[182:185], v[114:117]
	v_mfma_f32_16x16x32_bf16 v[102:105], v[162:165], v[190:193], v[102:105]
	v_mfma_f32_16x16x32_bf16 v[98:101], v[170:173], v[190:193], v[98:101]
	v_mfma_f32_16x16x32_bf16 v[86:89], v[162:165], v[198:201], v[86:89]
	v_mfma_f32_16x16x32_bf16 v[82:85], v[170:173], v[198:201], v[82:85]
	v_mfma_f32_16x16x32_bf16 v[70:73], v[162:165], v[214:217], v[70:73]
	v_mfma_f32_16x16x32_bf16 v[66:69], v[170:173], v[214:217], v[66:69]
	v_mfma_f32_16x16x32_bf16 v[118:121], v[166:169], v[186:189], v[118:121]
	v_mfma_f32_16x16x32_bf16 v[114:117], v[178:181], v[186:189], v[114:117]
	v_mfma_f32_16x16x32_bf16 v[102:105], v[166:169], v[194:197], v[102:105]
	v_mfma_f32_16x16x32_bf16 v[98:101], v[178:181], v[194:197], v[98:101]
	v_mfma_f32_16x16x32_bf16 v[86:89], v[166:169], v[202:205], v[86:89]
	v_mfma_f32_16x16x32_bf16 v[82:85], v[178:181], v[202:205], v[82:85]
	v_mfma_f32_16x16x32_bf16 v[70:73], v[166:169], v[218:221], v[70:73]
	v_mfma_f32_16x16x32_bf16 v[66:69], v[178:181], v[218:221], v[66:69]
	s_setprio 0
	s_barrier
	s_add_i32 s79, s79, s51
	v_lshl_add_u64 v[140:141], s[26:27], 0, v[0:1]
	s_mov_b32 m0, s79
	ds_read_b128 v[182:185], v145 offset:16384
	ds_read_b128 v[186:189], v145 offset:17408
	ds_read_b128 v[190:193], v145 offset:18432
	ds_read_b128 v[194:197], v145 offset:19456
	ds_read_b128 v[198:201], v145 offset:20480
	ds_read_b128 v[202:205], v145 offset:21504
	ds_read_b128 v[214:217], v145 offset:22528
	ds_read_b128 v[218:221], v145 offset:23552
	global_load_lds_dwordx4 v[140:141], off
	s_add_i32 m0, s79, 0x2000
	s_add_u32 s80, s26, 0x40000
	v_lshl_add_u64 v[174:175], s[26:27], 0, v[130:131]
	s_addc_u32 s81, s27, 0
	s_add_i32 s79, s82, s51
	global_load_lds_dwordx4 v[174:175], off
	v_lshl_add_u64 v[208:209], s[80:81], 0, v[0:1]
	s_mov_b32 m0, s79
	v_lshl_add_u64 v[212:213], s[28:29], 0, v[132:133]
	global_load_lds_dwordx4 v[208:209], off
	v_lshl_add_u64 v[208:209], s[80:81], 0, v[130:131]
	s_add_i32 m0, s79, 0x2000
	s_nop 0
	global_load_lds_dwordx4 v[208:209], off
	v_lshl_add_u64 v[208:209], s[28:29], 0, v[134:135]
	s_mov_b32 m0, s21
	s_nop 0
	global_load_lds_dwordx4 v[208:209], off
	s_mov_b32 m0, s23
	s_nop 0
	global_load_lds_dwordx4 v[212:213], off
	s_waitcnt vmcnt(8) lgkmcnt(0)
	s_barrier
; #define PG8_STAGE(bufoff, gbase, voff) do { _Pragma("unroll") for (int _i = 0; _i < 2; ++_i) \
;         __builtin_amdgcn_global_load_lds((const unsigned*)((const char*)(gbase) + (voff)[_i]), (PG8_LAS unsigned*)(lds + (bufoff) + ldsw + _i * 8192), 16, 0, 0); } while (0)
; #define PG8_LDA(dst, b, h) do { _Pragma("unroll") for (int m = 0; m < 4; ++m) _Pragma("unroll") for (int k = 0; k < 2; ++k) dst[m][k] = *(const PG8_LAS bf16x8*)(lds + PG8_SA(b, h) + aoff + m * 2048 + k * 1024); } while (0)
; #define PG8_LDB(dst, b, h) do { _Pragma("unroll") for (int n = 0; n < 2; ++n) _Pragma("unroll") for (int k = 0; k < 2; ++k) dst[n][k] = *(const PG8_LAS bf16x8*)(lds + PG8_SB(b, h) + boff + n * 2048 + k * 1024); } while (0)
; #define PG8_MMA(ai, bj, At, Bt) do { __builtin_amdgcn_s_setprio(1); _Pragma("unroll") for (int m = 0; m < 4; ++m) _Pragma("unroll") for (int n = 0; n < 2; ++n) _Pragma("unroll") for (int k = 0; k < 2; ++k) \
;         acc[ai][bj][m][n] = __builtin_amdgcn_mfma_f32_16x16x32_bf16(Bt[n][k], At[m][k], acc[ai][bj][m][n], 0, 0, 0); __builtin_amdgcn_s_setprio(0); } while (0)
; #define PG8_WAIT_V(n) asm volatile("s_waitcnt vmcnt(" #n ")" ::: "memory")
; #define PG8_WAIT_L(n) asm volatile("s_waitcnt lgkmcnt(" #n ")" ::: "memory")
; #define PG8_BAR __builtin_amdgcn_s_barrier()
; #define PG8_SCHED __builtin_amdgcn_sched_barrier(0)
; template <class Epi, class Sched, bool ALIGN_EPI = false, bool SP2 = false>
; __device__ __forceinline__ void gemm_phase(PG8_LAS unsigned char* lds, const Gemm g, const Sched& S, const Epi& E, int wave_s) {
;     ...
;             PG8_WAIT_V(8); PG8_WAIT_L(0); PG8_BAR; PG8_MMA(1, 0, At, B0); PG8_MMA(1, 1, At, B1); PG8_BAR; PG8_SCHED;
;             PG8_LDB(B0, 1, 0); PG8_LDB(B1, 1, 1); PG8_SCHED; PG8_LDA(At, 1, 0); PG8_STAGE(PG8_SA(0, 1), a2 + hstep, voffA);
;             PG8_WAIT_V(8); PG8_WAIT_L(0); PG8_BAR; PG8_MMA(0, 0, At, B0); PG8_MMA(0, 1, At, B1); PG8_BAR; PG8_SCHED;
	s_setprio 1
	v_mfma_f32_16x16x32_bf16 v[62:65], v[146:149], v[182:185], v[62:65]
	v_mfma_f32_16x16x32_bf16 v[58:61], v[154:157], v[182:185], v[58:61]
	v_mfma_f32_16x16x32_bf16 v[46:49], v[146:149], v[190:193], v[46:49]
	v_mfma_f32_16x16x32_bf16 v[42:45], v[154:157], v[190:193], v[42:45]
	v_mfma_f32_16x16x32_bf16 v[30:33], v[146:149], v[198:201], v[30:33]
	v_mfma_f32_16x16x32_bf16 v[26:29], v[154:157], v[198:201], v[26:29]
	v_mfma_f32_16x16x32_bf16 v[14:17], v[146:149], v[214:217], v[14:17]
	v_mfma_f32_16x16x32_bf16 v[10:13], v[154:157], v[214:217], v[10:13]
	v_mfma_f32_16x16x32_bf16 v[62:65], v[150:153], v[186:189], v[62:65]
	v_mfma_f32_16x16x32_bf16 v[58:61], v[158:161], v[186:189], v[58:61]
	v_mfma_f32_16x16x32_bf16 v[46:49], v[150:153], v[194:197], v[46:49]
	v_mfma_f32_16x16x32_bf16 v[42:45], v[158:161], v[194:197], v[42:45]
	v_mfma_f32_16x16x32_bf16 v[30:33], v[150:153], v[202:205], v[30:33]
	v_mfma_f32_16x16x32_bf16 v[26:29], v[158:161], v[202:205], v[26:29]
	v_mfma_f32_16x16x32_bf16 v[14:17], v[150:153], v[218:221], v[14:17]
	v_mfma_f32_16x16x32_bf16 v[10:13], v[158:161], v[218:221], v[10:13]
	s_setprio 0
	s_setprio 1
	v_mfma_f32_16x16x32_bf16 v[54:57], v[162:165], v[182:185], v[54:57]
	v_mfma_f32_16x16x32_bf16 v[50:53], v[170:173], v[182:185], v[50:53]
	v_mfma_f32_16x16x32_bf16 v[38:41], v[162:165], v[190:193], v[38:41]
	v_mfma_f32_16x16x32_bf16 v[34:37], v[170:173], v[190:193], v[34:37]
	v_mfma_f32_16x16x32_bf16 v[22:25], v[162:165], v[198:201], v[22:25]
	v_mfma_f32_16x16x32_bf16 v[18:21], v[170:173], v[198:201], v[18:21]
	v_mfma_f32_16x16x32_bf16 v[6:9], v[162:165], v[214:217], v[6:9]
	v_mfma_f32_16x16x32_bf16 v[2:5], v[170:173], v[214:217], v[2:5]
	v_mfma_f32_16x16x32_bf16 v[54:57], v[166:169], v[186:189], v[54:57]
	v_mfma_f32_16x16x32_bf16 v[50:53], v[178:181], v[186:189], v[50:53]
	v_mfma_f32_16x16x32_bf16 v[38:41], v[166:169], v[194:197], v[38:41]
	v_mfma_f32_16x16x32_bf16 v[34:37], v[178:181], v[194:197], v[34:37]
	v_mfma_f32_16x16x32_bf16 v[22:25], v[166:169], v[202:205], v[22:25]
	v_mfma_f32_16x16x32_bf16 v[18:21], v[178:181], v[202:205], v[18:21]
	v_mfma_f32_16x16x32_bf16 v[6:9], v[166:169], v[218:221], v[6:9]
	v_mfma_f32_16x16x32_bf16 v[2:5], v[178:181], v[218:221], v[2:5]
	s_setprio 0
	s_barrier
	s_add_i32 s79, 0, 0x18000
	s_add_i32 s80, 0, 0x1c000
	v_add_u32_e32 v158, s79, v143
	v_add_u32_e32 v178, s80, v143
	ds_read_b128 v[146:149], v158
	ds_read_b128 v[150:153], v158 offset:1024
	ds_read_b128 v[154:157], v158 offset:2048
	ds_read_b128 v[158:161], v158 offset:3072
	ds_read_b128 v[162:165], v178
	ds_read_b128 v[166:169], v178 offset:1024
	ds_read_b128 v[170:173], v178 offset:2048
	ds_read_b128 v[178:181], v178 offset:3072
	s_add_u32 s28, s28, 0x40000
	s_addc_u32 s29, s29, 0
	s_mov_b32 m0, s57
	v_lshl_add_u64 v[222:223], s[28:29], 0, v[134:135]
	ds_read_b128 v[182:185], v145 offset:32768
	ds_read_b128 v[186:189], v145 offset:33792
	ds_read_b128 v[190:193], v145 offset:34816
	ds_read_b128 v[194:197], v145 offset:35840
	ds_read_b128 v[198:201], v145 offset:36864
	ds_read_b128 v[202:205], v145 offset:37888
	ds_read_b128 v[214:217], v145 offset:38912
	ds_read_b128 v[218:221], v145 offset:39936
	global_load_lds_dwordx4 v[222:223], off
	v_lshl_add_u64 v[222:223], s[28:29], 0, v[132:133]
	s_mov_b32 m0, s58
	s_nop 0
	global_load_lds_dwordx4 v[222:223], off
	s_waitcnt vmcnt(8) lgkmcnt(0)
	s_barrier
	s_setprio 1
	v_mfma_f32_16x16x32_bf16 v[126:129], v[146:149], v[182:185], v[126:129]
	v_mfma_f32_16x16x32_bf16 v[122:125], v[154:157], v[182:185], v[122:125]
	v_mfma_f32_16x16x32_bf16 v[110:113], v[146:149], v[190:193], v[110:113]
	v_mfma_f32_16x16x32_bf16 v[106:109], v[154:157], v[190:193], v[106:109]
	v_mfma_f32_16x16x32_bf16 v[94:97], v[146:149], v[198:201], v[94:97]
	v_mfma_f32_16x16x32_bf16 v[90:93], v[154:157], v[198:201], v[90:93]
	v_mfma_f32_16x16x32_bf16 v[78:81], v[146:149], v[214:217], v[78:81]
	v_mfma_f32_16x16x32_bf16 v[74:77], v[154:157], v[214:217], v[74:77]
	v_mfma_f32_16x16x32_bf16 v[126:129], v[150:153], v[186:189], v[126:129]
	v_mfma_f32_16x16x32_bf16 v[122:125], v[158:161], v[186:189], v[122:125]
	v_mfma_f32_16x16x32_bf16 v[110:113], v[150:153], v[194:197], v[110:113]
	v_mfma_f32_16x16x32_bf16 v[106:109], v[158:161], v[194:197], v[106:109]
	v_mfma_f32_16x16x32_bf16 v[94:97], v[150:153], v[202:205], v[94:97]
	v_mfma_f32_16x16x32_bf16 v[90:93], v[158:161], v[202:205], v[90:93]
	v_mfma_f32_16x16x32_bf16 v[78:81], v[150:153], v[218:221], v[78:81]
	v_mfma_f32_16x16x32_bf16 v[74:77], v[158:161], v[218:221], v[74:77]
	s_setprio 0
	s_setprio 1
	v_mfma_f32_16x16x32_bf16 v[118:121], v[162:165], v[182:185], v[118:121]
	v_mfma_f32_16x16x32_bf16 v[114:117], v[170:173], v[182:185], v[114:117]
	v_mfma_f32_16x16x32_bf16 v[102:105], v[162:165], v[190:193], v[102:105]
	v_mfma_f32_16x16x32_bf16 v[98:101], v[170:173], v[190:193], v[98:101]
	v_mfma_f32_16x16x32_bf16 v[86:89], v[162:165], v[198:201], v[86:89]
	v_mfma_f32_16x16x32_bf16 v[82:85], v[170:173], v[198:201], v[82:85]
	v_mfma_f32_16x16x32_bf16 v[70:73], v[162:165], v[214:217], v[70:73]
	v_mfma_f32_16x16x32_bf16 v[66:69], v[170:173], v[214:217], v[66:69]
	v_mfma_f32_16x16x32_bf16 v[118:121], v[166:169], v[186:189], v[118:121]
	v_mfma_f32_16x16x32_bf16 v[114:117], v[178:181], v[186:189], v[114:117]
	v_mfma_f32_16x16x32_bf16 v[102:105], v[166:169], v[194:197], v[102:105]
	v_mfma_f32_16x16x32_bf16 v[98:101], v[178:181], v[194:197], v[98:101]
	v_mfma_f32_16x16x32_bf16 v[86:89], v[166:169], v[202:205], v[86:89]
	v_mfma_f32_16x16x32_bf16 v[82:85], v[178:181], v[202:205], v[82:85]
	v_mfma_f32_16x16x32_bf16 v[70:73], v[166:169], v[218:221], v[70:73]
	v_mfma_f32_16x16x32_bf16 v[66:69], v[178:181], v[218:221], v[66:69]
	s_setprio 0
	s_barrier
; #define PG8_STAGE(bufoff, gbase, voff) do { _Pragma("unroll") for (int _i = 0; _i < 2; ++_i) \
;         __builtin_amdgcn_global_load_lds((const unsigned*)((const char*)(gbase) + (voff)[_i]), (PG8_LAS unsigned*)(lds + (bufoff) + ldsw + _i * 8192), 16, 0, 0); } while (0)
; #define PG8_LDA(dst, b, h) do { _Pragma("unroll") for (int m = 0; m < 4; ++m) _Pragma("unroll") for (int k = 0; k < 2; ++k) dst[m][k] = *(const PG8_LAS bf16x8*)(lds + PG8_SA(b, h) + aoff + m * 2048 + k * 1024); } while (0)
; #define PG8_MMA(ai, bj, At, Bt) do { __builtin_amdgcn_s_setprio(1); _Pragma("unroll") for (int m = 0; m < 4; ++m) _Pragma("unroll") for (int n = 0; n < 2; ++n) _Pragma("unroll") for (int k = 0; k < 2; ++k) \
;         acc[ai][bj][m][n] = __builtin_amdgcn_mfma_f32_16x16x32_bf16(Bt[n][k], At[m][k], acc[ai][bj][m][n], 0, 0, 0); __builtin_amdgcn_s_setprio(0); } while (0)
; #define PG8_WAIT_V(n) asm volatile("s_waitcnt vmcnt(" #n ")" ::: "memory")
; #define PG8_WAIT_L(n) asm volatile("s_waitcnt lgkmcnt(" #n ")" ::: "memory")
; #define PG8_BAR __builtin_amdgcn_s_barrier()
; #define PG8_SCHED __builtin_amdgcn_sched_barrier(0)
; template <class Epi, class Sched, bool ALIGN_EPI = false, bool SP2 = false>
; __device__ __forceinline__ void gemm_phase(PG8_LAS unsigned char* lds, const Gemm g, const Sched& S, const Epi& E, int wave_s) {
;     ...
;         for (int t = 0; t < nt; t += 2) {
;     ...
;             PG8_LDA(At, 1, 1); PG8_STAGE(PG8_SB(1, 0), b3, voffB); PG8_STAGE(PG8_SB(1, 1), b3 + hstep, voffB); PG8_STAGE(PG8_SA(1, 0), a3, voffA);
;             PG8_WAIT_V(8); PG8_WAIT_L(0); PG8_BAR; PG8_MMA(1, 0, At, B0); PG8_MMA(1, 1, At, B1); PG8_BAR; PG8_SCHED;
	s_add_i32 s28, s79, s51
	v_lshl_add_u64 v[140:141], v[140:141], 0, s[60:61]
	s_mov_b32 m0, s28
	ds_read_b128 v[182:185], v145 offset:49152
	ds_read_b128 v[186:189], v145 offset:50176
	ds_read_b128 v[190:193], v145 offset:51200
	ds_read_b128 v[194:197], v145 offset:52224
	ds_read_b128 v[198:201], v145 offset:53248
	ds_read_b128 v[202:205], v145 offset:54272
	ds_read_b128 v[214:217], v145 offset:55296
	ds_read_b128 v[218:221], v145 offset:56320
	global_load_lds_dwordx4 v[140:141], off
	s_add_i32 m0, s28, 0x2000
	s_add_u32 s26, s26, 0x40080
	v_lshl_add_u64 v[140:141], v[174:175], 0, s[60:61]
	s_addc_u32 s27, s27, 0
	s_add_i32 s28, s80, s51
	global_load_lds_dwordx4 v[140:141], off
	v_lshl_add_u64 v[140:141], s[26:27], 0, v[0:1]
	s_mov_b32 m0, s28
	s_nop 0
	global_load_lds_dwordx4 v[140:141], off
	v_lshl_add_u64 v[140:141], s[26:27], 0, v[130:131]
	s_add_i32 m0, s28, 0x2000
	s_nop 0
	global_load_lds_dwordx4 v[140:141], off
	v_lshl_add_u64 v[140:141], v[208:209], 0, s[60:61]
	s_mov_b32 m0, s62
	s_nop 0
	global_load_lds_dwordx4 v[140:141], off
	v_lshl_add_u64 v[140:141], v[212:213], 0, s[60:61]
	s_mov_b32 m0, s63
	s_nop 0
	global_load_lds_dwordx4 v[140:141], off
	s_waitcnt vmcnt(8) lgkmcnt(0)
	s_barrier
	s_setprio 1
	v_mfma_f32_16x16x32_bf16 v[62:65], v[146:149], v[182:185], v[62:65]
	v_mfma_f32_16x16x32_bf16 v[58:61], v[154:157], v[182:185], v[58:61]
	v_mfma_f32_16x16x32_bf16 v[46:49], v[146:149], v[190:193], v[46:49]
	v_mfma_f32_16x16x32_bf16 v[42:45], v[154:157], v[190:193], v[42:45]
	v_mfma_f32_16x16x32_bf16 v[30:33], v[146:149], v[198:201], v[30:33]
	v_mfma_f32_16x16x32_bf16 v[26:29], v[154:157], v[198:201], v[26:29]
	v_mfma_f32_16x16x32_bf16 v[14:17], v[146:149], v[214:217], v[14:17]
	v_mfma_f32_16x16x32_bf16 v[10:13], v[154:157], v[214:217], v[10:13]
	v_mfma_f32_16x16x32_bf16 v[62:65], v[150:153], v[186:189], v[62:65]
	v_mfma_f32_16x16x32_bf16 v[58:61], v[158:161], v[186:189], v[58:61]
	v_mfma_f32_16x16x32_bf16 v[46:49], v[150:153], v[194:197], v[46:49]
	v_mfma_f32_16x16x32_bf16 v[42:45], v[158:161], v[194:197], v[42:45]
	v_mfma_f32_16x16x32_bf16 v[30:33], v[150:153], v[202:205], v[30:33]
	v_mfma_f32_16x16x32_bf16 v[26:29], v[158:161], v[202:205], v[26:29]
	v_mfma_f32_16x16x32_bf16 v[14:17], v[150:153], v[218:221], v[14:17]
	v_mfma_f32_16x16x32_bf16 v[10:13], v[158:161], v[218:221], v[10:13]
	s_setprio 0
	s_setprio 1
	v_mfma_f32_16x16x32_bf16 v[54:57], v[162:165], v[182:185], v[54:57]
	v_mfma_f32_16x16x32_bf16 v[50:53], v[170:173], v[182:185], v[50:53]
	v_mfma_f32_16x16x32_bf16 v[38:41], v[162:165], v[190:193], v[38:41]
	v_mfma_f32_16x16x32_bf16 v[34:37], v[170:173], v[190:193], v[34:37]
	v_mfma_f32_16x16x32_bf16 v[22:25], v[162:165], v[198:201], v[22:25]
	v_mfma_f32_16x16x32_bf16 v[18:21], v[170:173], v[198:201], v[18:21]
	v_mfma_f32_16x16x32_bf16 v[6:9], v[162:165], v[214:217], v[6:9]
	v_mfma_f32_16x16x32_bf16 v[2:5], v[170:173], v[214:217], v[2:5]
	v_mfma_f32_16x16x32_bf16 v[54:57], v[166:169], v[186:189], v[54:57]
	v_mfma_f32_16x16x32_bf16 v[50:53], v[178:181], v[186:189], v[50:53]
	v_mfma_f32_16x16x32_bf16 v[38:41], v[166:169], v[194:197], v[38:41]
	v_mfma_f32_16x16x32_bf16 v[34:37], v[178:181], v[194:197], v[34:37]
	v_mfma_f32_16x16x32_bf16 v[22:25], v[166:169], v[202:205], v[22:25]
	v_mfma_f32_16x16x32_bf16 v[18:21], v[178:181], v[202:205], v[18:21]
	v_mfma_f32_16x16x32_bf16 v[6:9], v[166:169], v[218:221], v[6:9]
	v_mfma_f32_16x16x32_bf16 v[2:5], v[178:181], v[218:221], v[2:5]
	s_setprio 0
	s_barrier
	s_add_i32 s78, s78, 2
	s_add_u32 s24, s24, 0x100
	s_addc_u32 s25, s25, 0
	s_add_u32 s76, s76, 0x100
	s_addc_u32 s77, s77, 0
	s_cmp_gt_u32 s78, 13
	s_cbranch_scc0 .LBB0_1008
	s_and_b64 vcc, exec, s[8:9]
	s_cbranch_vccz .LBB0_1011
	s_barrier

; #define PG8_STAGE(bufoff, gbase, voff) do { _Pragma("unroll") for (int _i = 0; _i < 2; ++_i) \
;         __builtin_amdgcn_global_load_lds((const unsigned*)((const char*)(gbase) + (voff)[_i]), (PG8_LAS unsigned*)(lds + (bufoff) + ldsw + _i * 8192), 16, 0, 0); } while (0)
; #define PG8_LDA(dst, b, h) do { _Pragma("unroll") for (int m = 0; m < 4; ++m) _Pragma("unroll") for (int k = 0; k < 2; ++k) dst[m][k] = *(const PG8_LAS bf16x8*)(lds + PG8_SA(b, h) + aoff + m * 2048 + k * 1024); } while (0)
; #define PG8_LDB(dst, b, h) do { _Pragma("unroll") for (int n = 0; n < 2; ++n) _Pragma("unroll") for (int k = 0; k < 2; ++k) dst[n][k] = *(const PG8_LAS bf16x8*)(lds + PG8_SB(b, h) + boff + n * 2048 + k * 1024); } while (0)
; #define PG8_WAIT_V(n) asm volatile("s_waitcnt vmcnt(" #n ")" ::: "memory")
; #define PG8_WAIT_L(n) asm volatile("s_waitcnt lgkmcnt(" #n ")" ::: "memory")
; #define PG8_BAR __builtin_amdgcn_s_barrier()
; #define PG8_SCHED __builtin_amdgcn_sched_barrier(0)
; template <class Epi, class Sched, bool ALIGN_EPI = false, bool SP2 = false>
; __device__ __forceinline__ void gemm_phase(PG8_LAS unsigned char* lds, const Gemm g, const Sched& S, const Epi& E, int wave_s) {
;     ...
;         for (int t = 0; t < nt; t += 2) {
;             const bool last = (t == nt - 2);
;             const char* a1 = cA + (size_t)(t + 1) * kstep;
;             const char* a2 = last ? nA : cA + (size_t)(t + 2) * kstep; const char* b2 = last ? nB : cB + (size_t)(t + 2) * kstep;
;             const char* a3 = a2 + kstep; const char* b3 = b2 + kstep;
;             if (last && has_next) S.a_ready(nxt);
;             if constexpr (SP2) {
;             PG8_LDB(B0, 0, 0); PG8_LDB(B1, 0, 1); PG8_SCHED; PG8_LDA(At, 0, 0); PG8_STAGE(PG8_SA(1, 1), a1 + hstep, voffA);
;             PG8_WAIT_V(8); PG8_WAIT_L(0); PG8_BAR; PG8_MMA(0, 0, At, B0); PG8_MMA(0, 1, At, B1); PG8_BAR; PG8_SCHED;
;             PG8_LDA(At, 0, 1); PG8_STAGE(PG8_SB(0, 0), b2, voffB); PG8_STAGE(PG8_SB(0, 1), b2 + hstep, voffB); PG8_STAGE(PG8_SA(0, 0), a2, voffA);
;             PG8_WAIT_V(8); PG8_WAIT_L(0); PG8_BAR; PG8_MMA(1, 0, At, B0); PG8_MMA(1, 1, At, B1); PG8_BAR; PG8_SCHED;
; __global__ void __launch_bounds__(512, 2) fwd_megakernel(Params p) {
;     ...
;         { PHASE_IDS(); pg8::Gemm g{BH, (const bf16_t*)(WL + W_DN), NLAT, 1024, DFF, DFF}; pg8::StaticOrder S; S.init(NLAT, 1024, G, blk); S.rev = true; pg8::EpiBf16<0> E{BY, 1024};
.LBB0_1084:
	s_add_u32 s22, s20, 0xfff00080
	s_addc_u32 s23, s21, -1
	s_add_i32 s75, 0, 0x10000
	s_cmp_eq_u32 s74, 60
	s_cselect_b32 s25, s13, s23
	s_cselect_b32 s24, s62, s22
	v_add_u32_e32 v140, s75, v143
	s_cselect_b32 s23, s11, s73
	s_cselect_b32 s22, s63, s72
	s_add_i32 s78, 0, 0x14000
	ds_read_b128 v[146:149], v140
	ds_read_b128 v[150:153], v140 offset:1024
	ds_read_b128 v[154:157], v140 offset:2048
	ds_read_b128 v[158:161], v140 offset:3072
	v_add_u32_e32 v140, s78, v143
	ds_read_b128 v[162:165], v140
	ds_read_b128 v[166:169], v140 offset:1024
	ds_read_b128 v[170:173], v140 offset:2048
	ds_read_b128 v[178:181], v140 offset:3072
	v_lshl_add_u64 v[140:141], s[20:21], 0, v[136:137]
	s_add_i32 m0, s46, 0xc000
	ds_read_b128 v[182:185], v145
	ds_read_b128 v[186:189], v145 offset:1024
	ds_read_b128 v[190:193], v145 offset:2048
	ds_read_b128 v[194:197], v145 offset:3072
	ds_read_b128 v[198:201], v145 offset:4096
	ds_read_b128 v[202:205], v145 offset:5120
	ds_read_b128 v[214:217], v145 offset:6144
	ds_read_b128 v[218:221], v145 offset:7168
	global_load_lds_dwordx4 v[140:141], off
	v_lshl_add_u64 v[140:141], s[20:21], 0, v[138:139]
	s_add_i32 m0, s46, 0xe000
	s_nop 0
	global_load_lds_dwordx4 v[140:141], off
	s_waitcnt vmcnt(8) lgkmcnt(0)
	s_barrier
	s_setprio 1
	v_mfma_f32_16x16x32_bf16 v[126:129], v[146:149], v[182:185], v[126:129]
	v_mfma_f32_16x16x32_bf16 v[122:125], v[154:157], v[182:185], v[122:125]
	v_mfma_f32_16x16x32_bf16 v[118:121], v[146:149], v[190:193], v[118:121]
	v_mfma_f32_16x16x32_bf16 v[110:113], v[154:157], v[190:193], v[110:113]
	v_mfma_f32_16x16x32_bf16 v[102:105], v[146:149], v[198:201], v[102:105]
	v_mfma_f32_16x16x32_bf16 v[94:97], v[154:157], v[198:201], v[94:97]
	v_mfma_f32_16x16x32_bf16 v[86:89], v[146:149], v[214:217], v[86:89]
	v_mfma_f32_16x16x32_bf16 v[78:81], v[154:157], v[214:217], v[78:81]
	v_mfma_f32_16x16x32_bf16 v[126:129], v[150:153], v[186:189], v[126:129]
	v_mfma_f32_16x16x32_bf16 v[122:125], v[158:161], v[186:189], v[122:125]
	v_mfma_f32_16x16x32_bf16 v[118:121], v[150:153], v[194:197], v[118:121]
	v_mfma_f32_16x16x32_bf16 v[110:113], v[158:161], v[194:197], v[110:113]
	v_mfma_f32_16x16x32_bf16 v[102:105], v[150:153], v[202:205], v[102:105]
	v_mfma_f32_16x16x32_bf16 v[94:97], v[158:161], v[202:205], v[94:97]
	v_mfma_f32_16x16x32_bf16 v[86:89], v[150:153], v[218:221], v[86:89]
	v_mfma_f32_16x16x32_bf16 v[78:81], v[158:161], v[218:221], v[78:81]
	s_setprio 0
	s_setprio 1
	v_mfma_f32_16x16x32_bf16 v[114:117], v[162:165], v[182:185], v[114:117]
	v_mfma_f32_16x16x32_bf16 v[106:109], v[170:173], v[182:185], v[106:109]
	v_mfma_f32_16x16x32_bf16 v[98:101], v[162:165], v[190:193], v[98:101]
	v_mfma_f32_16x16x32_bf16 v[90:93], v[170:173], v[190:193], v[90:93]
	v_mfma_f32_16x16x32_bf16 v[82:85], v[162:165], v[198:201], v[82:85]
	v_mfma_f32_16x16x32_bf16 v[74:77], v[170:173], v[198:201], v[74:77]
	v_mfma_f32_16x16x32_bf16 v[70:73], v[162:165], v[214:217], v[70:73]
	v_mfma_f32_16x16x32_bf16 v[66:69], v[170:173], v[214:217], v[66:69]
	v_mfma_f32_16x16x32_bf16 v[114:117], v[166:169], v[186:189], v[114:117]
	v_mfma_f32_16x16x32_bf16 v[106:109], v[178:181], v[186:189], v[106:109]
	v_mfma_f32_16x16x32_bf16 v[98:101], v[166:169], v[194:197], v[98:101]
	v_mfma_f32_16x16x32_bf16 v[90:93], v[178:181], v[194:197], v[90:93]
	v_mfma_f32_16x16x32_bf16 v[82:85], v[166:169], v[202:205], v[82:85]
	v_mfma_f32_16x16x32_bf16 v[74:77], v[178:181], v[202:205], v[74:77]
	v_mfma_f32_16x16x32_bf16 v[70:73], v[166:169], v[218:221], v[70:73]
	v_mfma_f32_16x16x32_bf16 v[66:69], v[178:181], v[218:221], v[66:69]
	s_setprio 0
	s_barrier
	s_add_i32 s75, s75, s37
	v_lshl_add_u64 v[140:141], s[22:23], 0, v[0:1]
	s_mov_b32 m0, s75
	ds_read_b128 v[182:185], v145 offset:16384
	ds_read_b128 v[186:189], v145 offset:17408
	ds_read_b128 v[190:193], v145 offset:18432
	ds_read_b128 v[194:197], v145 offset:19456
	ds_read_b128 v[198:201], v145 offset:20480
	ds_read_b128 v[202:205], v145 offset:21504
	ds_read_b128 v[214:217], v145 offset:22528
	ds_read_b128 v[218:221], v145 offset:23552
	global_load_lds_dwordx4 v[140:141], off
	s_add_i32 m0, s75, 0x2000
	s_add_u32 s76, s22, 0x100000
	v_lshl_add_u64 v[174:175], s[22:23], 0, v[134:135]
	s_addc_u32 s77, s23, 0
	s_add_i32 s75, s78, s37
	global_load_lds_dwordx4 v[174:175], off
	v_lshl_add_u64 v[208:209], s[76:77], 0, v[0:1]
	s_mov_b32 m0, s75
	v_lshl_add_u64 v[212:213], s[24:25], 0, v[132:133]
	global_load_lds_dwordx4 v[208:209], off
	v_lshl_add_u64 v[208:209], s[76:77], 0, v[134:135]
	s_add_i32 m0, s75, 0x2000
	s_nop 0
	global_load_lds_dwordx4 v[208:209], off
	v_lshl_add_u64 v[208:209], s[24:25], 0, v[130:131]
	s_mov_b32 m0, s46
	s_nop 0
	global_load_lds_dwordx4 v[208:209], off
	s_mov_b32 m0, s47
	s_nop 0
	global_load_lds_dwordx4 v[212:213], off
	s_waitcnt vmcnt(8) lgkmcnt(0)
	s_barrier
; #define PG8_STAGE(bufoff, gbase, voff) do { _Pragma("unroll") for (int _i = 0; _i < 2; ++_i) \
;         __builtin_amdgcn_global_load_lds((const unsigned*)((const char*)(gbase) + (voff)[_i]), (PG8_LAS unsigned*)(lds + (bufoff) + ldsw + _i * 8192), 16, 0, 0); } while (0)
; #define PG8_LDA(dst, b, h) do { _Pragma("unroll") for (int m = 0; m < 4; ++m) _Pragma("unroll") for (int k = 0; k < 2; ++k) dst[m][k] = *(const PG8_LAS bf16x8*)(lds + PG8_SA(b, h) + aoff + m * 2048 + k * 1024); } while (0)
; #define PG8_LDB(dst, b, h) do { _Pragma("unroll") for (int n = 0; n < 2; ++n) _Pragma("unroll") for (int k = 0; k < 2; ++k) dst[n][k] = *(const PG8_LAS bf16x8*)(lds + PG8_SB(b, h) + boff + n * 2048 + k * 1024); } while (0)
; #define PG8_MMA(ai, bj, At, Bt) do { __builtin_amdgcn_s_setprio(1); _Pragma("unroll") for (int m = 0; m < 4; ++m) _Pragma("unroll") for (int n = 0; n < 2; ++n) _Pragma("unroll") for (int k = 0; k < 2; ++k) \
;         acc[ai][bj][m][n] = __builtin_amdgcn_mfma_f32_16x16x32_bf16(Bt[n][k], At[m][k], acc[ai][bj][m][n], 0, 0, 0); __builtin_amdgcn_s_setprio(0); } while (0)
; #define PG8_WAIT_V(n) asm volatile("s_waitcnt vmcnt(" #n ")" ::: "memory")
; #define PG8_WAIT_L(n) asm volatile("s_waitcnt lgkmcnt(" #n ")" ::: "memory")
; #define PG8_BAR __builtin_amdgcn_s_barrier()
; #define PG8_SCHED __builtin_amdgcn_sched_barrier(0)
; template <class Epi, class Sched, bool ALIGN_EPI = false, bool SP2 = false>
; __device__ __forceinline__ void gemm_phase(PG8_LAS unsigned char* lds, const Gemm g, const Sched& S, const Epi& E, int wave_s) {
;     ...
;             PG8_WAIT_V(8); PG8_WAIT_L(0); PG8_BAR; PG8_MMA(1, 0, At, B0); PG8_MMA(1, 1, At, B1); PG8_BAR; PG8_SCHED;
;             PG8_LDB(B0, 1, 0); PG8_LDB(B1, 1, 1); PG8_SCHED; PG8_LDA(At, 1, 0); PG8_STAGE(PG8_SA(0, 1), a2 + hstep, voffA);
;             PG8_WAIT_V(8); PG8_WAIT_L(0); PG8_BAR; PG8_MMA(0, 0, At, B0); PG8_MMA(0, 1, At, B1); PG8_BAR; PG8_SCHED;
	s_setprio 1
	v_mfma_f32_16x16x32_bf16 v[62:65], v[146:149], v[182:185], v[62:65]
	v_mfma_f32_16x16x32_bf16 v[58:61], v[154:157], v[182:185], v[58:61]
	v_mfma_f32_16x16x32_bf16 v[54:57], v[146:149], v[190:193], v[54:57]
	v_mfma_f32_16x16x32_bf16 v[46:49], v[154:157], v[190:193], v[46:49]
	v_mfma_f32_16x16x32_bf16 v[38:41], v[146:149], v[198:201], v[38:41]
	v_mfma_f32_16x16x32_bf16 v[30:33], v[154:157], v[198:201], v[30:33]
	v_mfma_f32_16x16x32_bf16 v[22:25], v[146:149], v[214:217], v[22:25]
	v_mfma_f32_16x16x32_bf16 v[14:17], v[154:157], v[214:217], v[14:17]
	v_mfma_f32_16x16x32_bf16 v[62:65], v[150:153], v[186:189], v[62:65]
	v_mfma_f32_16x16x32_bf16 v[58:61], v[158:161], v[186:189], v[58:61]
	v_mfma_f32_16x16x32_bf16 v[54:57], v[150:153], v[194:197], v[54:57]
	v_mfma_f32_16x16x32_bf16 v[46:49], v[158:161], v[194:197], v[46:49]
	v_mfma_f32_16x16x32_bf16 v[38:41], v[150:153], v[202:205], v[38:41]
	v_mfma_f32_16x16x32_bf16 v[30:33], v[158:161], v[202:205], v[30:33]
	v_mfma_f32_16x16x32_bf16 v[22:25], v[150:153], v[218:221], v[22:25]
	v_mfma_f32_16x16x32_bf16 v[14:17], v[158:161], v[218:221], v[14:17]
	s_setprio 0
	s_setprio 1
	v_mfma_f32_16x16x32_bf16 v[50:53], v[162:165], v[182:185], v[50:53]
	v_mfma_f32_16x16x32_bf16 v[42:45], v[170:173], v[182:185], v[42:45]
	v_mfma_f32_16x16x32_bf16 v[34:37], v[162:165], v[190:193], v[34:37]
	v_mfma_f32_16x16x32_bf16 v[26:29], v[170:173], v[190:193], v[26:29]
	v_mfma_f32_16x16x32_bf16 v[18:21], v[162:165], v[198:201], v[18:21]
	v_mfma_f32_16x16x32_bf16 v[10:13], v[170:173], v[198:201], v[10:13]
	v_mfma_f32_16x16x32_bf16 v[6:9], v[162:165], v[214:217], v[6:9]
	v_mfma_f32_16x16x32_bf16 v[2:5], v[170:173], v[214:217], v[2:5]
	v_mfma_f32_16x16x32_bf16 v[50:53], v[166:169], v[186:189], v[50:53]
	v_mfma_f32_16x16x32_bf16 v[42:45], v[178:181], v[186:189], v[42:45]
	v_mfma_f32_16x16x32_bf16 v[34:37], v[166:169], v[194:197], v[34:37]
	v_mfma_f32_16x16x32_bf16 v[26:29], v[178:181], v[194:197], v[26:29]
	v_mfma_f32_16x16x32_bf16 v[18:21], v[166:169], v[202:205], v[18:21]
	v_mfma_f32_16x16x32_bf16 v[10:13], v[178:181], v[202:205], v[10:13]
	v_mfma_f32_16x16x32_bf16 v[6:9], v[166:169], v[218:221], v[6:9]
	v_mfma_f32_16x16x32_bf16 v[2:5], v[178:181], v[218:221], v[2:5]
	s_setprio 0
	s_barrier
	s_add_i32 s75, 0, 0x18000
	s_add_i32 s76, 0, 0x1c000
	v_add_u32_e32 v158, s75, v143
	v_add_u32_e32 v178, s76, v143
	ds_read_b128 v[146:149], v158
	ds_read_b128 v[150:153], v158 offset:1024
	ds_read_b128 v[154:157], v158 offset:2048
	ds_read_b128 v[158:161], v158 offset:3072
	ds_read_b128 v[162:165], v178
	ds_read_b128 v[166:169], v178 offset:1024
	ds_read_b128 v[170:173], v178 offset:2048
	ds_read_b128 v[178:181], v178 offset:3072
	s_add_u32 s24, s24, 0x100000
	s_addc_u32 s25, s25, 0
	s_mov_b32 m0, s48
	v_lshl_add_u64 v[222:223], s[24:25], 0, v[130:131]
	ds_read_b128 v[182:185], v145 offset:32768
	ds_read_b128 v[186:189], v145 offset:33792
	ds_read_b128 v[190:193], v145 offset:34816
	ds_read_b128 v[194:197], v145 offset:35840
	ds_read_b128 v[198:201], v145 offset:36864
	ds_read_b128 v[202:205], v145 offset:37888
	ds_read_b128 v[214:217], v145 offset:38912
	ds_read_b128 v[218:221], v145 offset:39936
	global_load_lds_dwordx4 v[222:223], off
	v_lshl_add_u64 v[222:223], s[24:25], 0, v[132:133]
	s_mov_b32 m0, s49
	s_nop 0
	global_load_lds_dwordx4 v[222:223], off
	s_waitcnt vmcnt(8) lgkmcnt(0)
	s_barrier
	s_setprio 1
	v_mfma_f32_16x16x32_bf16 v[126:129], v[146:149], v[182:185], v[126:129]
	v_mfma_f32_16x16x32_bf16 v[122:125], v[154:157], v[182:185], v[122:125]
	v_mfma_f32_16x16x32_bf16 v[118:121], v[146:149], v[190:193], v[118:121]
	v_mfma_f32_16x16x32_bf16 v[110:113], v[154:157], v[190:193], v[110:113]
	v_mfma_f32_16x16x32_bf16 v[102:105], v[146:149], v[198:201], v[102:105]
	v_mfma_f32_16x16x32_bf16 v[94:97], v[154:157], v[198:201], v[94:97]
	v_mfma_f32_16x16x32_bf16 v[86:89], v[146:149], v[214:217], v[86:89]
	v_mfma_f32_16x16x32_bf16 v[78:81], v[154:157], v[214:217], v[78:81]
	v_mfma_f32_16x16x32_bf16 v[126:129], v[150:153], v[186:189], v[126:129]
	v_mfma_f32_16x16x32_bf16 v[122:125], v[158:161], v[186:189], v[122:125]
	v_mfma_f32_16x16x32_bf16 v[118:121], v[150:153], v[194:197], v[118:121]
	v_mfma_f32_16x16x32_bf16 v[110:113], v[158:161], v[194:197], v[110:113]
	v_mfma_f32_16x16x32_bf16 v[102:105], v[150:153], v[202:205], v[102:105]
	v_mfma_f32_16x16x32_bf16 v[94:97], v[158:161], v[202:205], v[94:97]
	v_mfma_f32_16x16x32_bf16 v[86:89], v[150:153], v[218:221], v[86:89]
	v_mfma_f32_16x16x32_bf16 v[78:81], v[158:161], v[218:221], v[78:81]
	s_setprio 0
	s_setprio 1
	v_mfma_f32_16x16x32_bf16 v[114:117], v[162:165], v[182:185], v[114:117]
	v_mfma_f32_16x16x32_bf16 v[106:109], v[170:173], v[182:185], v[106:109]
	v_mfma_f32_16x16x32_bf16 v[98:101], v[162:165], v[190:193], v[98:101]
	v_mfma_f32_16x16x32_bf16 v[90:93], v[170:173], v[190:193], v[90:93]
	v_mfma_f32_16x16x32_bf16 v[82:85], v[162:165], v[198:201], v[82:85]
	v_mfma_f32_16x16x32_bf16 v[74:77], v[170:173], v[198:201], v[74:77]
	v_mfma_f32_16x16x32_bf16 v[70:73], v[162:165], v[214:217], v[70:73]
	v_mfma_f32_16x16x32_bf16 v[66:69], v[170:173], v[214:217], v[66:69]
	v_mfma_f32_16x16x32_bf16 v[114:117], v[166:169], v[186:189], v[114:117]
	v_mfma_f32_16x16x32_bf16 v[106:109], v[178:181], v[186:189], v[106:109]
	v_mfma_f32_16x16x32_bf16 v[98:101], v[166:169], v[194:197], v[98:101]
	v_mfma_f32_16x16x32_bf16 v[90:93], v[178:181], v[194:197], v[90:93]
	v_mfma_f32_16x16x32_bf16 v[82:85], v[166:169], v[202:205], v[82:85]
	v_mfma_f32_16x16x32_bf16 v[74:77], v[178:181], v[202:205], v[74:77]
	v_mfma_f32_16x16x32_bf16 v[70:73], v[166:169], v[218:221], v[70:73]
	v_mfma_f32_16x16x32_bf16 v[66:69], v[178:181], v[218:221], v[66:69]
	s_setprio 0
	s_barrier
; #define PG8_STAGE(bufoff, gbase, voff) do { _Pragma("unroll") for (int _i = 0; _i < 2; ++_i) \
;         __builtin_amdgcn_global_load_lds((const unsigned*)((const char*)(gbase) + (voff)[_i]), (PG8_LAS unsigned*)(lds + (bufoff) + ldsw + _i * 8192), 16, 0, 0); } while (0)
; #define PG8_LDA(dst, b, h) do { _Pragma("unroll") for (int m = 0; m < 4; ++m) _Pragma("unroll") for (int k = 0; k < 2; ++k) dst[m][k] = *(const PG8_LAS bf16x8*)(lds + PG8_SA(b, h) + aoff + m * 2048 + k * 1024); } while (0)
; #define PG8_MMA(ai, bj, At, Bt) do { __builtin_amdgcn_s_setprio(1); _Pragma("unroll") for (int m = 0; m < 4; ++m) _Pragma("unroll") for (int n = 0; n < 2; ++n) _Pragma("unroll") for (int k = 0; k < 2; ++k) \
;         acc[ai][bj][m][n] = __builtin_amdgcn_mfma_f32_16x16x32_bf16(Bt[n][k], At[m][k], acc[ai][bj][m][n], 0, 0, 0); __builtin_amdgcn_s_setprio(0); } while (0)
; #define PG8_WAIT_V(n) asm volatile("s_waitcnt vmcnt(" #n ")" ::: "memory")
; #define PG8_WAIT_L(n) asm volatile("s_waitcnt lgkmcnt(" #n ")" ::: "memory")
; #define PG8_BAR __builtin_amdgcn_s_barrier()
; #define PG8_SCHED __builtin_amdgcn_sched_barrier(0)
; template <class Epi, class Sched, bool ALIGN_EPI = false, bool SP2 = false>
; __device__ __forceinline__ void gemm_phase(PG8_LAS unsigned char* lds, const Gemm g, const Sched& S, const Epi& E, int wave_s) {
;     ...
;         for (int t = 0; t < nt; t += 2) {
;     ...
;             PG8_LDA(At, 1, 1); PG8_STAGE(PG8_SB(1, 0), b3, voffB); PG8_STAGE(PG8_SB(1, 1), b3 + hstep, voffB); PG8_STAGE(PG8_SA(1, 0), a3, voffA);
;             PG8_WAIT_V(8); PG8_WAIT_L(0); PG8_BAR; PG8_MMA(1, 0, At, B0); PG8_MMA(1, 1, At, B1); PG8_BAR; PG8_SCHED;
	s_add_i32 s24, s75, s37
	v_lshl_add_u64 v[140:141], v[140:141], 0, s[60:61]
	s_mov_b32 m0, s24
	ds_read_b128 v[182:185], v145 offset:49152
	ds_read_b128 v[186:189], v145 offset:50176
	ds_read_b128 v[190:193], v145 offset:51200
	ds_read_b128 v[194:197], v145 offset:52224
	ds_read_b128 v[198:201], v145 offset:53248
	ds_read_b128 v[202:205], v145 offset:54272
	ds_read_b128 v[214:217], v145 offset:55296
	ds_read_b128 v[218:221], v145 offset:56320
	global_load_lds_dwordx4 v[140:141], off
	s_add_i32 m0, s24, 0x2000
	s_add_u32 s22, s22, 0x100080
	v_lshl_add_u64 v[140:141], v[174:175], 0, s[60:61]
	s_addc_u32 s23, s23, 0
	s_add_i32 s24, s76, s37
	global_load_lds_dwordx4 v[140:141], off
	v_lshl_add_u64 v[140:141], s[22:23], 0, v[0:1]
	s_mov_b32 m0, s24
	s_nop 0
	global_load_lds_dwordx4 v[140:141], off
	v_lshl_add_u64 v[140:141], s[22:23], 0, v[134:135]
	s_add_i32 m0, s24, 0x2000
	s_nop 0
	global_load_lds_dwordx4 v[140:141], off
	v_lshl_add_u64 v[140:141], v[208:209], 0, s[60:61]
	s_mov_b32 m0, s50
	s_nop 0
	global_load_lds_dwordx4 v[140:141], off
	v_lshl_add_u64 v[140:141], v[212:213], 0, s[60:61]
	s_mov_b32 m0, s51
	s_nop 0
	global_load_lds_dwordx4 v[140:141], off
	s_waitcnt vmcnt(8) lgkmcnt(0)
	s_barrier
	s_setprio 1
	v_mfma_f32_16x16x32_bf16 v[62:65], v[146:149], v[182:185], v[62:65]
	v_mfma_f32_16x16x32_bf16 v[58:61], v[154:157], v[182:185], v[58:61]
	v_mfma_f32_16x16x32_bf16 v[54:57], v[146:149], v[190:193], v[54:57]
	v_mfma_f32_16x16x32_bf16 v[46:49], v[154:157], v[190:193], v[46:49]
	v_mfma_f32_16x16x32_bf16 v[38:41], v[146:149], v[198:201], v[38:41]
	v_mfma_f32_16x16x32_bf16 v[30:33], v[154:157], v[198:201], v[30:33]
	v_mfma_f32_16x16x32_bf16 v[22:25], v[146:149], v[214:217], v[22:25]
	v_mfma_f32_16x16x32_bf16 v[14:17], v[154:157], v[214:217], v[14:17]
	v_mfma_f32_16x16x32_bf16 v[62:65], v[150:153], v[186:189], v[62:65]
	v_mfma_f32_16x16x32_bf16 v[58:61], v[158:161], v[186:189], v[58:61]
	v_mfma_f32_16x16x32_bf16 v[54:57], v[150:153], v[194:197], v[54:57]
	v_mfma_f32_16x16x32_bf16 v[46:49], v[158:161], v[194:197], v[46:49]
	v_mfma_f32_16x16x32_bf16 v[38:41], v[150:153], v[202:205], v[38:41]
	v_mfma_f32_16x16x32_bf16 v[30:33], v[158:161], v[202:205], v[30:33]
	v_mfma_f32_16x16x32_bf16 v[22:25], v[150:153], v[218:221], v[22:25]
	v_mfma_f32_16x16x32_bf16 v[14:17], v[158:161], v[218:221], v[14:17]
	s_setprio 0
	s_setprio 1
	v_mfma_f32_16x16x32_bf16 v[50:53], v[162:165], v[182:185], v[50:53]
	v_mfma_f32_16x16x32_bf16 v[42:45], v[170:173], v[182:185], v[42:45]
	v_mfma_f32_16x16x32_bf16 v[34:37], v[162:165], v[190:193], v[34:37]
	v_mfma_f32_16x16x32_bf16 v[26:29], v[170:173], v[190:193], v[26:29]
	v_mfma_f32_16x16x32_bf16 v[18:21], v[162:165], v[198:201], v[18:21]
	v_mfma_f32_16x16x32_bf16 v[10:13], v[170:173], v[198:201], v[10:13]
	v_mfma_f32_16x16x32_bf16 v[6:9], v[162:165], v[214:217], v[6:9]
	v_mfma_f32_16x16x32_bf16 v[2:5], v[170:173], v[214:217], v[2:5]
	v_mfma_f32_16x16x32_bf16 v[50:53], v[166:169], v[186:189], v[50:53]
	v_mfma_f32_16x16x32_bf16 v[42:45], v[178:181], v[186:189], v[42:45]
	v_mfma_f32_16x16x32_bf16 v[34:37], v[166:169], v[194:197], v[34:37]
	v_mfma_f32_16x16x32_bf16 v[26:29], v[178:181], v[194:197], v[26:29]
	v_mfma_f32_16x16x32_bf16 v[18:21], v[166:169], v[202:205], v[18:21]
	v_mfma_f32_16x16x32_bf16 v[10:13], v[178:181], v[202:205], v[10:13]
	v_mfma_f32_16x16x32_bf16 v[6:9], v[166:169], v[218:221], v[6:9]
	v_mfma_f32_16x16x32_bf16 v[2:5], v[178:181], v[218:221], v[2:5]
	s_setprio 0
	s_barrier
	s_add_i32 s74, s74, 2
	s_add_u32 s20, s20, 0x100
	s_addc_u32 s21, s21, 0
	s_add_u32 s72, s72, 0x100
	s_addc_u32 s73, s73, 0
	s_cmp_gt_u32 s74, 61
	s_cbranch_scc0 .LBB0_1084
	s_and_b64 vcc, exec, s[8:9]
	s_cbranch_vccz .LBB0_1087
	s_barrier

; #define PG8_STAGE(bufoff, gbase, voff) do { _Pragma("unroll") for (int _i = 0; _i < 2; ++_i) \
;         __builtin_amdgcn_global_load_lds((const unsigned*)((const char*)(gbase) + (voff)[_i]), (PG8_LAS unsigned*)(lds + (bufoff) + ldsw + _i * 8192), 16, 0, 0); } while (0)
; #define PG8_LDA(dst, b, h) do { _Pragma("unroll") for (int m = 0; m < 4; ++m) _Pragma("unroll") for (int k = 0; k < 2; ++k) dst[m][k] = *(const PG8_LAS bf16x8*)(lds + PG8_SA(b, h) + aoff + m * 2048 + k * 1024); } while (0)
; #define PG8_LDB(dst, b, h) do { _Pragma("unroll") for (int n = 0; n < 2; ++n) _Pragma("unroll") for (int k = 0; k < 2; ++k) dst[n][k] = *(const PG8_LAS bf16x8*)(lds + PG8_SB(b, h) + boff + n * 2048 + k * 1024); } while (0)
; #define PG8_MMA(ai, bj, At, Bt) do { __builtin_amdgcn_s_setprio(1); _Pragma("unroll") for (int m = 0; m < 4; ++m) _Pragma("unroll") for (int n = 0; n < 2; ++n) _Pragma("unroll") for (int k = 0; k < 2; ++k) \
;         acc[ai][bj][m][n] = __builtin_amdgcn_mfma_f32_16x16x32_bf16(Bt[n][k], At[m][k], acc[ai][bj][m][n], 0, 0, 0); __builtin_amdgcn_s_setprio(0); } while (0)
; #define PG8_WAIT_V(n) asm volatile("s_waitcnt vmcnt(" #n ")" ::: "memory")
; template <class Epi, class Sched, bool ALIGN_EPI = false, bool SP2 = false>
; __device__ __forceinline__ void gemm_phase(PG8_LAS unsigned char* lds, const Gemm g, const Sched& S, const Epi& E, int wave_s) {
;     ...
;         for (int t = 0; t < nt; t += 2) {
;             const bool last = (t == nt - 2);
;             const char* a1 = cA + (size_t)(t + 1) * kstep;
;             const char* a2 = last ? nA : cA + (size_t)(t + 2) * kstep; const char* b2 = last ? nB : cB + (size_t)(t + 2) * kstep;
;             const char* a3 = a2 + kstep; const char* b3 = b2 + kstep;
;             if (last && has_next) S.a_ready(nxt);
;             if constexpr (SP2) {
;             PG8_LDB(B0, 0, 0); PG8_LDB(B1, 0, 1); PG8_SCHED; PG8_LDA(At, 0, 0); PG8_STAGE(PG8_SA(1, 1), a1 + hstep, voffA);
;             PG8_WAIT_V(8); PG8_WAIT_L(0); PG8_BAR; PG8_MMA(0, 0, At, B0); PG8_MMA(0, 1, At, B1); PG8_BAR; PG8_SCHED;
; __global__ void __launch_bounds__(512, 2) fwd_megakernel(Params p) {
;     ...
;         if (!last) { PHASE_IDS(); pg8::Gemm g{BH, (const bf16_t*)(WL + W_DN), MTOT, 1024, 256, DFF}; pg8::SplitOrder S; S.init(4, 4, 16, 128, G, blk); pg8::EpiF32Part E{WSP(float, WS_PART), 1024, 128, (size_t)1024 * 1024};
.LBB0_1104:
	s_add_i32 s17, 0, 0x10000
	s_add_i32 s19, 0, 0x14000
	v_add_u32_e32 v220, s17, v136
	v_add_u32_e32 v221, s19, v136
	ds_read_b128 v[2:5], v220
	ds_read_b128 v[6:9], v220 offset:1024
	ds_read_b128 v[10:13], v220 offset:2048
	ds_read_b128 v[14:17], v220 offset:3072
	ds_read_b128 v[18:21], v221
	ds_read_b128 v[22:25], v221 offset:1024
	ds_read_b128 v[26:29], v221 offset:2048
	ds_read_b128 v[30:33], v221 offset:3072
	s_add_u32 s62, s26, 0x100080
	s_addc_u32 s63, s27, 0
	s_add_i32 s70, s9, 0xc000
	v_lshl_add_u64 v[66:67], s[62:63], 0, v[134:135]
	s_mov_b32 m0, s70
	s_add_i32 s7, s9, 0xe000
	ds_read_b128 v[34:37], v139
	ds_read_b128 v[38:41], v139 offset:1024
	ds_read_b128 v[42:45], v139 offset:2048
	ds_read_b128 v[46:49], v139 offset:3072
	ds_read_b128 v[50:53], v139 offset:4096
	ds_read_b128 v[54:57], v139 offset:5120
	ds_read_b128 v[58:61], v139 offset:6144
	ds_read_b128 v[62:65], v139 offset:7168
	global_load_lds_dwordx4 v[66:67], off
	v_lshl_add_u64 v[66:67], s[62:63], 0, v[132:133]
	s_mov_b32 m0, s7
	s_nop 0
	global_load_lds_dwordx4 v[66:67], off
	s_waitcnt vmcnt(8) lgkmcnt(0)
	s_barrier
	s_setprio 1
	v_mfma_f32_16x16x32_bf16 v[66:69], v[2:5], v[34:37], 0
	v_mfma_f32_16x16x32_bf16 v[70:73], v[10:13], v[34:37], 0
	v_mfma_f32_16x16x32_bf16 v[74:77], v[2:5], v[42:45], 0
	v_mfma_f32_16x16x32_bf16 v[78:81], v[10:13], v[42:45], 0
	v_mfma_f32_16x16x32_bf16 v[82:85], v[2:5], v[50:53], 0
	v_mfma_f32_16x16x32_bf16 v[86:89], v[10:13], v[50:53], 0
	v_mfma_f32_16x16x32_bf16 v[90:93], v[2:5], v[58:61], 0
	v_mfma_f32_16x16x32_bf16 v[94:97], v[10:13], v[58:61], 0
	v_mfma_f32_16x16x32_bf16 v[66:69], v[6:9], v[38:41], v[66:69]
	v_mfma_f32_16x16x32_bf16 v[70:73], v[14:17], v[38:41], v[70:73]
	v_mfma_f32_16x16x32_bf16 v[74:77], v[6:9], v[46:49], v[74:77]
	v_mfma_f32_16x16x32_bf16 v[78:81], v[14:17], v[46:49], v[78:81]
	v_mfma_f32_16x16x32_bf16 v[82:85], v[6:9], v[54:57], v[82:85]
	v_mfma_f32_16x16x32_bf16 v[86:89], v[14:17], v[54:57], v[86:89]
	v_mfma_f32_16x16x32_bf16 v[90:93], v[6:9], v[62:65], v[90:93]
	v_mfma_f32_16x16x32_bf16 v[94:97], v[14:17], v[62:65], v[94:97]
	s_setprio 0
	s_setprio 1
	v_mfma_f32_16x16x32_bf16 v[98:101], v[18:21], v[34:37], 0
	v_mfma_f32_16x16x32_bf16 v[34:37], v[26:29], v[34:37], 0
	v_mfma_f32_16x16x32_bf16 v[98:101], v[22:25], v[38:41], v[98:101]
	v_mfma_f32_16x16x32_bf16 v[34:37], v[30:33], v[38:41], v[34:37]
	v_mfma_f32_16x16x32_bf16 v[38:41], v[18:21], v[42:45], 0
	v_mfma_f32_16x16x32_bf16 v[42:45], v[26:29], v[42:45], 0
	v_mfma_f32_16x16x32_bf16 v[38:41], v[22:25], v[46:49], v[38:41]
	v_mfma_f32_16x16x32_bf16 v[42:45], v[30:33], v[46:49], v[42:45]
	v_mfma_f32_16x16x32_bf16 v[46:49], v[18:21], v[50:53], 0
	v_mfma_f32_16x16x32_bf16 v[50:53], v[26:29], v[50:53], 0
	v_mfma_f32_16x16x32_bf16 v[46:49], v[22:25], v[54:57], v[46:49]
	v_mfma_f32_16x16x32_bf16 v[50:53], v[30:33], v[54:57], v[50:53]
	v_mfma_f32_16x16x32_bf16 v[54:57], v[18:21], v[58:61], 0
	v_mfma_f32_16x16x32_bf16 v[58:61], v[26:29], v[58:61], 0
	v_mfma_f32_16x16x32_bf16 v[54:57], v[22:25], v[62:65], v[54:57]
	v_mfma_f32_16x16x32_bf16 v[58:61], v[30:33], v[62:65], v[58:61]
	s_setprio 0
	s_barrier
	s_add_i32 s62, s17, s47
	v_lshl_add_u64 v[172:173], s[28:29], 0, v[0:1]
	s_mov_b64 s[74:75], 0x100
	s_add_i32 s17, s62, 0x2000
	v_lshl_add_u64 v[140:141], v[172:173], 0, s[74:75]
	s_mov_b32 m0, s62
	v_lshl_add_u64 v[174:175], s[28:29], 0, v[130:131]
	s_add_u32 s72, s28, 0x100100
	ds_read_b128 v[62:65], v139 offset:16384
	ds_read_b128 v[102:105], v139 offset:17408
	ds_read_b128 v[106:109], v139 offset:18432
	ds_read_b128 v[110:113], v139 offset:19456
	ds_read_b128 v[114:117], v139 offset:20480
	ds_read_b128 v[118:121], v139 offset:21504
	ds_read_b128 v[122:125], v139 offset:22528
	ds_read_b128 v[126:129], v139 offset:23552
	global_load_lds_dwordx4 v[140:141], off
	v_lshl_add_u64 v[140:141], v[174:175], 0, s[74:75]
	s_mov_b32 m0, s17
	s_addc_u32 s73, s29, 0
	s_add_i32 s19, s19, s47
	global_load_lds_dwordx4 v[140:141], off
	v_lshl_add_u64 v[140:141], s[72:73], 0, v[0:1]
	s_mov_b32 m0, s19
	s_add_i32 s21, s19, 0x2000
	global_load_lds_dwordx4 v[140:141], off
	v_lshl_add_u64 v[140:141], s[72:73], 0, v[130:131]
	s_mov_b32 m0, s21
	v_lshl_add_u64 v[208:209], s[26:27], 0, v[134:135]
	global_load_lds_dwordx4 v[140:141], off
	v_lshl_add_u64 v[140:141], v[208:209], 0, s[74:75]
	s_mov_b32 m0, s9
	v_lshl_add_u64 v[212:213], s[26:27], 0, v[132:133]
	global_load_lds_dwordx4 v[140:141], off
	v_lshl_add_u64 v[140:141], v[212:213], 0, s[74:75]
	s_mov_b32 m0, s11
	s_nop 0
	global_load_lds_dwordx4 v[140:141], off
	s_waitcnt vmcnt(8) lgkmcnt(0)
	s_barrier
; #define PG8_STAGE(bufoff, gbase, voff) do { _Pragma("unroll") for (int _i = 0; _i < 2; ++_i) \
;         __builtin_amdgcn_global_load_lds((const unsigned*)((const char*)(gbase) + (voff)[_i]), (PG8_LAS unsigned*)(lds + (bufoff) + ldsw + _i * 8192), 16, 0, 0); } while (0)
; #define PG8_LDA(dst, b, h) do { _Pragma("unroll") for (int m = 0; m < 4; ++m) _Pragma("unroll") for (int k = 0; k < 2; ++k) dst[m][k] = *(const PG8_LAS bf16x8*)(lds + PG8_SA(b, h) + aoff + m * 2048 + k * 1024); } while (0)
; #define PG8_LDB(dst, b, h) do { _Pragma("unroll") for (int n = 0; n < 2; ++n) _Pragma("unroll") for (int k = 0; k < 2; ++k) dst[n][k] = *(const PG8_LAS bf16x8*)(lds + PG8_SB(b, h) + boff + n * 2048 + k * 1024); } while (0)
; #define PG8_MMA(ai, bj, At, Bt) do { __builtin_amdgcn_s_setprio(1); _Pragma("unroll") for (int m = 0; m < 4; ++m) _Pragma("unroll") for (int n = 0; n < 2; ++n) _Pragma("unroll") for (int k = 0; k < 2; ++k) \
;         acc[ai][bj][m][n] = __builtin_amdgcn_mfma_f32_16x16x32_bf16(Bt[n][k], At[m][k], acc[ai][bj][m][n], 0, 0, 0); __builtin_amdgcn_s_setprio(0); } while (0)
; #define PG8_WAIT_V(n) asm volatile("s_waitcnt vmcnt(" #n ")" ::: "memory")
; #define PG8_WAIT_L(n) asm volatile("s_waitcnt lgkmcnt(" #n ")" ::: "memory")
; #define PG8_BAR __builtin_amdgcn_s_barrier()
; #define PG8_SCHED __builtin_amdgcn_sched_barrier(0)
; template <class Epi, class Sched, bool ALIGN_EPI = false, bool SP2 = false>
; __device__ __forceinline__ void gemm_phase(PG8_LAS unsigned char* lds, const Gemm g, const Sched& S, const Epi& E, int wave_s) {
;     ...
;             PG8_WAIT_V(8); PG8_WAIT_L(0); PG8_BAR; PG8_MMA(0, 0, At, B0); PG8_MMA(0, 1, At, B1); PG8_BAR; PG8_SCHED;
;             PG8_LDA(At, 0, 1); PG8_STAGE(PG8_SB(0, 0), b2, voffB); PG8_STAGE(PG8_SB(0, 1), b2 + hstep, voffB); PG8_STAGE(PG8_SA(0, 0), a2, voffA);
;             PG8_WAIT_V(8); PG8_WAIT_L(0); PG8_BAR; PG8_MMA(1, 0, At, B0); PG8_MMA(1, 1, At, B1); PG8_BAR; PG8_SCHED;
;             PG8_LDB(B0, 1, 0); PG8_LDB(B1, 1, 1); PG8_SCHED; PG8_LDA(At, 1, 0); PG8_STAGE(PG8_SA(0, 1), a2 + hstep, voffA);
;             PG8_WAIT_V(8); PG8_WAIT_L(0); PG8_BAR; PG8_MMA(0, 0, At, B0); PG8_MMA(0, 1, At, B1); PG8_BAR; PG8_SCHED;
	s_setprio 1
	v_mfma_f32_16x16x32_bf16 v[140:143], v[2:5], v[62:65], 0
	v_mfma_f32_16x16x32_bf16 v[148:151], v[2:5], v[106:109], 0
	v_mfma_f32_16x16x32_bf16 v[156:159], v[2:5], v[114:117], 0
	v_mfma_f32_16x16x32_bf16 v[2:5], v[2:5], v[122:125], 0
	v_mfma_f32_16x16x32_bf16 v[140:143], v[6:9], v[102:105], v[140:143]
	v_mfma_f32_16x16x32_bf16 v[148:151], v[6:9], v[110:113], v[148:151]
	v_mfma_f32_16x16x32_bf16 v[156:159], v[6:9], v[118:121], v[156:159]
	v_mfma_f32_16x16x32_bf16 v[2:5], v[6:9], v[126:129], v[2:5]
	v_mfma_f32_16x16x32_bf16 v[6:9], v[10:13], v[122:125], 0
	v_mfma_f32_16x16x32_bf16 v[144:147], v[10:13], v[62:65], 0
	v_mfma_f32_16x16x32_bf16 v[152:155], v[10:13], v[106:109], 0
	v_mfma_f32_16x16x32_bf16 v[160:163], v[10:13], v[114:117], 0
	v_mfma_f32_16x16x32_bf16 v[6:9], v[14:17], v[126:129], v[6:9]
	v_mfma_f32_16x16x32_bf16 v[144:147], v[14:17], v[102:105], v[144:147]
	v_mfma_f32_16x16x32_bf16 v[152:155], v[14:17], v[110:113], v[152:155]
	v_mfma_f32_16x16x32_bf16 v[160:163], v[14:17], v[118:121], v[160:163]
	s_setprio 0
	s_setprio 1
	v_mfma_f32_16x16x32_bf16 v[10:13], v[18:21], v[62:65], 0
	v_mfma_f32_16x16x32_bf16 v[14:17], v[26:29], v[62:65], 0
	v_mfma_f32_16x16x32_bf16 v[10:13], v[22:25], v[102:105], v[10:13]
	v_mfma_f32_16x16x32_bf16 v[14:17], v[30:33], v[102:105], v[14:17]
	v_mfma_f32_16x16x32_bf16 v[62:65], v[18:21], v[106:109], 0
	v_mfma_f32_16x16x32_bf16 v[102:105], v[26:29], v[106:109], 0
	v_mfma_f32_16x16x32_bf16 v[106:109], v[18:21], v[114:117], 0
	v_mfma_f32_16x16x32_bf16 v[18:21], v[18:21], v[122:125], 0
	v_mfma_f32_16x16x32_bf16 v[62:65], v[22:25], v[110:113], v[62:65]
	v_mfma_f32_16x16x32_bf16 v[102:105], v[30:33], v[110:113], v[102:105]
	v_mfma_f32_16x16x32_bf16 v[106:109], v[22:25], v[118:121], v[106:109]
	v_mfma_f32_16x16x32_bf16 v[110:113], v[26:29], v[114:117], 0
	v_mfma_f32_16x16x32_bf16 v[18:21], v[22:25], v[126:129], v[18:21]
	v_mfma_f32_16x16x32_bf16 v[22:25], v[26:29], v[122:125], 0
	v_mfma_f32_16x16x32_bf16 v[110:113], v[30:33], v[118:121], v[110:113]
	v_mfma_f32_16x16x32_bf16 v[22:25], v[30:33], v[126:129], v[22:25]
	s_setprio 0
	s_barrier
	s_add_i32 s63, 0, 0x18000
	s_add_i32 s76, 0, 0x1c000
	v_add_u32_e32 v230, s63, v136
	v_add_u32_e32 v234, s76, v136
	ds_read_b128 v[26:29], v230
	ds_read_b128 v[30:33], v230 offset:1024
	ds_read_b128 v[114:117], v230 offset:2048
	ds_read_b128 v[118:121], v230 offset:3072
	ds_read_b128 v[122:125], v234
	ds_read_b128 v[126:129], v234 offset:1024
	ds_read_b128 v[164:167], v234 offset:2048
	ds_read_b128 v[168:171], v234 offset:3072
	s_add_u32 s72, s26, 0x100100
	s_addc_u32 s73, s27, 0
	s_mov_b32 m0, s48
	v_lshl_add_u64 v[218:219], s[72:73], 0, v[134:135]
	ds_read_b128 v[178:181], v139 offset:32768
	ds_read_b128 v[182:185], v139 offset:33792
	ds_read_b128 v[186:189], v139 offset:34816
	ds_read_b128 v[190:193], v139 offset:35840
	ds_read_b128 v[194:197], v139 offset:36864
	ds_read_b128 v[198:201], v139 offset:37888
	ds_read_b128 v[202:205], v139 offset:38912
	ds_read_b128 v[214:217], v139 offset:39936
	global_load_lds_dwordx4 v[218:219], off
	v_lshl_add_u64 v[218:219], s[72:73], 0, v[132:133]
	s_mov_b32 m0, s49
	s_nop 0
	global_load_lds_dwordx4 v[218:219], off
	s_waitcnt vmcnt(8) lgkmcnt(0)
	s_barrier
	s_setprio 1
	v_mfma_f32_16x16x32_bf16 v[66:69], v[26:29], v[178:181], v[66:69]
	v_mfma_f32_16x16x32_bf16 v[70:73], v[114:117], v[178:181], v[70:73]
	v_mfma_f32_16x16x32_bf16 v[74:77], v[26:29], v[186:189], v[74:77]
	v_mfma_f32_16x16x32_bf16 v[78:81], v[114:117], v[186:189], v[78:81]
	v_mfma_f32_16x16x32_bf16 v[82:85], v[26:29], v[194:197], v[82:85]
	v_mfma_f32_16x16x32_bf16 v[86:89], v[114:117], v[194:197], v[86:89]
	v_mfma_f32_16x16x32_bf16 v[90:93], v[26:29], v[202:205], v[90:93]
	v_mfma_f32_16x16x32_bf16 v[94:97], v[114:117], v[202:205], v[94:97]
	v_mfma_f32_16x16x32_bf16 v[66:69], v[30:33], v[182:185], v[66:69]
	v_mfma_f32_16x16x32_bf16 v[70:73], v[118:121], v[182:185], v[70:73]
	v_mfma_f32_16x16x32_bf16 v[74:77], v[30:33], v[190:193], v[74:77]
	v_mfma_f32_16x16x32_bf16 v[78:81], v[118:121], v[190:193], v[78:81]
	v_mfma_f32_16x16x32_bf16 v[82:85], v[30:33], v[198:201], v[82:85]
	v_mfma_f32_16x16x32_bf16 v[86:89], v[118:121], v[198:201], v[86:89]
	v_mfma_f32_16x16x32_bf16 v[90:93], v[30:33], v[214:217], v[90:93]
	v_mfma_f32_16x16x32_bf16 v[94:97], v[118:121], v[214:217], v[94:97]
	s_setprio 0
	s_setprio 1
	v_mfma_f32_16x16x32_bf16 v[98:101], v[122:125], v[178:181], v[98:101]
	v_mfma_f32_16x16x32_bf16 v[34:37], v[164:167], v[178:181], v[34:37]
	v_mfma_f32_16x16x32_bf16 v[38:41], v[122:125], v[186:189], v[38:41]
	v_mfma_f32_16x16x32_bf16 v[42:45], v[164:167], v[186:189], v[42:45]
	v_mfma_f32_16x16x32_bf16 v[46:49], v[122:125], v[194:197], v[46:49]
	v_mfma_f32_16x16x32_bf16 v[50:53], v[164:167], v[194:197], v[50:53]
	v_mfma_f32_16x16x32_bf16 v[54:57], v[122:125], v[202:205], v[54:57]
	v_mfma_f32_16x16x32_bf16 v[58:61], v[164:167], v[202:205], v[58:61]
	v_mfma_f32_16x16x32_bf16 v[98:101], v[126:129], v[182:185], v[98:101]
	v_mfma_f32_16x16x32_bf16 v[34:37], v[168:171], v[182:185], v[34:37]
	v_mfma_f32_16x16x32_bf16 v[38:41], v[126:129], v[190:193], v[38:41]
	v_mfma_f32_16x16x32_bf16 v[42:45], v[168:171], v[190:193], v[42:45]
	v_mfma_f32_16x16x32_bf16 v[46:49], v[126:129], v[198:201], v[46:49]
	v_mfma_f32_16x16x32_bf16 v[50:53], v[168:171], v[198:201], v[50:53]
	v_mfma_f32_16x16x32_bf16 v[54:57], v[126:129], v[214:217], v[54:57]
	v_mfma_f32_16x16x32_bf16 v[58:61], v[168:171], v[214:217], v[58:61]
	s_setprio 0
	s_barrier
; #define PG8_STAGE(bufoff, gbase, voff) do { _Pragma("unroll") for (int _i = 0; _i < 2; ++_i) \
;         __builtin_amdgcn_global_load_lds((const unsigned*)((const char*)(gbase) + (voff)[_i]), (PG8_LAS unsigned*)(lds + (bufoff) + ldsw + _i * 8192), 16, 0, 0); } while (0)
; #define PG8_LDA(dst, b, h) do { _Pragma("unroll") for (int m = 0; m < 4; ++m) _Pragma("unroll") for (int k = 0; k < 2; ++k) dst[m][k] = *(const PG8_LAS bf16x8*)(lds + PG8_SA(b, h) + aoff + m * 2048 + k * 1024); } while (0)
; #define PG8_LDB(dst, b, h) do { _Pragma("unroll") for (int n = 0; n < 2; ++n) _Pragma("unroll") for (int k = 0; k < 2; ++k) dst[n][k] = *(const PG8_LAS bf16x8*)(lds + PG8_SB(b, h) + boff + n * 2048 + k * 1024); } while (0)
; #define PG8_MMA(ai, bj, At, Bt) do { __builtin_amdgcn_s_setprio(1); _Pragma("unroll") for (int m = 0; m < 4; ++m) _Pragma("unroll") for (int n = 0; n < 2; ++n) _Pragma("unroll") for (int k = 0; k < 2; ++k) \
;         acc[ai][bj][m][n] = __builtin_amdgcn_mfma_f32_16x16x32_bf16(Bt[n][k], At[m][k], acc[ai][bj][m][n], 0, 0, 0); __builtin_amdgcn_s_setprio(0); } while (0)
; #define PG8_WAIT_V(n) asm volatile("s_waitcnt vmcnt(" #n ")" ::: "memory")
; #define PG8_WAIT_L(n) asm volatile("s_waitcnt lgkmcnt(" #n ")" ::: "memory")
; #define PG8_BAR __builtin_amdgcn_s_barrier()
; #define PG8_SCHED __builtin_amdgcn_sched_barrier(0)
; template <class Epi, class Sched, bool ALIGN_EPI = false, bool SP2 = false>
; __device__ __forceinline__ void gemm_phase(PG8_LAS unsigned char* lds, const Gemm g, const Sched& S, const Epi& E, int wave_s) {
;     ...
;             PG8_LDB(B0, 0, 0); PG8_LDB(B1, 0, 1); PG8_SCHED; PG8_LDA(At, 0, 0); PG8_STAGE(PG8_SA(1, 1), a1 + hstep, voffA);
;             PG8_WAIT_V(8); PG8_WAIT_L(0); PG8_BAR; PG8_MMA(0, 0, At, B0); PG8_MMA(0, 1, At, B1); PG8_BAR; PG8_SCHED;
;     ...
;             PG8_WAIT_V(8); PG8_WAIT_L(0); PG8_BAR; PG8_MMA(0, 0, At, B0); PG8_MMA(0, 1, At, B1); PG8_BAR; PG8_SCHED;
;             PG8_LDA(At, 1, 1); PG8_STAGE(PG8_SB(1, 0), b3, voffB); PG8_STAGE(PG8_SB(1, 1), b3 + hstep, voffB); PG8_STAGE(PG8_SA(1, 0), a3, voffA);
;             PG8_WAIT_V(8); PG8_WAIT_L(0); PG8_BAR; PG8_MMA(1, 0, At, B0); PG8_MMA(1, 1, At, B1); PG8_BAR; PG8_SCHED;
	s_add_i32 s72, s63, s47
	s_mov_b64 s[78:79], 0x180
	s_add_i32 s63, s72, 0x2000
	v_lshl_add_u64 v[172:173], v[172:173], 0, s[78:79]
	s_mov_b32 m0, s72
	s_add_u32 s74, s28, 0x100180
	ds_read_b128 v[178:181], v139 offset:49152
	ds_read_b128 v[182:185], v139 offset:50176
	ds_read_b128 v[186:189], v139 offset:51200
	ds_read_b128 v[190:193], v139 offset:52224
	ds_read_b128 v[194:197], v139 offset:53248
	ds_read_b128 v[198:201], v139 offset:54272
	ds_read_b128 v[202:205], v139 offset:55296
	ds_read_b128 v[214:217], v139 offset:56320
	global_load_lds_dwordx4 v[172:173], off
	v_lshl_add_u64 v[172:173], v[174:175], 0, s[78:79]
	s_mov_b32 m0, s63
	s_addc_u32 s75, s29, 0
	s_add_i32 s28, s76, s47
	global_load_lds_dwordx4 v[172:173], off
	v_lshl_add_u64 v[172:173], s[74:75], 0, v[0:1]
	s_mov_b32 m0, s28
	s_add_i32 s29, s28, 0x2000
	global_load_lds_dwordx4 v[172:173], off
	v_lshl_add_u64 v[172:173], s[74:75], 0, v[130:131]
	s_mov_b32 m0, s29
	s_nop 0
	global_load_lds_dwordx4 v[172:173], off
	v_lshl_add_u64 v[172:173], v[208:209], 0, s[78:79]
	s_mov_b32 m0, s56
	s_nop 0
	global_load_lds_dwordx4 v[172:173], off
	v_lshl_add_u64 v[172:173], v[212:213], 0, s[78:79]
	s_mov_b32 m0, s57
	s_nop 0
	global_load_lds_dwordx4 v[172:173], off
	s_waitcnt vmcnt(8) lgkmcnt(0)
	s_barrier
	s_setprio 1
	v_mfma_f32_16x16x32_bf16 v[2:5], v[26:29], v[202:205], v[2:5]
	v_mfma_f32_16x16x32_bf16 v[6:9], v[114:117], v[202:205], v[6:9]
	v_mfma_f32_16x16x32_bf16 v[140:143], v[26:29], v[178:181], v[140:143]
	v_mfma_f32_16x16x32_bf16 v[144:147], v[114:117], v[178:181], v[144:147]
	v_mfma_f32_16x16x32_bf16 v[148:151], v[26:29], v[186:189], v[148:151]
	v_mfma_f32_16x16x32_bf16 v[152:155], v[114:117], v[186:189], v[152:155]
	v_mfma_f32_16x16x32_bf16 v[156:159], v[26:29], v[194:197], v[156:159]
	v_mfma_f32_16x16x32_bf16 v[160:163], v[114:117], v[194:197], v[160:163]
	v_mfma_f32_16x16x32_bf16 v[2:5], v[30:33], v[214:217], v[2:5]
	v_mfma_f32_16x16x32_bf16 v[6:9], v[118:121], v[214:217], v[6:9]
	v_mfma_f32_16x16x32_bf16 v[140:143], v[30:33], v[182:185], v[140:143]
	v_mfma_f32_16x16x32_bf16 v[144:147], v[118:121], v[182:185], v[144:147]
	v_mfma_f32_16x16x32_bf16 v[148:151], v[30:33], v[190:193], v[148:151]
	v_mfma_f32_16x16x32_bf16 v[152:155], v[118:121], v[190:193], v[152:155]
	v_mfma_f32_16x16x32_bf16 v[156:159], v[30:33], v[198:201], v[156:159]
	v_mfma_f32_16x16x32_bf16 v[160:163], v[118:121], v[198:201], v[160:163]
	s_setprio 0
	s_setprio 1
	v_mfma_f32_16x16x32_bf16 v[10:13], v[122:125], v[178:181], v[10:13]
	v_mfma_f32_16x16x32_bf16 v[14:17], v[164:167], v[178:181], v[14:17]
	v_mfma_f32_16x16x32_bf16 v[26:29], v[122:125], v[186:189], v[62:65]
	v_mfma_f32_16x16x32_bf16 v[30:33], v[164:167], v[186:189], v[102:105]
	v_mfma_f32_16x16x32_bf16 v[62:65], v[122:125], v[194:197], v[106:109]
	v_mfma_f32_16x16x32_bf16 v[102:105], v[164:167], v[194:197], v[110:113]
	v_mfma_f32_16x16x32_bf16 v[18:21], v[122:125], v[202:205], v[18:21]
	v_mfma_f32_16x16x32_bf16 v[22:25], v[164:167], v[202:205], v[22:25]
	v_mfma_f32_16x16x32_bf16 v[10:13], v[126:129], v[182:185], v[10:13]
	v_mfma_f32_16x16x32_bf16 v[14:17], v[168:171], v[182:185], v[14:17]
	v_mfma_f32_16x16x32_bf16 v[26:29], v[126:129], v[190:193], v[26:29]
	v_mfma_f32_16x16x32_bf16 v[30:33], v[168:171], v[190:193], v[30:33]
	v_mfma_f32_16x16x32_bf16 v[62:65], v[126:129], v[198:201], v[62:65]
	v_mfma_f32_16x16x32_bf16 v[102:105], v[168:171], v[198:201], v[102:105]
	v_mfma_f32_16x16x32_bf16 v[18:21], v[126:129], v[214:217], v[18:21]
	v_mfma_f32_16x16x32_bf16 v[22:25], v[168:171], v[214:217], v[22:25]
	s_setprio 0
	s_barrier
	ds_read_b128 v[106:109], v220
	ds_read_b128 v[110:113], v220 offset:1024
	ds_read_b128 v[114:117], v220 offset:2048
	ds_read_b128 v[118:121], v220 offset:3072
	ds_read_b128 v[122:125], v221
	ds_read_b128 v[126:129], v221 offset:1024
	ds_read_b128 v[164:167], v221 offset:2048
	ds_read_b128 v[168:171], v221 offset:3072
	s_add_u32 s26, s26, 0x100180
	s_addc_u32 s27, s27, 0
	s_mov_b32 m0, s70
	v_lshl_add_u64 v[172:173], s[26:27], 0, v[134:135]
	ds_read_b128 v[178:181], v139
	ds_read_b128 v[182:185], v139 offset:1024
	ds_read_b128 v[186:189], v139 offset:2048
	ds_read_b128 v[190:193], v139 offset:3072
	ds_read_b128 v[194:197], v139 offset:4096
	ds_read_b128 v[198:201], v139 offset:5120
	ds_read_b128 v[202:205], v139 offset:6144
	ds_read_b128 v[214:217], v139 offset:7168
	global_load_lds_dwordx4 v[172:173], off
	v_lshl_add_u64 v[172:173], s[26:27], 0, v[132:133]
	s_mov_b32 m0, s7
	s_nop 0
	global_load_lds_dwordx4 v[172:173], off
	s_waitcnt vmcnt(8) lgkmcnt(0)
	s_barrier
; #define PG8_STAGE(bufoff, gbase, voff) do { _Pragma("unroll") for (int _i = 0; _i < 2; ++_i) \
;         __builtin_amdgcn_global_load_lds((const unsigned*)((const char*)(gbase) + (voff)[_i]), (PG8_LAS unsigned*)(lds + (bufoff) + ldsw + _i * 8192), 16, 0, 0); } while (0)
; #define PG8_LDA(dst, b, h) do { _Pragma("unroll") for (int m = 0; m < 4; ++m) _Pragma("unroll") for (int k = 0; k < 2; ++k) dst[m][k] = *(const PG8_LAS bf16x8*)(lds + PG8_SA(b, h) + aoff + m * 2048 + k * 1024); } while (0)
; #define PG8_LDB(dst, b, h) do { _Pragma("unroll") for (int n = 0; n < 2; ++n) _Pragma("unroll") for (int k = 0; k < 2; ++k) dst[n][k] = *(const PG8_LAS bf16x8*)(lds + PG8_SB(b, h) + boff + n * 2048 + k * 1024); } while (0)
; #define PG8_MMA(ai, bj, At, Bt) do { __builtin_amdgcn_s_setprio(1); _Pragma("unroll") for (int m = 0; m < 4; ++m) _Pragma("unroll") for (int n = 0; n < 2; ++n) _Pragma("unroll") for (int k = 0; k < 2; ++k) \
;         acc[ai][bj][m][n] = __builtin_amdgcn_mfma_f32_16x16x32_bf16(Bt[n][k], At[m][k], acc[ai][bj][m][n], 0, 0, 0); __builtin_amdgcn_s_setprio(0); } while (0)
; #define PG8_WAIT_V(n) asm volatile("s_waitcnt vmcnt(" #n ")" ::: "memory")
; #define PG8_WAIT_L(n) asm volatile("s_waitcnt lgkmcnt(" #n ")" ::: "memory")
; #define PG8_BAR __builtin_amdgcn_s_barrier()
; #define PG8_SCHED __builtin_amdgcn_sched_barrier(0)
; template <class Epi, class Sched, bool ALIGN_EPI = false, bool SP2 = false>
; __device__ __forceinline__ void gemm_phase(PG8_LAS unsigned char* lds, const Gemm g, const Sched& S, const Epi& E, int wave_s) {
;     ...
;             PG8_LDB(B0, 0, 0); PG8_LDB(B1, 0, 1); PG8_SCHED; PG8_LDA(At, 0, 0); PG8_STAGE(PG8_SA(1, 1), a1 + hstep, voffA);
;             PG8_WAIT_V(8); PG8_WAIT_L(0); PG8_BAR; PG8_MMA(0, 0, At, B0); PG8_MMA(0, 1, At, B1); PG8_BAR; PG8_SCHED;
;             PG8_LDA(At, 0, 1); PG8_STAGE(PG8_SB(0, 0), b2, voffB); PG8_STAGE(PG8_SB(0, 1), b2 + hstep, voffB); PG8_STAGE(PG8_SA(0, 0), a2, voffA);
;             PG8_WAIT_V(8); PG8_WAIT_L(0); PG8_BAR; PG8_MMA(1, 0, At, B0); PG8_MMA(1, 1, At, B1); PG8_BAR; PG8_SCHED;
	s_setprio 1
	v_mfma_f32_16x16x32_bf16 v[66:69], v[106:109], v[178:181], v[66:69]
	v_mfma_f32_16x16x32_bf16 v[70:73], v[114:117], v[178:181], v[70:73]
	v_mfma_f32_16x16x32_bf16 v[74:77], v[106:109], v[186:189], v[74:77]
	v_mfma_f32_16x16x32_bf16 v[78:81], v[114:117], v[186:189], v[78:81]
	v_mfma_f32_16x16x32_bf16 v[82:85], v[106:109], v[194:197], v[82:85]
	v_mfma_f32_16x16x32_bf16 v[86:89], v[114:117], v[194:197], v[86:89]
	v_mfma_f32_16x16x32_bf16 v[90:93], v[106:109], v[202:205], v[90:93]
	v_mfma_f32_16x16x32_bf16 v[94:97], v[114:117], v[202:205], v[94:97]
	v_mfma_f32_16x16x32_bf16 v[66:69], v[110:113], v[182:185], v[66:69]
	v_mfma_f32_16x16x32_bf16 v[70:73], v[118:121], v[182:185], v[70:73]
	v_mfma_f32_16x16x32_bf16 v[74:77], v[110:113], v[190:193], v[74:77]
	v_mfma_f32_16x16x32_bf16 v[78:81], v[118:121], v[190:193], v[78:81]
	v_mfma_f32_16x16x32_bf16 v[82:85], v[110:113], v[198:201], v[82:85]
	v_mfma_f32_16x16x32_bf16 v[86:89], v[118:121], v[198:201], v[86:89]
	v_mfma_f32_16x16x32_bf16 v[90:93], v[110:113], v[214:217], v[90:93]
	v_mfma_f32_16x16x32_bf16 v[94:97], v[118:121], v[214:217], v[94:97]
	s_setprio 0
	s_setprio 1
	v_mfma_f32_16x16x32_bf16 v[34:37], v[164:167], v[178:181], v[34:37]
	v_mfma_f32_16x16x32_bf16 v[98:101], v[122:125], v[178:181], v[98:101]
	v_mfma_f32_16x16x32_bf16 v[178:181], v[168:171], v[182:185], v[34:37]
	v_mfma_f32_16x16x32_bf16 v[34:37], v[122:125], v[186:189], v[38:41]
	v_mfma_f32_16x16x32_bf16 v[98:101], v[126:129], v[182:185], v[98:101]
	v_mfma_f32_16x16x32_bf16 v[182:185], v[126:129], v[190:193], v[34:37]
	v_mfma_f32_16x16x32_bf16 v[34:37], v[164:167], v[186:189], v[42:45]
	v_mfma_f32_16x16x32_bf16 v[42:45], v[168:171], v[190:193], v[34:37]
	v_mfma_f32_16x16x32_bf16 v[34:37], v[122:125], v[194:197], v[46:49]
	v_mfma_f32_16x16x32_bf16 v[46:49], v[126:129], v[198:201], v[34:37]
	v_mfma_f32_16x16x32_bf16 v[34:37], v[164:167], v[194:197], v[50:53]
	v_mfma_f32_16x16x32_bf16 v[50:53], v[168:171], v[198:201], v[34:37]
	v_mfma_f32_16x16x32_bf16 v[34:37], v[122:125], v[202:205], v[54:57]
	v_mfma_f32_16x16x32_bf16 v[54:57], v[126:129], v[214:217], v[34:37]
	v_mfma_f32_16x16x32_bf16 v[34:37], v[164:167], v[202:205], v[58:61]
	v_mfma_f32_16x16x32_bf16 v[186:189], v[168:171], v[214:217], v[34:37]
	s_setprio 0
	s_barrier
	s_mov_b32 m0, s62
	v_lshl_add_u64 v[172:173], s[24:25], 0, v[0:1]
	s_add_u32 s26, s24, 0x100000
	s_nop 1
	ds_read_b128 v[34:37], v139 offset:16384
	ds_read_b128 v[38:41], v139 offset:17408
	ds_read_b128 v[58:61], v139 offset:18432
	ds_read_b128 v[190:193], v139 offset:19456
	ds_read_b128 v[194:197], v139 offset:20480
	ds_read_b128 v[198:201], v139 offset:21504
	ds_read_b128 v[202:205], v139 offset:22528
	ds_read_b128 v[214:217], v139 offset:23552
	global_load_lds_dwordx4 v[172:173], off
	v_lshl_add_u64 v[174:175], s[24:25], 0, v[130:131]
	s_mov_b32 m0, s17
	s_addc_u32 s27, s25, 0
	global_load_lds_dwordx4 v[174:175], off
	v_lshl_add_u64 v[208:209], s[26:27], 0, v[0:1]
	s_mov_b32 m0, s19
	v_lshl_add_u64 v[212:213], s[22:23], 0, v[132:133]
	global_load_lds_dwordx4 v[208:209], off
	v_lshl_add_u64 v[208:209], s[26:27], 0, v[130:131]
	s_mov_b32 m0, s21
	s_nop 0
	global_load_lds_dwordx4 v[208:209], off
	v_lshl_add_u64 v[208:209], s[22:23], 0, v[134:135]
	s_mov_b32 m0, s9
	s_nop 0
	global_load_lds_dwordx4 v[208:209], off
	s_mov_b32 m0, s11
	s_nop 0
	global_load_lds_dwordx4 v[212:213], off
	s_waitcnt vmcnt(8) lgkmcnt(0)
	s_barrier
	s_setprio 1
	v_mfma_f32_16x16x32_bf16 v[140:143], v[106:109], v[34:37], v[140:143]
	v_mfma_f32_16x16x32_bf16 v[148:151], v[106:109], v[58:61], v[148:151]
	v_mfma_f32_16x16x32_bf16 v[156:159], v[106:109], v[194:197], v[156:159]
	v_mfma_f32_16x16x32_bf16 v[2:5], v[106:109], v[202:205], v[2:5]
	v_mfma_f32_16x16x32_bf16 v[140:143], v[110:113], v[38:41], v[140:143]
	v_mfma_f32_16x16x32_bf16 v[148:151], v[110:113], v[190:193], v[148:151]
	v_mfma_f32_16x16x32_bf16 v[156:159], v[110:113], v[198:201], v[156:159]
	v_mfma_f32_16x16x32_bf16 v[110:113], v[110:113], v[214:217], v[2:5]
	v_mfma_f32_16x16x32_bf16 v[2:5], v[114:117], v[202:205], v[6:9]
	v_mfma_f32_16x16x32_bf16 v[144:147], v[114:117], v[34:37], v[144:147]
	v_mfma_f32_16x16x32_bf16 v[152:155], v[114:117], v[58:61], v[152:155]
	v_mfma_f32_16x16x32_bf16 v[160:163], v[114:117], v[194:197], v[160:163]
	v_mfma_f32_16x16x32_bf16 v[114:117], v[118:121], v[214:217], v[2:5]
	v_mfma_f32_16x16x32_bf16 v[144:147], v[118:121], v[38:41], v[144:147]
	v_mfma_f32_16x16x32_bf16 v[152:155], v[118:121], v[190:193], v[152:155]
	v_mfma_f32_16x16x32_bf16 v[160:163], v[118:121], v[198:201], v[160:163]
	s_setprio 0
	s_setprio 1
	v_mfma_f32_16x16x32_bf16 v[2:5], v[122:125], v[34:37], v[10:13]
	v_mfma_f32_16x16x32_bf16 v[118:121], v[126:129], v[38:41], v[2:5]
	v_mfma_f32_16x16x32_bf16 v[2:5], v[164:167], v[34:37], v[14:17]
	v_mfma_f32_16x16x32_bf16 v[218:221], v[168:171], v[38:41], v[2:5]
	v_mfma_f32_16x16x32_bf16 v[2:5], v[122:125], v[58:61], v[26:29]
	v_mfma_f32_16x16x32_bf16 v[222:225], v[126:129], v[190:193], v[2:5]
	v_mfma_f32_16x16x32_bf16 v[2:5], v[164:167], v[58:61], v[30:33]
	v_mfma_f32_16x16x32_bf16 v[190:193], v[168:171], v[190:193], v[2:5]
	v_mfma_f32_16x16x32_bf16 v[2:5], v[122:125], v[194:197], v[62:65]
	v_mfma_f32_16x16x32_bf16 v[226:229], v[126:129], v[198:201], v[2:5]
	v_mfma_f32_16x16x32_bf16 v[2:5], v[164:167], v[194:197], v[102:105]
	v_mfma_f32_16x16x32_bf16 v[194:197], v[168:171], v[198:201], v[2:5]
	v_mfma_f32_16x16x32_bf16 v[2:5], v[122:125], v[202:205], v[18:21]
	v_mfma_f32_16x16x32_bf16 v[198:201], v[126:129], v[214:217], v[2:5]
	v_mfma_f32_16x16x32_bf16 v[2:5], v[164:167], v[202:205], v[22:25]
	v_mfma_f32_16x16x32_bf16 v[164:167], v[168:171], v[214:217], v[2:5]
	s_setprio 0
	s_barrier
; #define PG8_STAGE(bufoff, gbase, voff) do { _Pragma("unroll") for (int _i = 0; _i < 2; ++_i) \
;         __builtin_amdgcn_global_load_lds((const unsigned*)((const char*)(gbase) + (voff)[_i]), (PG8_LAS unsigned*)(lds + (bufoff) + ldsw + _i * 8192), 16, 0, 0); } while (0)
; #define PG8_LDA(dst, b, h) do { _Pragma("unroll") for (int m = 0; m < 4; ++m) _Pragma("unroll") for (int k = 0; k < 2; ++k) dst[m][k] = *(const PG8_LAS bf16x8*)(lds + PG8_SA(b, h) + aoff + m * 2048 + k * 1024); } while (0)
; #define PG8_LDB(dst, b, h) do { _Pragma("unroll") for (int n = 0; n < 2; ++n) _Pragma("unroll") for (int k = 0; k < 2; ++k) dst[n][k] = *(const PG8_LAS bf16x8*)(lds + PG8_SB(b, h) + boff + n * 2048 + k * 1024); } while (0)
; #define PG8_MMA(ai, bj, At, Bt) do { __builtin_amdgcn_s_setprio(1); _Pragma("unroll") for (int m = 0; m < 4; ++m) _Pragma("unroll") for (int n = 0; n < 2; ++n) _Pragma("unroll") for (int k = 0; k < 2; ++k) \
;         acc[ai][bj][m][n] = __builtin_amdgcn_mfma_f32_16x16x32_bf16(Bt[n][k], At[m][k], acc[ai][bj][m][n], 0, 0, 0); __builtin_amdgcn_s_setprio(0); } while (0)
; #define PG8_WAIT_V(n) asm volatile("s_waitcnt vmcnt(" #n ")" ::: "memory")
; #define PG8_WAIT_L(n) asm volatile("s_waitcnt lgkmcnt(" #n ")" ::: "memory")
; #define PG8_BAR __builtin_amdgcn_s_barrier()
; #define PG8_SCHED __builtin_amdgcn_sched_barrier(0)
; template <class Epi, class Sched, bool ALIGN_EPI = false, bool SP2 = false>
; __device__ __forceinline__ void gemm_phase(PG8_LAS unsigned char* lds, const Gemm g, const Sched& S, const Epi& E, int wave_s) {
;     ...
;             PG8_LDB(B0, 1, 0); PG8_LDB(B1, 1, 1); PG8_SCHED; PG8_LDA(At, 1, 0); PG8_STAGE(PG8_SA(0, 1), a2 + hstep, voffA);
;             PG8_WAIT_V(8); PG8_WAIT_L(0); PG8_BAR; PG8_MMA(0, 0, At, B0); PG8_MMA(0, 1, At, B1); PG8_BAR; PG8_SCHED;
;             PG8_LDA(At, 1, 1); PG8_STAGE(PG8_SB(1, 0), b3, voffB); PG8_STAGE(PG8_SB(1, 1), b3 + hstep, voffB); PG8_STAGE(PG8_SA(1, 0), a3, voffA);
;             PG8_WAIT_V(8); PG8_WAIT_L(0); PG8_BAR; PG8_MMA(1, 0, At, B0); PG8_MMA(1, 1, At, B1); PG8_BAR; PG8_SCHED;
;     ...
;         if constexpr (ALIGN_EPI) { if (wr == 0) PG8_BAR; }
;         if constexpr (!Epi::AFTER_DRAIN) { E(acc, cur, wr, wc, fr, fq); S.done(cur); }
;         if (!has_next) break;
	ds_read_b128 v[102:105], v230
	ds_read_b128 v[122:125], v230 offset:1024
	ds_read_b128 v[126:129], v230 offset:2048
	ds_read_b128 v[168:171], v230 offset:3072
	ds_read_b128 v[202:205], v234
	ds_read_b128 v[214:217], v234 offset:1024
	ds_read_b128 v[230:233], v234 offset:2048
	ds_read_b128 v[234:237], v234 offset:3072
	s_add_u32 s26, s22, 0x100000
	s_addc_u32 s27, s23, 0
	s_mov_b32 m0, s48
	v_lshl_add_u64 v[2:3], s[26:27], 0, v[134:135]
	ds_read_b128 v[26:29], v139 offset:32768
	ds_read_b128 v[30:33], v139 offset:33792
	ds_read_b128 v[62:65], v139 offset:34816
	ds_read_b128 v[106:109], v139 offset:35840
	ds_read_b128 v[238:241], v139 offset:36864
	ds_read_b128 v[242:245], v139 offset:37888
	ds_read_b128 v[246:249], v139 offset:38912
	ds_read_b128 v[250:253], v139 offset:39936
	global_load_lds_dwordx4 v[2:3], off
	v_lshl_add_u64 v[2:3], s[26:27], 0, v[132:133]
	s_mov_b32 m0, s49
	s_nop 0
	global_load_lds_dwordx4 v[2:3], off
	s_waitcnt vmcnt(8) lgkmcnt(0)
	s_barrier
	s_setprio 1
	v_mfma_f32_16x16x32_bf16 v[2:5], v[102:105], v[26:29], v[66:69]
	v_mfma_f32_16x16x32_bf16 v[34:37], v[122:125], v[30:33], v[2:5]
	v_mfma_f32_16x16x32_bf16 v[2:5], v[126:129], v[26:29], v[70:73]
	v_mfma_f32_16x16x32_bf16 v[38:41], v[168:171], v[30:33], v[2:5]
	v_mfma_f32_16x16x32_bf16 v[2:5], v[102:105], v[62:65], v[74:77]
	v_mfma_f32_16x16x32_bf16 v[18:21], v[122:125], v[106:109], v[2:5]
	v_mfma_f32_16x16x32_bf16 v[2:5], v[126:129], v[62:65], v[78:81]
	v_mfma_f32_16x16x32_bf16 v[22:25], v[168:171], v[106:109], v[2:5]
	v_mfma_f32_16x16x32_bf16 v[2:5], v[102:105], v[238:241], v[82:85]
	v_mfma_f32_16x16x32_bf16 v[10:13], v[122:125], v[242:245], v[2:5]
	v_mfma_f32_16x16x32_bf16 v[2:5], v[126:129], v[238:241], v[86:89]
	v_mfma_f32_16x16x32_bf16 v[14:17], v[168:171], v[242:245], v[2:5]
	v_mfma_f32_16x16x32_bf16 v[2:5], v[102:105], v[246:249], v[90:93]
	v_mfma_f32_16x16x32_bf16 v[6:9], v[126:129], v[246:249], v[94:97]
	v_mfma_f32_16x16x32_bf16 v[2:5], v[122:125], v[250:253], v[2:5]
	v_mfma_f32_16x16x32_bf16 v[6:9], v[168:171], v[250:253], v[6:9]
	s_setprio 0
	s_setprio 1
	v_mfma_f32_16x16x32_bf16 v[58:61], v[202:205], v[26:29], v[98:101]
	v_mfma_f32_16x16x32_bf16 v[26:29], v[230:233], v[26:29], v[178:181]
	v_mfma_f32_16x16x32_bf16 v[78:81], v[234:237], v[30:33], v[26:29]
	v_mfma_f32_16x16x32_bf16 v[26:29], v[202:205], v[62:65], v[182:185]
	v_mfma_f32_16x16x32_bf16 v[70:73], v[214:217], v[30:33], v[58:61]
	v_mfma_f32_16x16x32_bf16 v[58:61], v[214:217], v[106:109], v[26:29]
	v_mfma_f32_16x16x32_bf16 v[26:29], v[230:233], v[62:65], v[42:45]
	v_mfma_f32_16x16x32_bf16 v[62:65], v[234:237], v[106:109], v[26:29]
	v_mfma_f32_16x16x32_bf16 v[26:29], v[202:205], v[238:241], v[46:49]
	v_mfma_f32_16x16x32_bf16 v[42:45], v[214:217], v[242:245], v[26:29]
	v_mfma_f32_16x16x32_bf16 v[26:29], v[230:233], v[238:241], v[50:53]
	v_mfma_f32_16x16x32_bf16 v[46:49], v[234:237], v[242:245], v[26:29]
	v_mfma_f32_16x16x32_bf16 v[26:29], v[202:205], v[246:249], v[54:57]
	v_mfma_f32_16x16x32_bf16 v[30:33], v[230:233], v[246:249], v[186:189]
	v_mfma_f32_16x16x32_bf16 v[26:29], v[214:217], v[250:253], v[26:29]
	v_mfma_f32_16x16x32_bf16 v[30:33], v[234:237], v[250:253], v[30:33]
	s_setprio 0
	s_barrier
	s_mov_b32 m0, s72
	v_lshl_add_u64 v[50:51], v[172:173], 0, s[60:61]
	s_add_u32 s26, s24, 0x100080
	ds_read_b128 v[82:85], v139 offset:49152
	ds_read_b128 v[90:93], v139 offset:50176
	ds_read_b128 v[178:181], v139 offset:51200
	ds_read_b128 v[182:185], v139 offset:52224
	ds_read_b128 v[186:189], v139 offset:53248
	ds_read_b128 v[238:241], v139 offset:54272
	ds_read_b128 v[242:245], v139 offset:55296
	ds_read_b128 v[246:249], v139 offset:56320
	global_load_lds_dwordx4 v[50:51], off
	v_lshl_add_u64 v[50:51], v[174:175], 0, s[60:61]
	s_mov_b32 m0, s63
	s_addc_u32 s27, s25, 0
	global_load_lds_dwordx4 v[50:51], off
	v_lshl_add_u64 v[50:51], s[26:27], 0, v[0:1]
	s_mov_b32 m0, s28
	s_nop 0
	global_load_lds_dwordx4 v[50:51], off
	v_lshl_add_u64 v[50:51], s[26:27], 0, v[130:131]
	s_mov_b32 m0, s29
	s_nop 0
	global_load_lds_dwordx4 v[50:51], off
	v_lshl_add_u64 v[50:51], v[208:209], 0, s[60:61]
	s_mov_b32 m0, s56
	s_nop 0
	global_load_lds_dwordx4 v[50:51], off
	v_lshl_add_u64 v[50:51], v[212:213], 0, s[60:61]
	s_mov_b32 m0, s57
	s_nop 0
	global_load_lds_dwordx4 v[50:51], off
	s_waitcnt vmcnt(8) lgkmcnt(0)
	s_barrier
	s_setprio 1
	v_mfma_f32_16x16x32_bf16 v[50:53], v[102:105], v[82:85], v[140:143]
	v_mfma_f32_16x16x32_bf16 v[98:101], v[122:125], v[90:93], v[50:53]
	v_mfma_f32_16x16x32_bf16 v[50:53], v[126:129], v[82:85], v[144:147]
	v_mfma_f32_16x16x32_bf16 v[106:109], v[168:171], v[90:93], v[50:53]
	v_mfma_f32_16x16x32_bf16 v[50:53], v[102:105], v[178:181], v[148:151]
	v_mfma_f32_16x16x32_bf16 v[86:89], v[122:125], v[182:185], v[50:53]
	v_mfma_f32_16x16x32_bf16 v[50:53], v[126:129], v[178:181], v[152:155]
	v_mfma_f32_16x16x32_bf16 v[94:97], v[168:171], v[182:185], v[50:53]
	v_mfma_f32_16x16x32_bf16 v[50:53], v[102:105], v[186:189], v[156:159]
	v_mfma_f32_16x16x32_bf16 v[66:69], v[122:125], v[238:241], v[50:53]
	v_mfma_f32_16x16x32_bf16 v[50:53], v[126:129], v[186:189], v[160:163]
	v_mfma_f32_16x16x32_bf16 v[74:77], v[168:171], v[238:241], v[50:53]
	v_mfma_f32_16x16x32_bf16 v[50:53], v[102:105], v[242:245], v[110:113]
	v_mfma_f32_16x16x32_bf16 v[54:57], v[126:129], v[242:245], v[114:117]
	v_mfma_f32_16x16x32_bf16 v[50:53], v[122:125], v[246:249], v[50:53]
	v_mfma_f32_16x16x32_bf16 v[54:57], v[168:171], v[246:249], v[54:57]
	s_setprio 0
	s_setprio 1
	v_mfma_f32_16x16x32_bf16 v[102:105], v[202:205], v[82:85], v[118:121]
	v_mfma_f32_16x16x32_bf16 v[82:85], v[230:233], v[82:85], v[218:221]
	v_mfma_f32_16x16x32_bf16 v[126:129], v[234:237], v[90:93], v[82:85]
	v_mfma_f32_16x16x32_bf16 v[82:85], v[202:205], v[178:181], v[222:225]
	v_mfma_f32_16x16x32_bf16 v[114:117], v[214:217], v[182:185], v[82:85]
	v_mfma_f32_16x16x32_bf16 v[82:85], v[230:233], v[178:181], v[190:193]
	v_mfma_f32_16x16x32_bf16 v[118:121], v[234:237], v[182:185], v[82:85]
	v_mfma_f32_16x16x32_bf16 v[82:85], v[202:205], v[186:189], v[226:229]
	v_mfma_f32_16x16x32_bf16 v[122:125], v[214:217], v[90:93], v[102:105]
	v_mfma_f32_16x16x32_bf16 v[102:105], v[214:217], v[238:241], v[82:85]
	v_mfma_f32_16x16x32_bf16 v[82:85], v[230:233], v[186:189], v[194:197]
	v_mfma_f32_16x16x32_bf16 v[110:113], v[234:237], v[238:241], v[82:85]
	v_mfma_f32_16x16x32_bf16 v[82:85], v[202:205], v[242:245], v[198:201]
	v_mfma_f32_16x16x32_bf16 v[90:93], v[230:233], v[242:245], v[164:167]
	v_mfma_f32_16x16x32_bf16 v[82:85], v[214:217], v[246:249], v[82:85]
	v_mfma_f32_16x16x32_bf16 v[90:93], v[234:237], v[246:249], v[90:93]
	s_setprio 0
	s_barrier
	s_andn2_b64 vcc, exec, s[12:13]
	s_cbranch_vccnz .LBB0_1106
	s_barrier

; __global__ void __launch_bounds__(512, 2) fwd_megakernel(Params p) {
;     ...
;     cg::this_grid().sync();
.LBB0_1332:
	s_mov_b64 s[4:5], exec
	buffer_wbl2 sc1
	s_waitcnt vmcnt(0) lgkmcnt(0)
	v_mbcnt_lo_u32_b32 v0, s4, 0
	v_mbcnt_hi_u32_b32 v0, s5, v0
	v_cmp_eq_u32_e32 vcc, 0, v0
	s_and_saveexec_b64 s[6:7], vcc
	s_cbranch_execz .LBB0_1334
	s_bcnt1_i32_b64 s4, s[4:5]
	v_mov_b32_e32 v3, s4
	v_readlane_b32 s4, v255, 6
	v_readlane_b32 s5, v255, 7
	s_nop 4
	global_atomic_add v3, v1, v3, s[4:5] sc0
